# static raise for waves 4-7 left in place after the first GEMM K-loop (not reset at loop exit), flips removed
# baseline (speedup 1.0000x reference)
; #define PG8_STAGE(bufoff, gbase, voff) do { _Pragma("unroll") for (int _i = 0; _i < 2; ++_i) \
;         __builtin_amdgcn_global_load_lds((const unsigned*)((const char*)(gbase) + (voff)[_i]), (LAS unsigned*)(lds + (bufoff) + ldsw + _i * 8192), 16, 0, 0); } while (0)
; #define PG8_LDA(dst, b, h) do { _Pragma("unroll") for (int m = 0; m < 4; ++m) _Pragma("unroll") for (int k = 0; k < 2; ++k) dst[m][k] = *(const LAS bf16x8*)(lds + PG8_SA(b, h) + aoff + m * 2048 + k * 1024); } while (0)
; #define PG8_LDB(dst, b, h) do { _Pragma("unroll") for (int n = 0; n < 2; ++n) _Pragma("unroll") for (int k = 0; k < 2; ++k) dst[n][k] = *(const LAS bf16x8*)(lds + PG8_SB(b, h) + boff + n * 2048 + k * 1024); } while (0)
; #define PG8_MMA(ai, bj, At, Bt) do { __builtin_amdgcn_s_setprio(1); _Pragma("unroll") for (int m = 0; m < 4; ++m) _Pragma("unroll") for (int n = 0; n < 2; ++n) _Pragma("unroll") for (int k = 0; k < 2; ++k) \
;         acc[ai][bj][m][n] = __builtin_amdgcn_mfma_f32_16x16x32_bf16(Bt[n][k], At[m][k], acc[ai][bj][m][n], 0, 0, 0); __builtin_amdgcn_s_setprio(0); } while (0)
; #define PG8_WAIT_V(n) asm volatile("s_waitcnt vmcnt(" #n ")" ::: "memory")
; #define PG8_WAIT_L(n) asm volatile("s_waitcnt lgkmcnt(" #n ")" ::: "memory")
; #define PG8_BAR __builtin_amdgcn_s_barrier()
; #define PG8_SCHED __builtin_amdgcn_sched_barrier(0)
; template <class Sched, class Epi, bool ALIGN_EPI, bool SP2>
; __device__ __forceinline__ void gemm_phase(LAS unsigned char* lds, const int K, const int lda, const int ldb, const Sched& S, const Epi& E) {
;     ...
;         for (int t = 0; t < nt; t += 2) {
;             const bool last = (t == nt - 2);
;             const char* a1 = cA + (size_t)(t + 1) * kstep;
;             const char* a2 = last ? nA : cA + (size_t)(t + 2) * kstep; const char* b2 = last ? nB : cB + (size_t)(t + 2) * kstep;
;             const char* a3 = a2 + kstep; const char* b3 = b2 + kstep;
;             if constexpr (SP2) {
;             PG8_LDB(B0, 0, 0); PG8_LDB(B1, 0, 1); PG8_SCHED; PG8_LDA(At, 0, 0); PG8_STAGE(PG8_SA(1, 1), a1 + hstepA, voffA);
;             PG8_WAIT_V(8); PG8_WAIT_L(0); PG8_BAR; PG8_MMA(0, 0, At, B0); PG8_MMA(0, 1, At, B1); PG8_BAR; PG8_SCHED;
;             PG8_LDA(At, 0, 1); PG8_STAGE(PG8_SB(0, 0), b2, voffB); PG8_STAGE(PG8_SB(0, 1), b2 + hstepB, voffB); PG8_STAGE(PG8_SA(0, 0), a2, voffA);
.Lprio_skip_155:
.LBB0_155:
	ds_read_b128 v[140:143], v147
	ds_read_b128 v[150:153], v147 offset:1024
	ds_read_b128 v[154:157], v147 offset:2048
	ds_read_b128 v[158:161], v147 offset:3072
	ds_read_b128 v[162:165], v148
	ds_read_b128 v[166:169], v148 offset:1024
	ds_read_b128 v[170:173], v148 offset:2048
	ds_read_b128 v[180:183], v148 offset:3072
	s_add_u32 s22, s20, 0xfff80080
	s_addc_u32 s23, s21, -1
	s_cmp_eq_u32 s75, 28
	s_cselect_b32 s25, s15, s23
	s_cselect_b32 s24, s14, s22
	s_cselect_b32 s23, s17, s74
	s_cselect_b32 s22, s16, s13
	v_lshl_add_u64 v[174:175], s[20:21], 0, v[136:137]
	s_add_i32 m0, s3, 0xc000
	ds_read_b128 v[184:187], v149
	ds_read_b128 v[188:191], v149 offset:1024
	ds_read_b128 v[192:195], v149 offset:2048
	ds_read_b128 v[196:199], v149 offset:3072
	ds_read_b128 v[200:203], v149 offset:4096
	ds_read_b128 v[204:207], v149 offset:5120
	ds_read_b128 v[208:211], v149 offset:6144
	ds_read_b128 v[212:215], v149 offset:7168
	global_load_lds_dwordx4 v[174:175], off
	v_lshl_add_u64 v[174:175], s[20:21], 0, v[138:139]
	s_add_i32 m0, s3, 0xe000
	s_nop 0
	global_load_lds_dwordx4 v[174:175], off
	s_waitcnt vmcnt(8)
	s_waitcnt lgkmcnt(0)
	s_barrier
	s_waitcnt lgkmcnt(0)
	v_mfma_f32_16x16x32_bf16 v[124:127], v[140:143], v[184:187], v[124:127]
	v_mfma_f32_16x16x32_bf16 v[120:123], v[154:157], v[184:187], v[120:123]
	v_mfma_f32_16x16x32_bf16 v[108:111], v[140:143], v[192:195], v[108:111]
	v_mfma_f32_16x16x32_bf16 v[104:107], v[154:157], v[192:195], v[104:107]
	v_mfma_f32_16x16x32_bf16 v[92:95], v[140:143], v[200:203], v[92:95]
	v_mfma_f32_16x16x32_bf16 v[88:91], v[154:157], v[200:203], v[88:91]
	v_mfma_f32_16x16x32_bf16 v[76:79], v[140:143], v[208:211], v[76:79]
	v_mfma_f32_16x16x32_bf16 v[72:75], v[154:157], v[208:211], v[72:75]
	v_mfma_f32_16x16x32_bf16 v[124:127], v[150:153], v[188:191], v[124:127]
	v_mfma_f32_16x16x32_bf16 v[120:123], v[158:161], v[188:191], v[120:123]
	v_mfma_f32_16x16x32_bf16 v[108:111], v[150:153], v[196:199], v[108:111]
	v_mfma_f32_16x16x32_bf16 v[104:107], v[158:161], v[196:199], v[104:107]
	v_mfma_f32_16x16x32_bf16 v[92:95], v[150:153], v[204:207], v[92:95]
	v_mfma_f32_16x16x32_bf16 v[88:91], v[158:161], v[204:207], v[88:91]
	v_mfma_f32_16x16x32_bf16 v[76:79], v[150:153], v[212:215], v[76:79]
	v_mfma_f32_16x16x32_bf16 v[72:75], v[158:161], v[212:215], v[72:75]
	v_mfma_f32_16x16x32_bf16 v[116:119], v[162:165], v[184:187], v[116:119]
	v_mfma_f32_16x16x32_bf16 v[112:115], v[170:173], v[184:187], v[112:115]
	v_mfma_f32_16x16x32_bf16 v[100:103], v[162:165], v[192:195], v[100:103]
	v_mfma_f32_16x16x32_bf16 v[96:99], v[170:173], v[192:195], v[96:99]
	v_mfma_f32_16x16x32_bf16 v[84:87], v[162:165], v[200:203], v[84:87]
	v_mfma_f32_16x16x32_bf16 v[80:83], v[170:173], v[200:203], v[80:83]
	v_mfma_f32_16x16x32_bf16 v[68:71], v[162:165], v[208:211], v[68:71]
	v_mfma_f32_16x16x32_bf16 v[64:67], v[170:173], v[208:211], v[64:67]
	v_mfma_f32_16x16x32_bf16 v[116:119], v[166:169], v[188:191], v[116:119]
	v_mfma_f32_16x16x32_bf16 v[112:115], v[180:183], v[188:191], v[112:115]
	v_mfma_f32_16x16x32_bf16 v[100:103], v[166:169], v[196:199], v[100:103]
	v_mfma_f32_16x16x32_bf16 v[96:99], v[180:183], v[196:199], v[96:99]
	v_mfma_f32_16x16x32_bf16 v[84:87], v[166:169], v[204:207], v[84:87]
	v_mfma_f32_16x16x32_bf16 v[80:83], v[180:183], v[204:207], v[80:83]
	v_mfma_f32_16x16x32_bf16 v[68:71], v[166:169], v[212:215], v[68:71]
	v_mfma_f32_16x16x32_bf16 v[64:67], v[180:183], v[212:215], v[64:67]
	s_barrier
	s_add_i32 s78, s35, s2
	v_lshl_add_u64 v[174:175], s[22:23], 0, v[130:131]
	s_mov_b32 m0, s78
	ds_read_b128 v[184:187], v149 offset:16384
	ds_read_b128 v[188:191], v149 offset:17408
	ds_read_b128 v[192:195], v149 offset:18432
	ds_read_b128 v[196:199], v149 offset:19456
	ds_read_b128 v[200:203], v149 offset:20480
	ds_read_b128 v[204:207], v149 offset:21504
	ds_read_b128 v[208:211], v149 offset:22528
	ds_read_b128 v[212:215], v149 offset:23552
	global_load_lds_dwordx4 v[174:175], off
	s_add_i32 m0, s78, 0x2000
	s_add_u32 s78, s22, 0x80000
	v_lshl_add_u64 v[216:217], s[22:23], 0, v[134:135]
	s_addc_u32 s79, s23, 0
	s_add_i32 s84, s50, s2
	global_load_lds_dwordx4 v[216:217], off
	v_lshl_add_u64 v[218:219], s[78:79], 0, v[130:131]
	s_mov_b32 m0, s84
	v_lshl_add_u64 v[220:221], s[24:25], 0, v[132:133]
	global_load_lds_dwordx4 v[218:219], off
	v_lshl_add_u64 v[218:219], s[78:79], 0, v[134:135]
	s_add_i32 m0, s84, 0x2000
	s_nop 0
	global_load_lds_dwordx4 v[218:219], off
	v_lshl_add_u64 v[218:219], s[24:25], 0, v[128:129]
	s_mov_b32 m0, s3
	s_nop 0
	global_load_lds_dwordx4 v[218:219], off
	s_mov_b32 m0, s19
	s_nop 0
	global_load_lds_dwordx4 v[220:221], off
	s_waitcnt vmcnt(8)
	s_waitcnt lgkmcnt(0)
	s_barrier
; #define PG8_STAGE(bufoff, gbase, voff) do { _Pragma("unroll") for (int _i = 0; _i < 2; ++_i) \
;         __builtin_amdgcn_global_load_lds((const unsigned*)((const char*)(gbase) + (voff)[_i]), (LAS unsigned*)(lds + (bufoff) + ldsw + _i * 8192), 16, 0, 0); } while (0)
; #define PG8_LDA(dst, b, h) do { _Pragma("unroll") for (int m = 0; m < 4; ++m) _Pragma("unroll") for (int k = 0; k < 2; ++k) dst[m][k] = *(const LAS bf16x8*)(lds + PG8_SA(b, h) + aoff + m * 2048 + k * 1024); } while (0)
; #define PG8_LDB(dst, b, h) do { _Pragma("unroll") for (int n = 0; n < 2; ++n) _Pragma("unroll") for (int k = 0; k < 2; ++k) dst[n][k] = *(const LAS bf16x8*)(lds + PG8_SB(b, h) + boff + n * 2048 + k * 1024); } while (0)
; #define PG8_MMA(ai, bj, At, Bt) do { __builtin_amdgcn_s_setprio(1); _Pragma("unroll") for (int m = 0; m < 4; ++m) _Pragma("unroll") for (int n = 0; n < 2; ++n) _Pragma("unroll") for (int k = 0; k < 2; ++k) \
;         acc[ai][bj][m][n] = __builtin_amdgcn_mfma_f32_16x16x32_bf16(Bt[n][k], At[m][k], acc[ai][bj][m][n], 0, 0, 0); __builtin_amdgcn_s_setprio(0); } while (0)
; #define PG8_WAIT_V(n) asm volatile("s_waitcnt vmcnt(" #n ")" ::: "memory")
; #define PG8_WAIT_L(n) asm volatile("s_waitcnt lgkmcnt(" #n ")" ::: "memory")
; #define PG8_BAR __builtin_amdgcn_s_barrier()
; #define PG8_SCHED __builtin_amdgcn_sched_barrier(0)
; template <class Sched, class Epi, bool ALIGN_EPI, bool SP2>
; __device__ __forceinline__ void gemm_phase(LAS unsigned char* lds, const int K, const int lda, const int ldb, const Sched& S, const Epi& E) {
;     ...
;             PG8_WAIT_V(8); PG8_WAIT_L(0); PG8_BAR; PG8_MMA(1, 0, At, B0); PG8_MMA(1, 1, At, B1); PG8_BAR; PG8_SCHED;
;             PG8_LDB(B0, 1, 0); PG8_LDB(B1, 1, 1); PG8_SCHED; PG8_LDA(At, 1, 0); PG8_STAGE(PG8_SA(0, 1), a2 + hstepA, voffA);
;             PG8_WAIT_V(8); PG8_WAIT_L(0); PG8_BAR; PG8_MMA(0, 0, At, B0); PG8_MMA(0, 1, At, B1); PG8_BAR; PG8_SCHED;
	s_waitcnt lgkmcnt(0)
	v_mfma_f32_16x16x32_bf16 v[60:63], v[140:143], v[184:187], v[60:63]
	v_mfma_f32_16x16x32_bf16 v[56:59], v[154:157], v[184:187], v[56:59]
	v_mfma_f32_16x16x32_bf16 v[44:47], v[140:143], v[192:195], v[44:47]
	v_mfma_f32_16x16x32_bf16 v[40:43], v[154:157], v[192:195], v[40:43]
	v_mfma_f32_16x16x32_bf16 v[28:31], v[140:143], v[200:203], v[28:31]
	v_mfma_f32_16x16x32_bf16 v[24:27], v[154:157], v[200:203], v[24:27]
	v_mfma_f32_16x16x32_bf16 v[12:15], v[140:143], v[208:211], v[12:15]
	v_mfma_f32_16x16x32_bf16 v[8:11], v[154:157], v[208:211], v[8:11]
	v_mfma_f32_16x16x32_bf16 v[60:63], v[150:153], v[188:191], v[60:63]
	v_mfma_f32_16x16x32_bf16 v[56:59], v[158:161], v[188:191], v[56:59]
	v_mfma_f32_16x16x32_bf16 v[44:47], v[150:153], v[196:199], v[44:47]
	v_mfma_f32_16x16x32_bf16 v[40:43], v[158:161], v[196:199], v[40:43]
	v_mfma_f32_16x16x32_bf16 v[28:31], v[150:153], v[204:207], v[28:31]
	v_mfma_f32_16x16x32_bf16 v[24:27], v[158:161], v[204:207], v[24:27]
	v_mfma_f32_16x16x32_bf16 v[12:15], v[150:153], v[212:215], v[12:15]
	v_mfma_f32_16x16x32_bf16 v[8:11], v[158:161], v[212:215], v[8:11]
	v_mfma_f32_16x16x32_bf16 v[52:55], v[162:165], v[184:187], v[52:55]
	v_mfma_f32_16x16x32_bf16 v[48:51], v[170:173], v[184:187], v[48:51]
	v_mfma_f32_16x16x32_bf16 v[36:39], v[162:165], v[192:195], v[36:39]
	v_mfma_f32_16x16x32_bf16 v[32:35], v[170:173], v[192:195], v[32:35]
	v_mfma_f32_16x16x32_bf16 v[20:23], v[162:165], v[200:203], v[20:23]
	v_mfma_f32_16x16x32_bf16 v[16:19], v[170:173], v[200:203], v[16:19]
	v_mfma_f32_16x16x32_bf16 v[4:7], v[162:165], v[208:211], v[4:7]
	v_mfma_f32_16x16x32_bf16 v[0:3], v[170:173], v[208:211], v[0:3]
	v_mfma_f32_16x16x32_bf16 v[52:55], v[166:169], v[188:191], v[52:55]
	v_mfma_f32_16x16x32_bf16 v[48:51], v[180:183], v[188:191], v[48:51]
	v_mfma_f32_16x16x32_bf16 v[36:39], v[166:169], v[196:199], v[36:39]
	v_mfma_f32_16x16x32_bf16 v[32:35], v[180:183], v[196:199], v[32:35]
	v_mfma_f32_16x16x32_bf16 v[20:23], v[166:169], v[204:207], v[20:23]
	v_mfma_f32_16x16x32_bf16 v[16:19], v[180:183], v[204:207], v[16:19]
	v_mfma_f32_16x16x32_bf16 v[4:7], v[166:169], v[212:215], v[4:7]
	v_mfma_f32_16x16x32_bf16 v[0:3], v[180:183], v[212:215], v[0:3]
	s_barrier
	s_add_i32 s78, 0, 0x18000
	s_add_i32 s79, 0, 0x1c000
	v_add_u32_e32 v158, s78, v145
	v_add_u32_e32 v177, s79, v145
	ds_read_b128 v[140:143], v158
	ds_read_b128 v[150:153], v158 offset:1024
	ds_read_b128 v[154:157], v158 offset:2048
	ds_read_b128 v[158:161], v158 offset:3072
	ds_read_b128 v[162:165], v177
	ds_read_b128 v[166:169], v177 offset:1024
	ds_read_b128 v[170:173], v177 offset:2048
	ds_read_b128 v[180:183], v177 offset:3072
	s_add_u32 s24, s24, 0x80000
	s_addc_u32 s25, s25, 0
	s_mov_b32 m0, s26
	v_lshl_add_u64 v[222:223], s[24:25], 0, v[128:129]
	ds_read_b128 v[184:187], v149 offset:32768
	ds_read_b128 v[188:191], v149 offset:33792
	ds_read_b128 v[192:195], v149 offset:34816
	ds_read_b128 v[196:199], v149 offset:35840
	ds_read_b128 v[200:203], v149 offset:36864
	ds_read_b128 v[204:207], v149 offset:37888
	ds_read_b128 v[208:211], v149 offset:38912
	ds_read_b128 v[212:215], v149 offset:39936
	global_load_lds_dwordx4 v[222:223], off
	v_lshl_add_u64 v[222:223], s[24:25], 0, v[132:133]
	s_mov_b32 m0, s27
	s_nop 0
	global_load_lds_dwordx4 v[222:223], off
	s_waitcnt vmcnt(8)
	s_waitcnt lgkmcnt(0)
	s_barrier
	s_waitcnt lgkmcnt(0)
	v_mfma_f32_16x16x32_bf16 v[124:127], v[140:143], v[184:187], v[124:127]
	v_mfma_f32_16x16x32_bf16 v[120:123], v[154:157], v[184:187], v[120:123]
	v_mfma_f32_16x16x32_bf16 v[108:111], v[140:143], v[192:195], v[108:111]
	v_mfma_f32_16x16x32_bf16 v[104:107], v[154:157], v[192:195], v[104:107]
	v_mfma_f32_16x16x32_bf16 v[92:95], v[140:143], v[200:203], v[92:95]
	v_mfma_f32_16x16x32_bf16 v[88:91], v[154:157], v[200:203], v[88:91]
	v_mfma_f32_16x16x32_bf16 v[76:79], v[140:143], v[208:211], v[76:79]
	v_mfma_f32_16x16x32_bf16 v[72:75], v[154:157], v[208:211], v[72:75]
	v_mfma_f32_16x16x32_bf16 v[124:127], v[150:153], v[188:191], v[124:127]
	v_mfma_f32_16x16x32_bf16 v[120:123], v[158:161], v[188:191], v[120:123]
	v_mfma_f32_16x16x32_bf16 v[108:111], v[150:153], v[196:199], v[108:111]
	v_mfma_f32_16x16x32_bf16 v[104:107], v[158:161], v[196:199], v[104:107]
	v_mfma_f32_16x16x32_bf16 v[92:95], v[150:153], v[204:207], v[92:95]
	v_mfma_f32_16x16x32_bf16 v[88:91], v[158:161], v[204:207], v[88:91]
	v_mfma_f32_16x16x32_bf16 v[76:79], v[150:153], v[212:215], v[76:79]
	v_mfma_f32_16x16x32_bf16 v[72:75], v[158:161], v[212:215], v[72:75]
	v_mfma_f32_16x16x32_bf16 v[116:119], v[162:165], v[184:187], v[116:119]
	v_mfma_f32_16x16x32_bf16 v[112:115], v[170:173], v[184:187], v[112:115]
	v_mfma_f32_16x16x32_bf16 v[100:103], v[162:165], v[192:195], v[100:103]
	v_mfma_f32_16x16x32_bf16 v[96:99], v[170:173], v[192:195], v[96:99]
	v_mfma_f32_16x16x32_bf16 v[84:87], v[162:165], v[200:203], v[84:87]
	v_mfma_f32_16x16x32_bf16 v[80:83], v[170:173], v[200:203], v[80:83]
	v_mfma_f32_16x16x32_bf16 v[68:71], v[162:165], v[208:211], v[68:71]
	v_mfma_f32_16x16x32_bf16 v[64:67], v[170:173], v[208:211], v[64:67]
	v_mfma_f32_16x16x32_bf16 v[116:119], v[166:169], v[188:191], v[116:119]
	v_mfma_f32_16x16x32_bf16 v[112:115], v[180:183], v[188:191], v[112:115]
	v_mfma_f32_16x16x32_bf16 v[100:103], v[166:169], v[196:199], v[100:103]
	v_mfma_f32_16x16x32_bf16 v[96:99], v[180:183], v[196:199], v[96:99]
	v_mfma_f32_16x16x32_bf16 v[84:87], v[166:169], v[204:207], v[84:87]
	v_mfma_f32_16x16x32_bf16 v[80:83], v[180:183], v[204:207], v[80:83]
	v_mfma_f32_16x16x32_bf16 v[68:71], v[166:169], v[212:215], v[68:71]
	v_mfma_f32_16x16x32_bf16 v[64:67], v[180:183], v[212:215], v[64:67]
	s_barrier
; #define PG8_STAGE(bufoff, gbase, voff) do { _Pragma("unroll") for (int _i = 0; _i < 2; ++_i) \
;         __builtin_amdgcn_global_load_lds((const unsigned*)((const char*)(gbase) + (voff)[_i]), (LAS unsigned*)(lds + (bufoff) + ldsw + _i * 8192), 16, 0, 0); } while (0)
; #define PG8_LDA(dst, b, h) do { _Pragma("unroll") for (int m = 0; m < 4; ++m) _Pragma("unroll") for (int k = 0; k < 2; ++k) dst[m][k] = *(const LAS bf16x8*)(lds + PG8_SA(b, h) + aoff + m * 2048 + k * 1024); } while (0)
; #define PG8_MMA(ai, bj, At, Bt) do { __builtin_amdgcn_s_setprio(1); _Pragma("unroll") for (int m = 0; m < 4; ++m) _Pragma("unroll") for (int n = 0; n < 2; ++n) _Pragma("unroll") for (int k = 0; k < 2; ++k) \
;         acc[ai][bj][m][n] = __builtin_amdgcn_mfma_f32_16x16x32_bf16(Bt[n][k], At[m][k], acc[ai][bj][m][n], 0, 0, 0); __builtin_amdgcn_s_setprio(0); } while (0)
; #define PG8_WAIT_V(n) asm volatile("s_waitcnt vmcnt(" #n ")" ::: "memory")
; #define PG8_WAIT_L(n) asm volatile("s_waitcnt lgkmcnt(" #n ")" ::: "memory")
; #define PG8_BAR __builtin_amdgcn_s_barrier()
; #define PG8_SCHED __builtin_amdgcn_sched_barrier(0)
; template <class Sched, class Epi, bool ALIGN_EPI, bool SP2>
; __device__ __forceinline__ void gemm_phase(LAS unsigned char* lds, const int K, const int lda, const int ldb, const Sched& S, const Epi& E) {
;     ...
;             PG8_LDA(At, 1, 1); PG8_STAGE(PG8_SB(1, 0), b3, voffB); PG8_STAGE(PG8_SB(1, 1), b3 + hstepB, voffB); PG8_STAGE(PG8_SA(1, 0), a3, voffA);
;             PG8_WAIT_V(8); PG8_WAIT_L(0); PG8_BAR; PG8_MMA(1, 0, At, B0); PG8_MMA(1, 1, At, B1); PG8_BAR; PG8_SCHED;
;     ...
;         }
;         if constexpr (ALIGN_EPI) { if (wr == 0) PG8_BAR; }
	s_add_i32 s24, s78, s2
	v_lshl_add_u64 v[174:175], v[174:175], 0, s[4:5]
	s_mov_b32 m0, s24
	ds_read_b128 v[184:187], v149 offset:49152
	ds_read_b128 v[188:191], v149 offset:50176
	ds_read_b128 v[192:195], v149 offset:51200
	ds_read_b128 v[196:199], v149 offset:52224
	ds_read_b128 v[200:203], v149 offset:53248
	ds_read_b128 v[204:207], v149 offset:54272
	ds_read_b128 v[208:211], v149 offset:55296
	ds_read_b128 v[212:215], v149 offset:56320
	global_load_lds_dwordx4 v[174:175], off
	s_add_i32 m0, s24, 0x2000
	s_add_u32 s22, s22, 0x80080
	v_lshl_add_u64 v[174:175], v[216:217], 0, s[4:5]
	s_addc_u32 s23, s23, 0
	s_add_i32 s24, s79, s2
	global_load_lds_dwordx4 v[174:175], off
	v_lshl_add_u64 v[174:175], s[22:23], 0, v[130:131]
	s_mov_b32 m0, s24
	s_nop 0
	global_load_lds_dwordx4 v[174:175], off
	v_lshl_add_u64 v[174:175], s[22:23], 0, v[134:135]
	s_add_i32 m0, s24, 0x2000
	s_nop 0
	global_load_lds_dwordx4 v[174:175], off
	v_lshl_add_u64 v[174:175], v[218:219], 0, s[4:5]
	s_mov_b32 m0, s29
	s_nop 0
	global_load_lds_dwordx4 v[174:175], off
	v_lshl_add_u64 v[174:175], v[220:221], 0, s[4:5]
	s_mov_b32 m0, s33
	s_nop 0
	global_load_lds_dwordx4 v[174:175], off
	s_waitcnt vmcnt(8)
	s_waitcnt lgkmcnt(0)
	s_barrier
	s_waitcnt lgkmcnt(0)
	v_mfma_f32_16x16x32_bf16 v[60:63], v[140:143], v[184:187], v[60:63]
	v_mfma_f32_16x16x32_bf16 v[56:59], v[154:157], v[184:187], v[56:59]
	v_mfma_f32_16x16x32_bf16 v[44:47], v[140:143], v[192:195], v[44:47]
	v_mfma_f32_16x16x32_bf16 v[40:43], v[154:157], v[192:195], v[40:43]
	v_mfma_f32_16x16x32_bf16 v[28:31], v[140:143], v[200:203], v[28:31]
	v_mfma_f32_16x16x32_bf16 v[24:27], v[154:157], v[200:203], v[24:27]
	v_mfma_f32_16x16x32_bf16 v[12:15], v[140:143], v[208:211], v[12:15]
	v_mfma_f32_16x16x32_bf16 v[8:11], v[154:157], v[208:211], v[8:11]
	v_mfma_f32_16x16x32_bf16 v[60:63], v[150:153], v[188:191], v[60:63]
	v_mfma_f32_16x16x32_bf16 v[56:59], v[158:161], v[188:191], v[56:59]
	v_mfma_f32_16x16x32_bf16 v[44:47], v[150:153], v[196:199], v[44:47]
	v_mfma_f32_16x16x32_bf16 v[40:43], v[158:161], v[196:199], v[40:43]
	v_mfma_f32_16x16x32_bf16 v[28:31], v[150:153], v[204:207], v[28:31]
	v_mfma_f32_16x16x32_bf16 v[24:27], v[158:161], v[204:207], v[24:27]
	v_mfma_f32_16x16x32_bf16 v[12:15], v[150:153], v[212:215], v[12:15]
	v_mfma_f32_16x16x32_bf16 v[8:11], v[158:161], v[212:215], v[8:11]
	v_mfma_f32_16x16x32_bf16 v[52:55], v[162:165], v[184:187], v[52:55]
	v_mfma_f32_16x16x32_bf16 v[48:51], v[170:173], v[184:187], v[48:51]
	v_mfma_f32_16x16x32_bf16 v[36:39], v[162:165], v[192:195], v[36:39]
	v_mfma_f32_16x16x32_bf16 v[32:35], v[170:173], v[192:195], v[32:35]
	v_mfma_f32_16x16x32_bf16 v[20:23], v[162:165], v[200:203], v[20:23]
	v_mfma_f32_16x16x32_bf16 v[16:19], v[170:173], v[200:203], v[16:19]
	v_mfma_f32_16x16x32_bf16 v[4:7], v[162:165], v[208:211], v[4:7]
	v_mfma_f32_16x16x32_bf16 v[0:3], v[170:173], v[208:211], v[0:3]
	v_mfma_f32_16x16x32_bf16 v[52:55], v[166:169], v[188:191], v[52:55]
	v_mfma_f32_16x16x32_bf16 v[48:51], v[180:183], v[188:191], v[48:51]
	v_mfma_f32_16x16x32_bf16 v[36:39], v[166:169], v[196:199], v[36:39]
	v_mfma_f32_16x16x32_bf16 v[32:35], v[180:183], v[196:199], v[32:35]
	v_mfma_f32_16x16x32_bf16 v[20:23], v[166:169], v[204:207], v[20:23]
	v_mfma_f32_16x16x32_bf16 v[16:19], v[180:183], v[204:207], v[16:19]
	v_mfma_f32_16x16x32_bf16 v[4:7], v[166:169], v[212:215], v[4:7]
	v_mfma_f32_16x16x32_bf16 v[0:3], v[180:183], v[212:215], v[0:3]
	s_barrier
	s_add_i32 s75, s75, 2
	s_add_u32 s20, s20, 0x100
	s_addc_u32 s21, s21, 0
	s_add_u32 s13, s13, 0x100
	s_addc_u32 s74, s74, 0
	s_cmp_gt_u32 s75, 29
	s_cbranch_scc0 .LBB0_155
	s_and_b64 vcc, exec, s[6:7]
	s_cbranch_vccz .LBB0_158
	s_barrier

; #define PG8_STAGE(bufoff, gbase, voff) do { _Pragma("unroll") for (int _i = 0; _i < 2; ++_i) \
;         __builtin_amdgcn_global_load_lds((const unsigned*)((const char*)(gbase) + (voff)[_i]), (LAS unsigned*)(lds + (bufoff) + ldsw + _i * 8192), 16, 0, 0); } while (0)
; #define PG8_LDA(dst, b, h) do { _Pragma("unroll") for (int m = 0; m < 4; ++m) _Pragma("unroll") for (int k = 0; k < 2; ++k) dst[m][k] = *(const LAS bf16x8*)(lds + PG8_SA(b, h) + aoff + m * 2048 + k * 1024); } while (0)
; #define PG8_LDB(dst, b, h) do { _Pragma("unroll") for (int n = 0; n < 2; ++n) _Pragma("unroll") for (int k = 0; k < 2; ++k) dst[n][k] = *(const LAS bf16x8*)(lds + PG8_SB(b, h) + boff + n * 2048 + k * 1024); } while (0)
; #define PG8_MMA(ai, bj, At, Bt) do { __builtin_amdgcn_s_setprio(1); _Pragma("unroll") for (int m = 0; m < 4; ++m) _Pragma("unroll") for (int n = 0; n < 2; ++n) _Pragma("unroll") for (int k = 0; k < 2; ++k) \
;         acc[ai][bj][m][n] = __builtin_amdgcn_mfma_f32_16x16x32_bf16(Bt[n][k], At[m][k], acc[ai][bj][m][n], 0, 0, 0); __builtin_amdgcn_s_setprio(0); } while (0)
; #define PG8_WAIT_V(n) asm volatile("s_waitcnt vmcnt(" #n ")" ::: "memory")
; #define PG8_WAIT_L(n) asm volatile("s_waitcnt lgkmcnt(" #n ")" ::: "memory")
; #define PG8_BAR __builtin_amdgcn_s_barrier()
; #define PG8_SCHED __builtin_amdgcn_sched_barrier(0)
; template <class Sched, class Epi, bool ALIGN_EPI, bool SP2>
; __device__ __forceinline__ void gemm_phase(LAS unsigned char* lds, const int K, const int lda, const int ldb, const Sched& S, const Epi& E) {
;     ...
;             const bool last = (t == nt - 2);
;             const char* a1 = cA + (size_t)(t + 1) * kstep;
;             const char* a2 = last ? nA : cA + (size_t)(t + 2) * kstep; const char* b2 = last ? nB : cB + (size_t)(t + 2) * kstep;
;             const char* a3 = a2 + kstep; const char* b3 = b2 + kstep;
;             if constexpr (SP2) {
;             PG8_LDB(B0, 0, 0); PG8_LDB(B1, 0, 1); PG8_SCHED; PG8_LDA(At, 0, 0); PG8_STAGE(PG8_SA(1, 1), a1 + hstepA, voffA);
;             PG8_WAIT_V(8); PG8_WAIT_L(0); PG8_BAR; PG8_MMA(0, 0, At, B0); PG8_MMA(0, 1, At, B1); PG8_BAR; PG8_SCHED;
;             PG8_LDA(At, 0, 1); PG8_STAGE(PG8_SB(0, 0), b2, voffB); PG8_STAGE(PG8_SB(0, 1), b2 + hstepB, voffB); PG8_STAGE(PG8_SA(0, 0), a2, voffA);
.Lprio_skip_243:
.LBB0_243:
	ds_read_b128 v[124:127], v169
	ds_read_b128 v[132:135], v169 offset:1024
	ds_read_b128 v[136:139], v169 offset:2048
	ds_read_b128 v[140:143], v169 offset:3072
	ds_read_b128 v[144:147], v170
	ds_read_b128 v[156:159], v170 offset:1024
	ds_read_b128 v[160:163], v170 offset:2048
	ds_read_b128 v[182:185], v170 offset:3072
	s_add_u32 s22, s20, 0x100
	s_addc_u32 s23, s21, 0
	s_cmpk_eq_i32 s91, 0x54
	s_cselect_b32 s27, s17, s23
	s_cselect_b32 s26, s16, s22
	s_cselect_b32 s25, s19, s90
	s_cselect_b32 s24, s18, s89
	s_mov_b32 m0, s78
	v_lshl_add_u64 v[164:165], s[20:21], 0, v[152:153]
	ds_read_b128 v[186:189], v171
	ds_read_b128 v[190:193], v171 offset:1024
	ds_read_b128 v[194:197], v171 offset:2048
	ds_read_b128 v[198:201], v171 offset:3072
	ds_read_b128 v[202:205], v171 offset:4096
	ds_read_b128 v[206:209], v171 offset:5120
	ds_read_b128 v[210:213], v171 offset:6144
	ds_read_b128 v[214:217], v171 offset:7168
	global_load_lds_dwordx4 v[164:165], off
	v_lshl_add_u64 v[164:165], s[20:21], 0, v[154:155]
	s_mov_b32 m0, s79
	s_nop 0
	global_load_lds_dwordx4 v[164:165], off
	s_waitcnt vmcnt(8)
	s_waitcnt lgkmcnt(0)
	s_barrier
	s_waitcnt lgkmcnt(0)
	v_mfma_f32_16x16x32_bf16 v[128:131], v[124:127], v[186:189], v[128:131]
	v_mfma_f32_16x16x32_bf16 v[120:123], v[136:139], v[186:189], v[120:123]
	v_mfma_f32_16x16x32_bf16 v[108:111], v[124:127], v[194:197], v[108:111]
	v_mfma_f32_16x16x32_bf16 v[104:107], v[136:139], v[194:197], v[104:107]
	v_mfma_f32_16x16x32_bf16 v[92:95], v[124:127], v[202:205], v[92:95]
	v_mfma_f32_16x16x32_bf16 v[88:91], v[136:139], v[202:205], v[88:91]
	v_mfma_f32_16x16x32_bf16 v[76:79], v[124:127], v[210:213], v[76:79]
	v_mfma_f32_16x16x32_bf16 v[72:75], v[136:139], v[210:213], v[72:75]
	v_mfma_f32_16x16x32_bf16 v[128:131], v[132:135], v[190:193], v[128:131]
	v_mfma_f32_16x16x32_bf16 v[120:123], v[140:143], v[190:193], v[120:123]
	v_mfma_f32_16x16x32_bf16 v[108:111], v[132:135], v[198:201], v[108:111]
	v_mfma_f32_16x16x32_bf16 v[104:107], v[140:143], v[198:201], v[104:107]
	v_mfma_f32_16x16x32_bf16 v[92:95], v[132:135], v[206:209], v[92:95]
	v_mfma_f32_16x16x32_bf16 v[88:91], v[140:143], v[206:209], v[88:91]
	v_mfma_f32_16x16x32_bf16 v[76:79], v[132:135], v[214:217], v[76:79]
	v_mfma_f32_16x16x32_bf16 v[72:75], v[140:143], v[214:217], v[72:75]
	v_mfma_f32_16x16x32_bf16 v[116:119], v[144:147], v[186:189], v[116:119]
	v_mfma_f32_16x16x32_bf16 v[112:115], v[160:163], v[186:189], v[112:115]
	v_mfma_f32_16x16x32_bf16 v[100:103], v[144:147], v[194:197], v[100:103]
	v_mfma_f32_16x16x32_bf16 v[96:99], v[160:163], v[194:197], v[96:99]
	v_mfma_f32_16x16x32_bf16 v[84:87], v[144:147], v[202:205], v[84:87]
	v_mfma_f32_16x16x32_bf16 v[80:83], v[160:163], v[202:205], v[80:83]
	v_mfma_f32_16x16x32_bf16 v[68:71], v[144:147], v[210:213], v[68:71]
	v_mfma_f32_16x16x32_bf16 v[64:67], v[160:163], v[210:213], v[64:67]
	v_mfma_f32_16x16x32_bf16 v[116:119], v[156:159], v[190:193], v[116:119]
	v_mfma_f32_16x16x32_bf16 v[112:115], v[182:185], v[190:193], v[112:115]
	v_mfma_f32_16x16x32_bf16 v[100:103], v[156:159], v[198:201], v[100:103]
	v_mfma_f32_16x16x32_bf16 v[96:99], v[182:185], v[198:201], v[96:99]
	v_mfma_f32_16x16x32_bf16 v[84:87], v[156:159], v[206:209], v[84:87]
	v_mfma_f32_16x16x32_bf16 v[80:83], v[182:185], v[206:209], v[80:83]
	v_mfma_f32_16x16x32_bf16 v[68:71], v[156:159], v[214:217], v[68:71]
	v_mfma_f32_16x16x32_bf16 v[64:67], v[182:185], v[214:217], v[64:67]
	s_barrier
	s_mov_b32 m0, s84
	v_lshl_add_u64 v[164:165], s[24:25], 0, v[148:149]
	ds_read_b128 v[186:189], v171 offset:16384
	ds_read_b128 v[190:193], v171 offset:17408
	ds_read_b128 v[194:197], v171 offset:18432
	ds_read_b128 v[198:201], v171 offset:19456
	ds_read_b128 v[202:205], v171 offset:20480
	ds_read_b128 v[206:209], v171 offset:21504
	ds_read_b128 v[210:213], v171 offset:22528
	ds_read_b128 v[214:217], v171 offset:23552
	global_load_lds_dwordx4 v[164:165], off
	s_add_i32 m0, s84, 0x2000
	s_add_u32 s20, s24, 0x160000
	v_lshl_add_u64 v[174:175], s[24:25], 0, v[150:151]
	s_addc_u32 s21, s25, 0
	s_add_i32 s96, s53, s13
	global_load_lds_dwordx4 v[174:175], off
	v_lshl_add_u64 v[218:219], s[20:21], 0, v[148:149]
	s_mov_b32 m0, s96
	v_lshl_add_u64 v[220:221], s[26:27], 0, v[150:151]
	global_load_lds_dwordx4 v[218:219], off
	v_lshl_add_u64 v[218:219], s[20:21], 0, v[150:151]
	s_add_i32 m0, s96, 0x2000
	s_nop 0
	global_load_lds_dwordx4 v[218:219], off
	v_lshl_add_u64 v[218:219], s[26:27], 0, v[148:149]
	s_mov_b32 m0, s28
	s_nop 0
	global_load_lds_dwordx4 v[218:219], off
	s_mov_b32 m0, s29
	s_nop 0
	global_load_lds_dwordx4 v[220:221], off
	s_waitcnt vmcnt(8)
	s_waitcnt lgkmcnt(0)
	s_barrier
; #define PG8_STAGE(bufoff, gbase, voff) do { _Pragma("unroll") for (int _i = 0; _i < 2; ++_i) \
;         __builtin_amdgcn_global_load_lds((const unsigned*)((const char*)(gbase) + (voff)[_i]), (LAS unsigned*)(lds + (bufoff) + ldsw + _i * 8192), 16, 0, 0); } while (0)
; #define PG8_LDA(dst, b, h) do { _Pragma("unroll") for (int m = 0; m < 4; ++m) _Pragma("unroll") for (int k = 0; k < 2; ++k) dst[m][k] = *(const LAS bf16x8*)(lds + PG8_SA(b, h) + aoff + m * 2048 + k * 1024); } while (0)
; #define PG8_LDB(dst, b, h) do { _Pragma("unroll") for (int n = 0; n < 2; ++n) _Pragma("unroll") for (int k = 0; k < 2; ++k) dst[n][k] = *(const LAS bf16x8*)(lds + PG8_SB(b, h) + boff + n * 2048 + k * 1024); } while (0)
; #define PG8_MMA(ai, bj, At, Bt) do { __builtin_amdgcn_s_setprio(1); _Pragma("unroll") for (int m = 0; m < 4; ++m) _Pragma("unroll") for (int n = 0; n < 2; ++n) _Pragma("unroll") for (int k = 0; k < 2; ++k) \
;         acc[ai][bj][m][n] = __builtin_amdgcn_mfma_f32_16x16x32_bf16(Bt[n][k], At[m][k], acc[ai][bj][m][n], 0, 0, 0); __builtin_amdgcn_s_setprio(0); } while (0)
; #define PG8_WAIT_V(n) asm volatile("s_waitcnt vmcnt(" #n ")" ::: "memory")
; #define PG8_WAIT_L(n) asm volatile("s_waitcnt lgkmcnt(" #n ")" ::: "memory")
; #define PG8_BAR __builtin_amdgcn_s_barrier()
; #define PG8_SCHED __builtin_amdgcn_sched_barrier(0)
; template <class Sched, class Epi, bool ALIGN_EPI, bool SP2>
; __device__ __forceinline__ void gemm_phase(LAS unsigned char* lds, const int K, const int lda, const int ldb, const Sched& S, const Epi& E) {
;     ...
;             PG8_WAIT_V(8); PG8_WAIT_L(0); PG8_BAR; PG8_MMA(1, 0, At, B0); PG8_MMA(1, 1, At, B1); PG8_BAR; PG8_SCHED;
;             PG8_LDB(B0, 1, 0); PG8_LDB(B1, 1, 1); PG8_SCHED; PG8_LDA(At, 1, 0); PG8_STAGE(PG8_SA(0, 1), a2 + hstepA, voffA);
;             PG8_WAIT_V(8); PG8_WAIT_L(0); PG8_BAR; PG8_MMA(0, 0, At, B0); PG8_MMA(0, 1, At, B1); PG8_BAR; PG8_SCHED;
	s_waitcnt lgkmcnt(0)
	v_mfma_f32_16x16x32_bf16 v[60:63], v[124:127], v[186:189], v[60:63]
	v_mfma_f32_16x16x32_bf16 v[56:59], v[136:139], v[186:189], v[56:59]
	v_mfma_f32_16x16x32_bf16 v[44:47], v[124:127], v[194:197], v[44:47]
	v_mfma_f32_16x16x32_bf16 v[40:43], v[136:139], v[194:197], v[40:43]
	v_mfma_f32_16x16x32_bf16 v[28:31], v[124:127], v[202:205], v[28:31]
	v_mfma_f32_16x16x32_bf16 v[24:27], v[136:139], v[202:205], v[24:27]
	v_mfma_f32_16x16x32_bf16 v[12:15], v[124:127], v[210:213], v[12:15]
	v_mfma_f32_16x16x32_bf16 v[8:11], v[136:139], v[210:213], v[8:11]
	v_mfma_f32_16x16x32_bf16 v[60:63], v[132:135], v[190:193], v[60:63]
	v_mfma_f32_16x16x32_bf16 v[56:59], v[140:143], v[190:193], v[56:59]
	v_mfma_f32_16x16x32_bf16 v[44:47], v[132:135], v[198:201], v[44:47]
	v_mfma_f32_16x16x32_bf16 v[40:43], v[140:143], v[198:201], v[40:43]
	v_mfma_f32_16x16x32_bf16 v[28:31], v[132:135], v[206:209], v[28:31]
	v_mfma_f32_16x16x32_bf16 v[24:27], v[140:143], v[206:209], v[24:27]
	v_mfma_f32_16x16x32_bf16 v[12:15], v[132:135], v[214:217], v[12:15]
	v_mfma_f32_16x16x32_bf16 v[8:11], v[140:143], v[214:217], v[8:11]
	v_mfma_f32_16x16x32_bf16 v[52:55], v[144:147], v[186:189], v[52:55]
	v_mfma_f32_16x16x32_bf16 v[48:51], v[160:163], v[186:189], v[48:51]
	v_mfma_f32_16x16x32_bf16 v[36:39], v[144:147], v[194:197], v[36:39]
	v_mfma_f32_16x16x32_bf16 v[32:35], v[160:163], v[194:197], v[32:35]
	v_mfma_f32_16x16x32_bf16 v[20:23], v[144:147], v[202:205], v[20:23]
	v_mfma_f32_16x16x32_bf16 v[16:19], v[160:163], v[202:205], v[16:19]
	v_mfma_f32_16x16x32_bf16 v[4:7], v[144:147], v[210:213], v[4:7]
	v_mfma_f32_16x16x32_bf16 v[0:3], v[160:163], v[210:213], v[0:3]
	v_mfma_f32_16x16x32_bf16 v[52:55], v[156:159], v[190:193], v[52:55]
	v_mfma_f32_16x16x32_bf16 v[48:51], v[182:185], v[190:193], v[48:51]
	v_mfma_f32_16x16x32_bf16 v[36:39], v[156:159], v[198:201], v[36:39]
	v_mfma_f32_16x16x32_bf16 v[32:35], v[182:185], v[198:201], v[32:35]
	v_mfma_f32_16x16x32_bf16 v[20:23], v[156:159], v[206:209], v[20:23]
	v_mfma_f32_16x16x32_bf16 v[16:19], v[182:185], v[206:209], v[16:19]
	v_mfma_f32_16x16x32_bf16 v[4:7], v[156:159], v[214:217], v[4:7]
	v_mfma_f32_16x16x32_bf16 v[0:3], v[182:185], v[214:217], v[0:3]
	s_barrier
	s_add_i32 s96, 0, 0x18000
	s_add_i32 s97, 0, 0x1c000
	v_add_u32_e32 v140, s96, v167
	v_add_u32_e32 v173, s97, v167
	ds_read_b128 v[124:127], v140
	ds_read_b128 v[132:135], v140 offset:1024
	ds_read_b128 v[136:139], v140 offset:2048
	ds_read_b128 v[140:143], v140 offset:3072
	ds_read_b128 v[144:147], v173
	ds_read_b128 v[156:159], v173 offset:1024
	ds_read_b128 v[160:163], v173 offset:2048
	ds_read_b128 v[182:185], v173 offset:3072
	s_add_u32 s20, s26, 0x160000
	s_addc_u32 s21, s27, 0
	s_mov_b32 m0, s33
	v_lshl_add_u64 v[222:223], s[20:21], 0, v[148:149]
	ds_read_b128 v[186:189], v171 offset:32768
	ds_read_b128 v[190:193], v171 offset:33792
	ds_read_b128 v[194:197], v171 offset:34816
	ds_read_b128 v[198:201], v171 offset:35840
	ds_read_b128 v[202:205], v171 offset:36864
	ds_read_b128 v[206:209], v171 offset:37888
	ds_read_b128 v[210:213], v171 offset:38912
	ds_read_b128 v[214:217], v171 offset:39936
	global_load_lds_dwordx4 v[222:223], off
	v_lshl_add_u64 v[222:223], s[20:21], 0, v[150:151]
	s_mov_b32 m0, s35
	s_nop 0
	global_load_lds_dwordx4 v[222:223], off
	s_waitcnt vmcnt(8)
	s_waitcnt lgkmcnt(0)
	s_barrier
	s_waitcnt lgkmcnt(0)
	v_mfma_f32_16x16x32_bf16 v[128:131], v[124:127], v[186:189], v[128:131]
	v_mfma_f32_16x16x32_bf16 v[120:123], v[136:139], v[186:189], v[120:123]
	v_mfma_f32_16x16x32_bf16 v[108:111], v[124:127], v[194:197], v[108:111]
	v_mfma_f32_16x16x32_bf16 v[104:107], v[136:139], v[194:197], v[104:107]
	v_mfma_f32_16x16x32_bf16 v[92:95], v[124:127], v[202:205], v[92:95]
	v_mfma_f32_16x16x32_bf16 v[88:91], v[136:139], v[202:205], v[88:91]
	v_mfma_f32_16x16x32_bf16 v[76:79], v[124:127], v[210:213], v[76:79]
	v_mfma_f32_16x16x32_bf16 v[72:75], v[136:139], v[210:213], v[72:75]
	v_mfma_f32_16x16x32_bf16 v[128:131], v[132:135], v[190:193], v[128:131]
	v_mfma_f32_16x16x32_bf16 v[120:123], v[140:143], v[190:193], v[120:123]
	v_mfma_f32_16x16x32_bf16 v[108:111], v[132:135], v[198:201], v[108:111]
	v_mfma_f32_16x16x32_bf16 v[104:107], v[140:143], v[198:201], v[104:107]
	v_mfma_f32_16x16x32_bf16 v[92:95], v[132:135], v[206:209], v[92:95]
	v_mfma_f32_16x16x32_bf16 v[88:91], v[140:143], v[206:209], v[88:91]
	v_mfma_f32_16x16x32_bf16 v[76:79], v[132:135], v[214:217], v[76:79]
	v_mfma_f32_16x16x32_bf16 v[72:75], v[140:143], v[214:217], v[72:75]
	v_mfma_f32_16x16x32_bf16 v[116:119], v[144:147], v[186:189], v[116:119]
	v_mfma_f32_16x16x32_bf16 v[112:115], v[160:163], v[186:189], v[112:115]
	v_mfma_f32_16x16x32_bf16 v[100:103], v[144:147], v[194:197], v[100:103]
	v_mfma_f32_16x16x32_bf16 v[96:99], v[160:163], v[194:197], v[96:99]
	v_mfma_f32_16x16x32_bf16 v[84:87], v[144:147], v[202:205], v[84:87]
	v_mfma_f32_16x16x32_bf16 v[80:83], v[160:163], v[202:205], v[80:83]
	v_mfma_f32_16x16x32_bf16 v[68:71], v[144:147], v[210:213], v[68:71]
	v_mfma_f32_16x16x32_bf16 v[64:67], v[160:163], v[210:213], v[64:67]
	v_mfma_f32_16x16x32_bf16 v[116:119], v[156:159], v[190:193], v[116:119]
	v_mfma_f32_16x16x32_bf16 v[112:115], v[182:185], v[190:193], v[112:115]
	v_mfma_f32_16x16x32_bf16 v[100:103], v[156:159], v[198:201], v[100:103]
	v_mfma_f32_16x16x32_bf16 v[96:99], v[182:185], v[198:201], v[96:99]
	v_mfma_f32_16x16x32_bf16 v[84:87], v[156:159], v[206:209], v[84:87]
	v_mfma_f32_16x16x32_bf16 v[80:83], v[182:185], v[206:209], v[80:83]
	v_mfma_f32_16x16x32_bf16 v[68:71], v[156:159], v[214:217], v[68:71]
	v_mfma_f32_16x16x32_bf16 v[64:67], v[182:185], v[214:217], v[64:67]
	s_barrier
; #define PG8_STAGE(bufoff, gbase, voff) do { _Pragma("unroll") for (int _i = 0; _i < 2; ++_i) \
;         __builtin_amdgcn_global_load_lds((const unsigned*)((const char*)(gbase) + (voff)[_i]), (LAS unsigned*)(lds + (bufoff) + ldsw + _i * 8192), 16, 0, 0); } while (0)
; #define PG8_LDA(dst, b, h) do { _Pragma("unroll") for (int m = 0; m < 4; ++m) _Pragma("unroll") for (int k = 0; k < 2; ++k) dst[m][k] = *(const LAS bf16x8*)(lds + PG8_SA(b, h) + aoff + m * 2048 + k * 1024); } while (0)
; #define PG8_MMA(ai, bj, At, Bt) do { __builtin_amdgcn_s_setprio(1); _Pragma("unroll") for (int m = 0; m < 4; ++m) _Pragma("unroll") for (int n = 0; n < 2; ++n) _Pragma("unroll") for (int k = 0; k < 2; ++k) \
;         acc[ai][bj][m][n] = __builtin_amdgcn_mfma_f32_16x16x32_bf16(Bt[n][k], At[m][k], acc[ai][bj][m][n], 0, 0, 0); __builtin_amdgcn_s_setprio(0); } while (0)
; #define PG8_WAIT_V(n) asm volatile("s_waitcnt vmcnt(" #n ")" ::: "memory")
; #define PG8_WAIT_L(n) asm volatile("s_waitcnt lgkmcnt(" #n ")" ::: "memory")
; #define PG8_BAR __builtin_amdgcn_s_barrier()
; #define PG8_SCHED __builtin_amdgcn_sched_barrier(0)
; template <class Sched, class Epi, bool ALIGN_EPI, bool SP2>
; __device__ __forceinline__ void gemm_phase(LAS unsigned char* lds, const int K, const int lda, const int ldb, const Sched& S, const Epi& E) {
;     ...
;             PG8_LDA(At, 1, 1); PG8_STAGE(PG8_SB(1, 0), b3, voffB); PG8_STAGE(PG8_SB(1, 1), b3 + hstepB, voffB); PG8_STAGE(PG8_SA(1, 0), a3, voffA);
;             PG8_WAIT_V(8); PG8_WAIT_L(0); PG8_BAR; PG8_MMA(1, 0, At, B0); PG8_MMA(1, 1, At, B1); PG8_BAR; PG8_SCHED;
;     ...
;         }
;         if constexpr (ALIGN_EPI) { if (wr == 0) PG8_BAR; }
	s_add_i32 s20, s96, s13
	v_lshl_add_u64 v[164:165], v[164:165], 0, s[6:7]
	s_mov_b32 m0, s20
	ds_read_b128 v[186:189], v171 offset:49152
	ds_read_b128 v[190:193], v171 offset:50176
	ds_read_b128 v[194:197], v171 offset:51200
	ds_read_b128 v[198:201], v171 offset:52224
	ds_read_b128 v[202:205], v171 offset:53248
	ds_read_b128 v[206:209], v171 offset:54272
	ds_read_b128 v[210:213], v171 offset:55296
	ds_read_b128 v[214:217], v171 offset:56320
	global_load_lds_dwordx4 v[164:165], off
	s_add_i32 m0, s20, 0x2000
	s_add_u32 s20, s24, 0x160080
	v_lshl_add_u64 v[164:165], v[174:175], 0, s[6:7]
	s_addc_u32 s21, s25, 0
	s_add_i32 s24, s97, s13
	global_load_lds_dwordx4 v[164:165], off
	v_lshl_add_u64 v[164:165], s[20:21], 0, v[148:149]
	s_mov_b32 m0, s24
	s_nop 0
	global_load_lds_dwordx4 v[164:165], off
	v_lshl_add_u64 v[164:165], s[20:21], 0, v[150:151]
	s_add_i32 m0, s24, 0x2000
	s_nop 0
	global_load_lds_dwordx4 v[164:165], off
	v_lshl_add_u64 v[164:165], v[218:219], 0, s[6:7]
	s_mov_b32 m0, s51
	s_nop 0
	global_load_lds_dwordx4 v[164:165], off
	v_lshl_add_u64 v[164:165], v[220:221], 0, s[6:7]
	s_mov_b32 m0, s52
	s_nop 0
	global_load_lds_dwordx4 v[164:165], off
	s_waitcnt vmcnt(8)
	s_waitcnt lgkmcnt(0)
	s_barrier
	s_waitcnt lgkmcnt(0)
	v_mfma_f32_16x16x32_bf16 v[60:63], v[124:127], v[186:189], v[60:63]
	v_mfma_f32_16x16x32_bf16 v[56:59], v[136:139], v[186:189], v[56:59]
	v_mfma_f32_16x16x32_bf16 v[44:47], v[124:127], v[194:197], v[44:47]
	v_mfma_f32_16x16x32_bf16 v[40:43], v[136:139], v[194:197], v[40:43]
	v_mfma_f32_16x16x32_bf16 v[28:31], v[124:127], v[202:205], v[28:31]
	v_mfma_f32_16x16x32_bf16 v[24:27], v[136:139], v[202:205], v[24:27]
	v_mfma_f32_16x16x32_bf16 v[12:15], v[124:127], v[210:213], v[12:15]
	v_mfma_f32_16x16x32_bf16 v[8:11], v[136:139], v[210:213], v[8:11]
	v_mfma_f32_16x16x32_bf16 v[60:63], v[132:135], v[190:193], v[60:63]
	v_mfma_f32_16x16x32_bf16 v[56:59], v[140:143], v[190:193], v[56:59]
	v_mfma_f32_16x16x32_bf16 v[44:47], v[132:135], v[198:201], v[44:47]
	v_mfma_f32_16x16x32_bf16 v[40:43], v[140:143], v[198:201], v[40:43]
	v_mfma_f32_16x16x32_bf16 v[28:31], v[132:135], v[206:209], v[28:31]
	v_mfma_f32_16x16x32_bf16 v[24:27], v[140:143], v[206:209], v[24:27]
	v_mfma_f32_16x16x32_bf16 v[12:15], v[132:135], v[214:217], v[12:15]
	v_mfma_f32_16x16x32_bf16 v[8:11], v[140:143], v[214:217], v[8:11]
	v_mfma_f32_16x16x32_bf16 v[52:55], v[144:147], v[186:189], v[52:55]
	v_mfma_f32_16x16x32_bf16 v[48:51], v[160:163], v[186:189], v[48:51]
	v_mfma_f32_16x16x32_bf16 v[36:39], v[144:147], v[194:197], v[36:39]
	v_mfma_f32_16x16x32_bf16 v[32:35], v[160:163], v[194:197], v[32:35]
	v_mfma_f32_16x16x32_bf16 v[20:23], v[144:147], v[202:205], v[20:23]
	v_mfma_f32_16x16x32_bf16 v[16:19], v[160:163], v[202:205], v[16:19]
	v_mfma_f32_16x16x32_bf16 v[4:7], v[144:147], v[210:213], v[4:7]
	v_mfma_f32_16x16x32_bf16 v[0:3], v[160:163], v[210:213], v[0:3]
	v_mfma_f32_16x16x32_bf16 v[52:55], v[156:159], v[190:193], v[52:55]
	v_mfma_f32_16x16x32_bf16 v[48:51], v[182:185], v[190:193], v[48:51]
	v_mfma_f32_16x16x32_bf16 v[36:39], v[156:159], v[198:201], v[36:39]
	v_mfma_f32_16x16x32_bf16 v[32:35], v[182:185], v[198:201], v[32:35]
	v_mfma_f32_16x16x32_bf16 v[20:23], v[156:159], v[206:209], v[20:23]
	v_mfma_f32_16x16x32_bf16 v[16:19], v[182:185], v[206:209], v[16:19]
	v_mfma_f32_16x16x32_bf16 v[4:7], v[156:159], v[214:217], v[4:7]
	v_mfma_f32_16x16x32_bf16 v[0:3], v[182:185], v[214:217], v[0:3]
	s_barrier
	s_add_i32 s91, s91, 2
	s_add_u32 s89, s89, 0x100
	s_addc_u32 s90, s90, 0
	s_cmpk_gt_u32 s91, 0x55
	s_mov_b64 s[20:21], s[22:23]
	s_cbranch_scc0 .LBB0_243
	s_and_b64 vcc, exec, s[10:11]
	s_cbranch_vccz .LBB0_246
	s_barrier

; #define PG8_STAGE(bufoff, gbase, voff) do { _Pragma("unroll") for (int _i = 0; _i < 2; ++_i) \
;         __builtin_amdgcn_global_load_lds((const unsigned*)((const char*)(gbase) + (voff)[_i]), (LAS unsigned*)(lds + (bufoff) + ldsw + _i * 8192), 16, 0, 0); } while (0)
; #define PG8_LDA(dst, b, h) do { _Pragma("unroll") for (int m = 0; m < 4; ++m) _Pragma("unroll") for (int k = 0; k < 2; ++k) dst[m][k] = *(const LAS bf16x8*)(lds + PG8_SA(b, h) + aoff + m * 2048 + k * 1024); } while (0)
; #define PG8_LDB(dst, b, h) do { _Pragma("unroll") for (int n = 0; n < 2; ++n) _Pragma("unroll") for (int k = 0; k < 2; ++k) dst[n][k] = *(const LAS bf16x8*)(lds + PG8_SB(b, h) + boff + n * 2048 + k * 1024); } while (0)
; #define PG8_MMA(ai, bj, At, Bt) do { __builtin_amdgcn_s_setprio(1); _Pragma("unroll") for (int m = 0; m < 4; ++m) _Pragma("unroll") for (int n = 0; n < 2; ++n) _Pragma("unroll") for (int k = 0; k < 2; ++k) \
;         acc[ai][bj][m][n] = __builtin_amdgcn_mfma_f32_16x16x32_bf16(Bt[n][k], At[m][k], acc[ai][bj][m][n], 0, 0, 0); __builtin_amdgcn_s_setprio(0); } while (0)
; #define PG8_WAIT_V(n) asm volatile("s_waitcnt vmcnt(" #n ")" ::: "memory")
; #define PG8_WAIT_L(n) asm volatile("s_waitcnt lgkmcnt(" #n ")" ::: "memory")
; #define PG8_BAR __builtin_amdgcn_s_barrier()
; #define PG8_SCHED __builtin_amdgcn_sched_barrier(0)
; template <class Sched, class Epi, bool ALIGN_EPI, bool SP2>
; __device__ __forceinline__ void gemm_phase(LAS unsigned char* lds, const int K, const int lda, const int ldb, const Sched& S, const Epi& E) {
;     ...
;             const bool last = (t == nt - 2);
;             const char* a1 = cA + (size_t)(t + 1) * kstep;
;             const char* a2 = last ? nA : cA + (size_t)(t + 2) * kstep; const char* b2 = last ? nB : cB + (size_t)(t + 2) * kstep;
;             const char* a3 = a2 + kstep; const char* b3 = b2 + kstep;
;             if constexpr (SP2) {
;             PG8_LDB(B0, 0, 0); PG8_LDB(B1, 0, 1); PG8_SCHED; PG8_LDA(At, 0, 0); PG8_STAGE(PG8_SA(1, 1), a1 + hstepA, voffA);
;             PG8_WAIT_V(8); PG8_WAIT_L(0); PG8_BAR; PG8_MMA(0, 0, At, B0); PG8_MMA(0, 1, At, B1); PG8_BAR; PG8_SCHED;
;             PG8_LDA(At, 0, 1); PG8_STAGE(PG8_SB(0, 0), b2, voffB); PG8_STAGE(PG8_SB(0, 1), b2 + hstepB, voffB); PG8_STAGE(PG8_SA(0, 0), a2, voffA);
.Lprio_skip_353:
.LBB0_353:
	s_waitcnt lgkmcnt(0)
	ds_read_b128 v[32:35], v211
	ds_read_b128 v[36:39], v211 offset:1024
	ds_read_b128 v[48:51], v211 offset:2048
	ds_read_b128 v[52:55], v211 offset:3072
	ds_read_b128 v[56:59], v212
	ds_read_b128 v[60:63], v212 offset:1024
	ds_read_b128 v[64:67], v212 offset:2048
	ds_read_b128 v[68:71], v212 offset:3072
	s_add_u32 s8, s26, 0xfff80080
	s_addc_u32 s9, s27, -1
	s_cmp_eq_u32 s7, 28
	s_cselect_b32 s37, s1, s9
	s_cselect_b32 s36, s4, s8
	s_cselect_b32 s29, s21, s6
	s_cselect_b32 s28, vcc_lo, vcc_hi
	v_lshl_add_u64 v[208:209], s[26:27], 0, v[192:193]
	s_add_i32 m0, s89, 0xc000
	ds_read_b128 v[76:79], v213
	ds_read_b128 v[80:83], v213 offset:1024
	ds_read_b128 v[88:91], v213 offset:2048
	ds_read_b128 v[92:95], v213 offset:3072
	ds_read_b128 v[196:199], v213 offset:4096
	ds_read_b128 v[200:203], v213 offset:5120
	ds_read_b128 v[204:207], v213 offset:6144
	ds_read_b128 v[216:219], v213 offset:7168
	global_load_lds_dwordx4 v[208:209], off
	v_lshl_add_u64 v[208:209], s[26:27], 0, v[194:195]
	s_add_i32 m0, s89, 0xe000
	s_nop 0
	global_load_lds_dwordx4 v[208:209], off
	s_waitcnt vmcnt(8)
	s_waitcnt lgkmcnt(0)
	s_barrier
	s_waitcnt lgkmcnt(0)
	v_mfma_f32_16x16x32_bf16 v[172:175], v[32:35], v[76:79], v[172:175]
	v_mfma_f32_16x16x32_bf16 v[168:171], v[48:51], v[76:79], v[168:171]
	v_mfma_f32_16x16x32_bf16 v[156:159], v[32:35], v[88:91], v[156:159]
	v_mfma_f32_16x16x32_bf16 v[152:155], v[48:51], v[88:91], v[152:155]
	v_mfma_f32_16x16x32_bf16 v[140:143], v[32:35], v[196:199], v[140:143]
	v_mfma_f32_16x16x32_bf16 v[136:139], v[48:51], v[196:199], v[136:139]
	v_mfma_f32_16x16x32_bf16 v[124:127], v[32:35], v[204:207], v[124:127]
	v_mfma_f32_16x16x32_bf16 v[120:123], v[48:51], v[204:207], v[120:123]
	v_mfma_f32_16x16x32_bf16 v[172:175], v[36:39], v[80:83], v[172:175]
	v_mfma_f32_16x16x32_bf16 v[168:171], v[52:55], v[80:83], v[168:171]
	v_mfma_f32_16x16x32_bf16 v[156:159], v[36:39], v[92:95], v[156:159]
	v_mfma_f32_16x16x32_bf16 v[152:155], v[52:55], v[92:95], v[152:155]
	v_mfma_f32_16x16x32_bf16 v[140:143], v[36:39], v[200:203], v[140:143]
	v_mfma_f32_16x16x32_bf16 v[136:139], v[52:55], v[200:203], v[136:139]
	v_mfma_f32_16x16x32_bf16 v[124:127], v[36:39], v[216:219], v[124:127]
	v_mfma_f32_16x16x32_bf16 v[120:123], v[52:55], v[216:219], v[120:123]
	v_mfma_f32_16x16x32_bf16 v[164:167], v[56:59], v[76:79], v[164:167]
	v_mfma_f32_16x16x32_bf16 v[76:79], v[64:67], v[76:79], v[160:163]
	v_mfma_f32_16x16x32_bf16 v[164:167], v[60:63], v[80:83], v[164:167]
	v_mfma_f32_16x16x32_bf16 v[76:79], v[68:71], v[80:83], v[76:79]
	v_mfma_f32_16x16x32_bf16 v[80:83], v[56:59], v[88:91], v[148:151]
	v_mfma_f32_16x16x32_bf16 v[88:91], v[64:67], v[88:91], v[144:147]
	v_mfma_f32_16x16x32_bf16 v[128:131], v[64:67], v[196:199], v[128:131]
	v_mfma_f32_16x16x32_bf16 v[116:119], v[56:59], v[204:207], v[116:119]
	v_mfma_f32_16x16x32_bf16 v[112:115], v[64:67], v[204:207], v[112:115]
	v_mfma_f32_16x16x32_bf16 v[80:83], v[60:63], v[92:95], v[80:83]
	v_mfma_f32_16x16x32_bf16 v[88:91], v[68:71], v[92:95], v[88:91]
	v_mfma_f32_16x16x32_bf16 v[92:95], v[56:59], v[196:199], v[132:135]
	v_mfma_f32_16x16x32_bf16 v[128:131], v[68:71], v[200:203], v[128:131]
	v_mfma_f32_16x16x32_bf16 v[116:119], v[60:63], v[216:219], v[116:119]
	v_mfma_f32_16x16x32_bf16 v[112:115], v[68:71], v[216:219], v[112:115]
	v_mfma_f32_16x16x32_bf16 v[92:95], v[60:63], v[200:203], v[92:95]
	s_barrier
	s_add_i32 s8, s85, s88
	v_lshl_add_u64 v[208:209], s[28:29], 0, v[186:187]
	s_mov_b32 m0, s8
	ds_read_b128 v[132:135], v213 offset:16384
	ds_read_b128 v[144:147], v213 offset:17408
	ds_read_b128 v[148:151], v213 offset:18432
	ds_read_b128 v[160:163], v213 offset:19456
	ds_read_b128 v[196:199], v213 offset:20480
	ds_read_b128 v[200:203], v213 offset:21504
	ds_read_b128 v[204:207], v213 offset:22528
	ds_read_b128 v[216:219], v213 offset:23552
	global_load_lds_dwordx4 v[208:209], off
	s_add_i32 m0, s8, 0x2000
	s_add_u32 s8, s28, 0x80000
	v_lshl_add_u64 v[228:229], s[28:29], 0, v[190:191]
	s_addc_u32 s9, s29, 0
	s_add_i32 s51, s50, s88
	global_load_lds_dwordx4 v[228:229], off
	v_lshl_add_u64 v[220:221], s[8:9], 0, v[186:187]
	s_mov_b32 m0, s51
	v_lshl_add_u64 v[230:231], s[36:37], 0, v[184:185]
	global_load_lds_dwordx4 v[220:221], off
	v_lshl_add_u64 v[220:221], s[8:9], 0, v[190:191]
	s_add_i32 m0, s51, 0x2000
	v_lshl_add_u64 v[232:233], s[36:37], 0, v[188:189]
	global_load_lds_dwordx4 v[220:221], off
	s_mov_b32 m0, s89
	s_nop 0
	global_load_lds_dwordx4 v[230:231], off
	s_mov_b32 m0, s90
	s_nop 0
	global_load_lds_dwordx4 v[232:233], off
	s_waitcnt vmcnt(8)
	s_waitcnt lgkmcnt(0)
	s_barrier
; #define PG8_STAGE(bufoff, gbase, voff) do { _Pragma("unroll") for (int _i = 0; _i < 2; ++_i) \
;         __builtin_amdgcn_global_load_lds((const unsigned*)((const char*)(gbase) + (voff)[_i]), (LAS unsigned*)(lds + (bufoff) + ldsw + _i * 8192), 16, 0, 0); } while (0)
; #define PG8_LDA(dst, b, h) do { _Pragma("unroll") for (int m = 0; m < 4; ++m) _Pragma("unroll") for (int k = 0; k < 2; ++k) dst[m][k] = *(const LAS bf16x8*)(lds + PG8_SA(b, h) + aoff + m * 2048 + k * 1024); } while (0)
; #define PG8_LDB(dst, b, h) do { _Pragma("unroll") for (int n = 0; n < 2; ++n) _Pragma("unroll") for (int k = 0; k < 2; ++k) dst[n][k] = *(const LAS bf16x8*)(lds + PG8_SB(b, h) + boff + n * 2048 + k * 1024); } while (0)
; #define PG8_MMA(ai, bj, At, Bt) do { __builtin_amdgcn_s_setprio(1); _Pragma("unroll") for (int m = 0; m < 4; ++m) _Pragma("unroll") for (int n = 0; n < 2; ++n) _Pragma("unroll") for (int k = 0; k < 2; ++k) \
;         acc[ai][bj][m][n] = __builtin_amdgcn_mfma_f32_16x16x32_bf16(Bt[n][k], At[m][k], acc[ai][bj][m][n], 0, 0, 0); __builtin_amdgcn_s_setprio(0); } while (0)
; #define PG8_WAIT_V(n) asm volatile("s_waitcnt vmcnt(" #n ")" ::: "memory")
; #define PG8_WAIT_L(n) asm volatile("s_waitcnt lgkmcnt(" #n ")" ::: "memory")
; #define PG8_BAR __builtin_amdgcn_s_barrier()
; #define PG8_SCHED __builtin_amdgcn_sched_barrier(0)
; template <class Sched, class Epi, bool ALIGN_EPI, bool SP2>
; __device__ __forceinline__ void gemm_phase(LAS unsigned char* lds, const int K, const int lda, const int ldb, const Sched& S, const Epi& E) {
;     ...
;             PG8_WAIT_V(8); PG8_WAIT_L(0); PG8_BAR; PG8_MMA(1, 0, At, B0); PG8_MMA(1, 1, At, B1); PG8_BAR; PG8_SCHED;
;             PG8_LDB(B0, 1, 0); PG8_LDB(B1, 1, 1); PG8_SCHED; PG8_LDA(At, 1, 0); PG8_STAGE(PG8_SA(0, 1), a2 + hstepA, voffA);
;             PG8_WAIT_V(8); PG8_WAIT_L(0); PG8_BAR; PG8_MMA(0, 0, At, B0); PG8_MMA(0, 1, At, B1); PG8_BAR; PG8_SCHED;
	s_waitcnt lgkmcnt(0)
	v_mfma_f32_16x16x32_bf16 v[108:111], v[32:35], v[132:135], v[108:111]
	v_mfma_f32_16x16x32_bf16 v[104:107], v[48:51], v[132:135], v[104:107]
	v_mfma_f32_16x16x32_bf16 v[84:87], v[32:35], v[148:151], v[84:87]
	v_mfma_f32_16x16x32_bf16 v[72:75], v[48:51], v[148:151], v[72:75]
	v_mfma_f32_16x16x32_bf16 v[28:31], v[32:35], v[196:199], v[28:31]
	v_mfma_f32_16x16x32_bf16 v[24:27], v[48:51], v[196:199], v[24:27]
	v_mfma_f32_16x16x32_bf16 v[12:15], v[32:35], v[204:207], v[12:15]
	v_mfma_f32_16x16x32_bf16 v[8:11], v[48:51], v[204:207], v[8:11]
	v_mfma_f32_16x16x32_bf16 v[108:111], v[36:39], v[144:147], v[108:111]
	v_mfma_f32_16x16x32_bf16 v[104:107], v[52:55], v[144:147], v[104:107]
	v_mfma_f32_16x16x32_bf16 v[84:87], v[36:39], v[160:163], v[84:87]
	v_mfma_f32_16x16x32_bf16 v[72:75], v[52:55], v[160:163], v[72:75]
	v_mfma_f32_16x16x32_bf16 v[28:31], v[36:39], v[200:203], v[28:31]
	v_mfma_f32_16x16x32_bf16 v[24:27], v[52:55], v[200:203], v[24:27]
	v_mfma_f32_16x16x32_bf16 v[12:15], v[36:39], v[216:219], v[12:15]
	v_mfma_f32_16x16x32_bf16 v[8:11], v[52:55], v[216:219], v[8:11]
	v_mfma_f32_16x16x32_bf16 v[44:47], v[56:59], v[148:151], v[44:47]
	v_mfma_f32_16x16x32_bf16 v[40:43], v[64:67], v[148:151], v[40:43]
	v_mfma_f32_16x16x32_bf16 v[20:23], v[56:59], v[196:199], v[20:23]
	v_mfma_f32_16x16x32_bf16 v[16:19], v[64:67], v[196:199], v[16:19]
	v_mfma_f32_16x16x32_bf16 v[4:7], v[56:59], v[204:207], v[4:7]
	v_mfma_f32_16x16x32_bf16 v[0:3], v[64:67], v[204:207], v[0:3]
	v_mfma_f32_16x16x32_bf16 v[32:35], v[56:59], v[132:135], v[100:103]
	v_mfma_f32_16x16x32_bf16 v[36:39], v[64:67], v[132:135], v[96:99]
	v_mfma_f32_16x16x32_bf16 v[44:47], v[60:63], v[160:163], v[44:47]
	v_mfma_f32_16x16x32_bf16 v[40:43], v[68:71], v[160:163], v[40:43]
	v_mfma_f32_16x16x32_bf16 v[20:23], v[60:63], v[200:203], v[20:23]
	v_mfma_f32_16x16x32_bf16 v[16:19], v[68:71], v[200:203], v[16:19]
	v_mfma_f32_16x16x32_bf16 v[4:7], v[60:63], v[216:219], v[4:7]
	v_mfma_f32_16x16x32_bf16 v[0:3], v[68:71], v[216:219], v[0:3]
	v_mfma_f32_16x16x32_bf16 v[32:35], v[60:63], v[144:147], v[32:35]
	v_mfma_f32_16x16x32_bf16 v[36:39], v[68:71], v[144:147], v[36:39]
	s_barrier
	s_add_i32 s51, 0, 0x18000
	s_add_i32 s17, 0, 0x1c000
	v_add_u32_e32 v60, s51, v183
	v_add_u32_e32 v96, s17, v183
	ds_read_b128 v[48:51], v60
	ds_read_b128 v[52:55], v60 offset:1024
	ds_read_b128 v[56:59], v60 offset:2048
	ds_read_b128 v[60:63], v60 offset:3072
	ds_read_b128 v[64:67], v96
	ds_read_b128 v[68:71], v96 offset:1024
	ds_read_b128 v[196:199], v96 offset:2048
	ds_read_b128 v[200:203], v96 offset:3072
	s_add_u32 s8, s36, 0x80000
	s_addc_u32 s9, s37, 0
	s_mov_b32 m0, s91
	v_lshl_add_u64 v[148:149], s[8:9], 0, v[184:185]
	ds_read_b128 v[96:99], v213 offset:32768
	ds_read_b128 v[100:103], v213 offset:33792
	ds_read_b128 v[132:135], v213 offset:34816
	ds_read_b128 v[144:147], v213 offset:35840
	ds_read_b128 v[204:207], v213 offset:36864
	ds_read_b128 v[216:219], v213 offset:37888
	ds_read_b128 v[220:223], v213 offset:38912
	ds_read_b128 v[224:227], v213 offset:39936
	global_load_lds_dwordx4 v[148:149], off
	v_lshl_add_u64 v[148:149], s[8:9], 0, v[188:189]
	s_mov_b32 m0, s96
	s_nop 0
	global_load_lds_dwordx4 v[148:149], off
	s_waitcnt vmcnt(8)
	s_waitcnt lgkmcnt(0)
	s_barrier
	s_waitcnt lgkmcnt(0)
	v_mfma_f32_16x16x32_bf16 v[148:151], v[48:51], v[96:99], v[172:175]
	v_mfma_f32_16x16x32_bf16 v[172:175], v[52:55], v[100:103], v[148:151]
	v_mfma_f32_16x16x32_bf16 v[148:151], v[56:59], v[96:99], v[168:171]
	v_mfma_f32_16x16x32_bf16 v[168:171], v[60:63], v[100:103], v[148:151]
	v_mfma_f32_16x16x32_bf16 v[148:151], v[48:51], v[132:135], v[156:159]
	v_mfma_f32_16x16x32_bf16 v[156:159], v[52:55], v[144:147], v[148:151]
	v_mfma_f32_16x16x32_bf16 v[148:151], v[56:59], v[132:135], v[152:155]
	v_mfma_f32_16x16x32_bf16 v[140:143], v[48:51], v[204:207], v[140:143]
	v_mfma_f32_16x16x32_bf16 v[136:139], v[56:59], v[204:207], v[136:139]
	v_mfma_f32_16x16x32_bf16 v[124:127], v[48:51], v[220:223], v[124:127]
	v_mfma_f32_16x16x32_bf16 v[120:123], v[56:59], v[220:223], v[120:123]
	v_mfma_f32_16x16x32_bf16 v[152:155], v[60:63], v[144:147], v[148:151]
	v_mfma_f32_16x16x32_bf16 v[140:143], v[52:55], v[216:219], v[140:143]
	v_mfma_f32_16x16x32_bf16 v[136:139], v[60:63], v[216:219], v[136:139]
	v_mfma_f32_16x16x32_bf16 v[124:127], v[52:55], v[224:227], v[124:127]
	v_mfma_f32_16x16x32_bf16 v[120:123], v[60:63], v[224:227], v[120:123]
	v_mfma_f32_16x16x32_bf16 v[76:79], v[196:199], v[96:99], v[76:79]
	v_mfma_f32_16x16x32_bf16 v[148:151], v[64:67], v[96:99], v[164:167]
	v_mfma_f32_16x16x32_bf16 v[160:163], v[200:203], v[100:103], v[76:79]
	v_mfma_f32_16x16x32_bf16 v[76:79], v[64:67], v[132:135], v[80:83]
	v_mfma_f32_16x16x32_bf16 v[164:167], v[68:71], v[100:103], v[148:151]
	v_mfma_f32_16x16x32_bf16 v[148:151], v[68:71], v[144:147], v[76:79]
	v_mfma_f32_16x16x32_bf16 v[76:79], v[196:199], v[132:135], v[88:91]
	v_mfma_f32_16x16x32_bf16 v[144:147], v[200:203], v[144:147], v[76:79]
	v_mfma_f32_16x16x32_bf16 v[76:79], v[64:67], v[204:207], v[92:95]
	v_mfma_f32_16x16x32_bf16 v[132:135], v[68:71], v[216:219], v[76:79]
	v_mfma_f32_16x16x32_bf16 v[76:79], v[196:199], v[204:207], v[128:131]
	v_mfma_f32_16x16x32_bf16 v[128:131], v[200:203], v[216:219], v[76:79]
	v_mfma_f32_16x16x32_bf16 v[76:79], v[64:67], v[220:223], v[116:119]
	v_mfma_f32_16x16x32_bf16 v[116:119], v[68:71], v[224:227], v[76:79]
	v_mfma_f32_16x16x32_bf16 v[76:79], v[196:199], v[220:223], v[112:115]
	v_mfma_f32_16x16x32_bf16 v[112:115], v[200:203], v[224:227], v[76:79]
	s_barrier
; #define PG8_STAGE(bufoff, gbase, voff) do { _Pragma("unroll") for (int _i = 0; _i < 2; ++_i) \
;         __builtin_amdgcn_global_load_lds((const unsigned*)((const char*)(gbase) + (voff)[_i]), (LAS unsigned*)(lds + (bufoff) + ldsw + _i * 8192), 16, 0, 0); } while (0)
; #define PG8_LDA(dst, b, h) do { _Pragma("unroll") for (int m = 0; m < 4; ++m) _Pragma("unroll") for (int k = 0; k < 2; ++k) dst[m][k] = *(const LAS bf16x8*)(lds + PG8_SA(b, h) + aoff + m * 2048 + k * 1024); } while (0)
; #define PG8_MMA(ai, bj, At, Bt) do { __builtin_amdgcn_s_setprio(1); _Pragma("unroll") for (int m = 0; m < 4; ++m) _Pragma("unroll") for (int n = 0; n < 2; ++n) _Pragma("unroll") for (int k = 0; k < 2; ++k) \
;         acc[ai][bj][m][n] = __builtin_amdgcn_mfma_f32_16x16x32_bf16(Bt[n][k], At[m][k], acc[ai][bj][m][n], 0, 0, 0); __builtin_amdgcn_s_setprio(0); } while (0)
; #define PG8_WAIT_V(n) asm volatile("s_waitcnt vmcnt(" #n ")" ::: "memory")
; #define PG8_WAIT_L(n) asm volatile("s_waitcnt lgkmcnt(" #n ")" ::: "memory")
; #define PG8_BAR __builtin_amdgcn_s_barrier()
; #define PG8_SCHED __builtin_amdgcn_sched_barrier(0)
; template <class Sched, class Epi, bool ALIGN_EPI, bool SP2>
; __device__ __forceinline__ void gemm_phase(LAS unsigned char* lds, const int K, const int lda, const int ldb, const Sched& S, const Epi& E) {
;     ...
;             PG8_LDA(At, 1, 1); PG8_STAGE(PG8_SB(1, 0), b3, voffB); PG8_STAGE(PG8_SB(1, 1), b3 + hstepB, voffB); PG8_STAGE(PG8_SA(1, 0), a3, voffA);
;             PG8_WAIT_V(8); PG8_WAIT_L(0); PG8_BAR; PG8_MMA(1, 0, At, B0); PG8_MMA(1, 1, At, B1); PG8_BAR; PG8_SCHED;
;     ...
;         }
;         if constexpr (ALIGN_EPI) { if (wr == 0) PG8_BAR; }
	s_add_i32 s8, s51, s88
	v_lshl_add_u64 v[96:97], v[208:209], 0, s[10:11]
	s_mov_b32 m0, s8
	s_nop 1
	ds_read_b128 v[76:79], v213 offset:49152
	ds_read_b128 v[80:83], v213 offset:50176
	ds_read_b128 v[88:91], v213 offset:51200
	ds_read_b128 v[92:95], v213 offset:52224
	ds_read_b128 v[204:207], v213 offset:53248
	ds_read_b128 v[216:219], v213 offset:54272
	ds_read_b128 v[220:223], v213 offset:55296
	ds_read_b128 v[224:227], v213 offset:56320
	global_load_lds_dwordx4 v[96:97], off
	s_add_i32 m0, s8, 0x2000
	s_add_u32 s8, s28, 0x80080
	v_lshl_add_u64 v[96:97], v[228:229], 0, s[10:11]
	s_addc_u32 s9, s29, 0
	s_add_i32 s17, s17, s88
	global_load_lds_dwordx4 v[96:97], off
	v_lshl_add_u64 v[96:97], s[8:9], 0, v[186:187]
	s_mov_b32 m0, s17
	s_nop 0
	global_load_lds_dwordx4 v[96:97], off
	v_lshl_add_u64 v[96:97], s[8:9], 0, v[190:191]
	s_add_i32 m0, s17, 0x2000
	s_nop 0
	global_load_lds_dwordx4 v[96:97], off
	v_lshl_add_u64 v[96:97], v[230:231], 0, s[10:11]
	s_mov_b32 m0, s97
	s_nop 0
	global_load_lds_dwordx4 v[96:97], off
	v_lshl_add_u64 v[96:97], v[232:233], 0, s[10:11]
	s_mov_b32 m0, s84
	s_nop 0
	global_load_lds_dwordx4 v[96:97], off
	s_waitcnt vmcnt(8)
	s_waitcnt lgkmcnt(0)
	s_barrier
	s_waitcnt lgkmcnt(0)
	v_mfma_f32_16x16x32_bf16 v[96:99], v[48:51], v[76:79], v[108:111]
	v_mfma_f32_16x16x32_bf16 v[108:111], v[52:55], v[80:83], v[96:99]
	v_mfma_f32_16x16x32_bf16 v[96:99], v[56:59], v[76:79], v[104:107]
	v_mfma_f32_16x16x32_bf16 v[84:87], v[48:51], v[88:91], v[84:87]
	v_mfma_f32_16x16x32_bf16 v[72:75], v[56:59], v[88:91], v[72:75]
	v_mfma_f32_16x16x32_bf16 v[28:31], v[48:51], v[204:207], v[28:31]
	v_mfma_f32_16x16x32_bf16 v[24:27], v[56:59], v[204:207], v[24:27]
	v_mfma_f32_16x16x32_bf16 v[12:15], v[48:51], v[220:223], v[12:15]
	v_mfma_f32_16x16x32_bf16 v[8:11], v[56:59], v[220:223], v[8:11]
	v_mfma_f32_16x16x32_bf16 v[104:107], v[60:63], v[80:83], v[96:99]
	v_mfma_f32_16x16x32_bf16 v[84:87], v[52:55], v[92:95], v[84:87]
	v_mfma_f32_16x16x32_bf16 v[72:75], v[60:63], v[92:95], v[72:75]
	v_mfma_f32_16x16x32_bf16 v[28:31], v[52:55], v[216:219], v[28:31]
	v_mfma_f32_16x16x32_bf16 v[24:27], v[60:63], v[216:219], v[24:27]
	v_mfma_f32_16x16x32_bf16 v[12:15], v[52:55], v[224:227], v[12:15]
	v_mfma_f32_16x16x32_bf16 v[8:11], v[60:63], v[224:227], v[8:11]
	v_mfma_f32_16x16x32_bf16 v[32:35], v[64:67], v[76:79], v[32:35]
	v_mfma_f32_16x16x32_bf16 v[100:103], v[68:71], v[80:83], v[32:35]
	v_mfma_f32_16x16x32_bf16 v[32:35], v[196:199], v[76:79], v[36:39]
	v_mfma_f32_16x16x32_bf16 v[96:99], v[200:203], v[80:83], v[32:35]
	v_mfma_f32_16x16x32_bf16 v[32:35], v[64:67], v[88:91], v[44:47]
	v_mfma_f32_16x16x32_bf16 v[44:47], v[68:71], v[92:95], v[32:35]
	v_mfma_f32_16x16x32_bf16 v[32:35], v[196:199], v[88:91], v[40:43]
	v_mfma_f32_16x16x32_bf16 v[20:23], v[64:67], v[204:207], v[20:23]
	v_mfma_f32_16x16x32_bf16 v[16:19], v[196:199], v[204:207], v[16:19]
	v_mfma_f32_16x16x32_bf16 v[4:7], v[64:67], v[220:223], v[4:7]
	v_mfma_f32_16x16x32_bf16 v[0:3], v[196:199], v[220:223], v[0:3]
	v_mfma_f32_16x16x32_bf16 v[40:43], v[200:203], v[92:95], v[32:35]
	v_mfma_f32_16x16x32_bf16 v[20:23], v[68:71], v[216:219], v[20:23]
	v_mfma_f32_16x16x32_bf16 v[16:19], v[200:203], v[216:219], v[16:19]
	v_mfma_f32_16x16x32_bf16 v[4:7], v[68:71], v[224:227], v[4:7]
	v_mfma_f32_16x16x32_bf16 v[0:3], v[200:203], v[224:227], v[0:3]
	s_barrier
	s_add_i32 s7, s7, 2
	s_add_u32 s26, s26, 0x100
	s_addc_u32 s27, s27, 0
	s_add_u32 vcc_hi, vcc_hi, 0x100
	s_addc_u32 s6, s6, 0
	s_cmp_gt_u32 s7, 29
	s_cbranch_scc0 .LBB0_353
	s_and_b64 vcc, exec, s[12:13]
	s_cbranch_vccz .LBB0_356
	s_barrier

; #define PG8_STAGE(bufoff, gbase, voff) do { _Pragma("unroll") for (int _i = 0; _i < 2; ++_i) \
;         __builtin_amdgcn_global_load_lds((const unsigned*)((const char*)(gbase) + (voff)[_i]), (LAS unsigned*)(lds + (bufoff) + ldsw + _i * 8192), 16, 0, 0); } while (0)
; #define PG8_LDA(dst, b, h) do { _Pragma("unroll") for (int m = 0; m < 4; ++m) _Pragma("unroll") for (int k = 0; k < 2; ++k) dst[m][k] = *(const LAS bf16x8*)(lds + PG8_SA(b, h) + aoff + m * 2048 + k * 1024); } while (0)
; #define PG8_LDB(dst, b, h) do { _Pragma("unroll") for (int n = 0; n < 2; ++n) _Pragma("unroll") for (int k = 0; k < 2; ++k) dst[n][k] = *(const LAS bf16x8*)(lds + PG8_SB(b, h) + boff + n * 2048 + k * 1024); } while (0)
; #define PG8_MMA(ai, bj, At, Bt) do { __builtin_amdgcn_s_setprio(1); _Pragma("unroll") for (int m = 0; m < 4; ++m) _Pragma("unroll") for (int n = 0; n < 2; ++n) _Pragma("unroll") for (int k = 0; k < 2; ++k) \
;         acc[ai][bj][m][n] = __builtin_amdgcn_mfma_f32_16x16x32_bf16(Bt[n][k], At[m][k], acc[ai][bj][m][n], 0, 0, 0); __builtin_amdgcn_s_setprio(0); } while (0)
; #define PG8_WAIT_V(n) asm volatile("s_waitcnt vmcnt(" #n ")" ::: "memory")
; #define PG8_WAIT_L(n) asm volatile("s_waitcnt lgkmcnt(" #n ")" ::: "memory")
; #define PG8_BAR __builtin_amdgcn_s_barrier()
; #define PG8_SCHED __builtin_amdgcn_sched_barrier(0)
; template <class Sched, class Epi, bool ALIGN_EPI, bool SP2>
; __device__ __forceinline__ void gemm_phase(LAS unsigned char* lds, const int K, const int lda, const int ldb, const Sched& S, const Epi& E) {
;     ...
;             const bool last = (t == nt - 2);
;             const char* a1 = cA + (size_t)(t + 1) * kstep;
;             const char* a2 = last ? nA : cA + (size_t)(t + 2) * kstep; const char* b2 = last ? nB : cB + (size_t)(t + 2) * kstep;
;             const char* a3 = a2 + kstep; const char* b3 = b2 + kstep;
;             if constexpr (SP2) {
;             PG8_LDB(B0, 0, 0); PG8_LDB(B1, 0, 1); PG8_SCHED; PG8_LDA(At, 0, 0); PG8_STAGE(PG8_SA(1, 1), a1 + hstepA, voffA);
;             PG8_WAIT_V(8); PG8_WAIT_L(0); PG8_BAR; PG8_MMA(0, 0, At, B0); PG8_MMA(0, 1, At, B1); PG8_BAR; PG8_SCHED;
;             PG8_LDA(At, 0, 1); PG8_STAGE(PG8_SB(0, 0), b2, voffB); PG8_STAGE(PG8_SB(0, 1), b2 + hstepB, voffB); PG8_STAGE(PG8_SA(0, 0), a2, voffA);
.Lprio_skip_821:
.LBB0_821:
	v_add_u32_e32 v140, s44, v181
	v_add_u32_e32 v170, s45, v181
	ds_read_b128 v[128:131], v140
	ds_read_b128 v[132:135], v140 offset:1024
	ds_read_b128 v[136:139], v140 offset:2048
	ds_read_b128 v[140:143], v140 offset:3072
	ds_read_b128 v[144:147], v170
	ds_read_b128 v[148:151], v170 offset:1024
	ds_read_b128 v[166:169], v170 offset:2048
	ds_read_b128 v[170:173], v170 offset:3072
	s_add_u32 s20, s4, 0x100
	s_addc_u32 s21, s5, 0
	s_cmp_eq_u32 s61, 12
	s_cselect_b32 s25, s15, s21
	s_cselect_b32 s24, s14, s20
	s_cselect_b32 s23, s17, s60
	s_cselect_b32 s22, s16, s53
	v_lshl_add_u64 v[174:175], s[4:5], 0, v[162:163]
	s_add_i32 m0, s29, 0xc000
	ds_read_b128 v[184:187], v183
	ds_read_b128 v[188:191], v183 offset:1024
	ds_read_b128 v[192:195], v183 offset:2048
	ds_read_b128 v[196:199], v183 offset:3072
	ds_read_b128 v[200:203], v183 offset:4096
	ds_read_b128 v[204:207], v183 offset:5120
	ds_read_b128 v[208:211], v183 offset:6144
	ds_read_b128 v[212:215], v183 offset:7168
	global_load_lds_dwordx4 v[174:175], off
	v_lshl_add_u64 v[174:175], s[4:5], 0, v[164:165]
	s_add_i32 m0, s29, 0xe000
	s_nop 0
	global_load_lds_dwordx4 v[174:175], off
	s_waitcnt vmcnt(8)
	s_waitcnt lgkmcnt(0)
	s_barrier
	s_waitcnt lgkmcnt(0)
	v_mfma_f32_16x16x32_bf16 v[124:127], v[128:131], v[184:187], v[124:127]
	v_mfma_f32_16x16x32_bf16 v[120:123], v[136:139], v[184:187], v[120:123]
	v_mfma_f32_16x16x32_bf16 v[116:119], v[128:131], v[192:195], v[116:119]
	v_mfma_f32_16x16x32_bf16 v[112:115], v[136:139], v[192:195], v[112:115]
	v_mfma_f32_16x16x32_bf16 v[108:111], v[128:131], v[200:203], v[108:111]
	v_mfma_f32_16x16x32_bf16 v[104:107], v[136:139], v[200:203], v[104:107]
	v_mfma_f32_16x16x32_bf16 v[100:103], v[128:131], v[208:211], v[100:103]
	v_mfma_f32_16x16x32_bf16 v[96:99], v[136:139], v[208:211], v[96:99]
	v_mfma_f32_16x16x32_bf16 v[124:127], v[132:135], v[188:191], v[124:127]
	v_mfma_f32_16x16x32_bf16 v[120:123], v[140:143], v[188:191], v[120:123]
	v_mfma_f32_16x16x32_bf16 v[116:119], v[132:135], v[196:199], v[116:119]
	v_mfma_f32_16x16x32_bf16 v[112:115], v[140:143], v[196:199], v[112:115]
	v_mfma_f32_16x16x32_bf16 v[108:111], v[132:135], v[204:207], v[108:111]
	v_mfma_f32_16x16x32_bf16 v[104:107], v[140:143], v[204:207], v[104:107]
	v_mfma_f32_16x16x32_bf16 v[100:103], v[132:135], v[212:215], v[100:103]
	v_mfma_f32_16x16x32_bf16 v[96:99], v[140:143], v[212:215], v[96:99]
	v_mfma_f32_16x16x32_bf16 v[92:95], v[144:147], v[184:187], v[92:95]
	v_mfma_f32_16x16x32_bf16 v[88:91], v[166:169], v[184:187], v[88:91]
	v_mfma_f32_16x16x32_bf16 v[84:87], v[144:147], v[192:195], v[84:87]
	v_mfma_f32_16x16x32_bf16 v[80:83], v[166:169], v[192:195], v[80:83]
	v_mfma_f32_16x16x32_bf16 v[76:79], v[144:147], v[200:203], v[76:79]
	v_mfma_f32_16x16x32_bf16 v[72:75], v[166:169], v[200:203], v[72:75]
	v_mfma_f32_16x16x32_bf16 v[68:71], v[144:147], v[208:211], v[68:71]
	v_mfma_f32_16x16x32_bf16 v[64:67], v[166:169], v[208:211], v[64:67]
	v_mfma_f32_16x16x32_bf16 v[92:95], v[148:151], v[188:191], v[92:95]
	v_mfma_f32_16x16x32_bf16 v[88:91], v[170:173], v[188:191], v[88:91]
	v_mfma_f32_16x16x32_bf16 v[84:87], v[148:151], v[196:199], v[84:87]
	v_mfma_f32_16x16x32_bf16 v[80:83], v[170:173], v[196:199], v[80:83]
	v_mfma_f32_16x16x32_bf16 v[76:79], v[148:151], v[204:207], v[76:79]
	v_mfma_f32_16x16x32_bf16 v[72:75], v[170:173], v[204:207], v[72:75]
	v_mfma_f32_16x16x32_bf16 v[68:71], v[148:151], v[212:215], v[68:71]
	v_mfma_f32_16x16x32_bf16 v[64:67], v[170:173], v[212:215], v[64:67]
	s_barrier
	s_add_i32 s4, s44, s28
	v_lshl_add_u64 v[174:175], s[22:23], 0, v[156:157]
	s_mov_b32 m0, s4
	ds_read_b128 v[184:187], v183 offset:16384
	ds_read_b128 v[188:191], v183 offset:17408
	ds_read_b128 v[192:195], v183 offset:18432
	ds_read_b128 v[196:199], v183 offset:19456
	ds_read_b128 v[200:203], v183 offset:20480
	ds_read_b128 v[204:207], v183 offset:21504
	ds_read_b128 v[208:211], v183 offset:22528
	ds_read_b128 v[212:215], v183 offset:23552
	global_load_lds_dwordx4 v[174:175], off
	s_add_i32 m0, s4, 0x2000
	s_add_u32 s4, s22, 0x40000
	v_lshl_add_u64 v[216:217], s[22:23], 0, v[160:161]
	s_addc_u32 s5, s23, 0
	s_add_i32 s62, s45, s28
	global_load_lds_dwordx4 v[216:217], off
	v_lshl_add_u64 v[218:219], s[4:5], 0, v[156:157]
	s_mov_b32 m0, s62
	v_lshl_add_u64 v[220:221], s[24:25], 0, v[158:159]
	global_load_lds_dwordx4 v[218:219], off
	v_lshl_add_u64 v[218:219], s[4:5], 0, v[160:161]
	s_add_i32 m0, s62, 0x2000
	s_nop 0
	global_load_lds_dwordx4 v[218:219], off
	v_lshl_add_u64 v[218:219], s[24:25], 0, v[154:155]
	s_mov_b32 m0, s29
	s_nop 0
	global_load_lds_dwordx4 v[218:219], off
	s_mov_b32 m0, s33
	s_nop 0
	global_load_lds_dwordx4 v[220:221], off
	s_waitcnt vmcnt(8)
	s_waitcnt lgkmcnt(0)
	s_barrier
; #define PG8_STAGE(bufoff, gbase, voff) do { _Pragma("unroll") for (int _i = 0; _i < 2; ++_i) \
;         __builtin_amdgcn_global_load_lds((const unsigned*)((const char*)(gbase) + (voff)[_i]), (LAS unsigned*)(lds + (bufoff) + ldsw + _i * 8192), 16, 0, 0); } while (0)
; #define PG8_LDA(dst, b, h) do { _Pragma("unroll") for (int m = 0; m < 4; ++m) _Pragma("unroll") for (int k = 0; k < 2; ++k) dst[m][k] = *(const LAS bf16x8*)(lds + PG8_SA(b, h) + aoff + m * 2048 + k * 1024); } while (0)
; #define PG8_LDB(dst, b, h) do { _Pragma("unroll") for (int n = 0; n < 2; ++n) _Pragma("unroll") for (int k = 0; k < 2; ++k) dst[n][k] = *(const LAS bf16x8*)(lds + PG8_SB(b, h) + boff + n * 2048 + k * 1024); } while (0)
; #define PG8_MMA(ai, bj, At, Bt) do { __builtin_amdgcn_s_setprio(1); _Pragma("unroll") for (int m = 0; m < 4; ++m) _Pragma("unroll") for (int n = 0; n < 2; ++n) _Pragma("unroll") for (int k = 0; k < 2; ++k) \
;         acc[ai][bj][m][n] = __builtin_amdgcn_mfma_f32_16x16x32_bf16(Bt[n][k], At[m][k], acc[ai][bj][m][n], 0, 0, 0); __builtin_amdgcn_s_setprio(0); } while (0)
; #define PG8_WAIT_V(n) asm volatile("s_waitcnt vmcnt(" #n ")" ::: "memory")
; #define PG8_WAIT_L(n) asm volatile("s_waitcnt lgkmcnt(" #n ")" ::: "memory")
; #define PG8_BAR __builtin_amdgcn_s_barrier()
; #define PG8_SCHED __builtin_amdgcn_sched_barrier(0)
; template <class Sched, class Epi, bool ALIGN_EPI, bool SP2>
; __device__ __forceinline__ void gemm_phase(LAS unsigned char* lds, const int K, const int lda, const int ldb, const Sched& S, const Epi& E) {
;     ...
;             PG8_WAIT_V(8); PG8_WAIT_L(0); PG8_BAR; PG8_MMA(1, 0, At, B0); PG8_MMA(1, 1, At, B1); PG8_BAR; PG8_SCHED;
;             PG8_LDB(B0, 1, 0); PG8_LDB(B1, 1, 1); PG8_SCHED; PG8_LDA(At, 1, 0); PG8_STAGE(PG8_SA(0, 1), a2 + hstepA, voffA);
;             PG8_WAIT_V(8); PG8_WAIT_L(0); PG8_BAR; PG8_MMA(0, 0, At, B0); PG8_MMA(0, 1, At, B1); PG8_BAR; PG8_SCHED;
	s_waitcnt lgkmcnt(0)
	v_mfma_f32_16x16x32_bf16 v[60:63], v[128:131], v[184:187], v[60:63]
	v_mfma_f32_16x16x32_bf16 v[56:59], v[136:139], v[184:187], v[56:59]
	v_mfma_f32_16x16x32_bf16 v[52:55], v[128:131], v[192:195], v[52:55]
	v_mfma_f32_16x16x32_bf16 v[48:51], v[136:139], v[192:195], v[48:51]
	v_mfma_f32_16x16x32_bf16 v[44:47], v[128:131], v[200:203], v[44:47]
	v_mfma_f32_16x16x32_bf16 v[40:43], v[136:139], v[200:203], v[40:43]
	v_mfma_f32_16x16x32_bf16 v[36:39], v[128:131], v[208:211], v[36:39]
	v_mfma_f32_16x16x32_bf16 v[32:35], v[136:139], v[208:211], v[32:35]
	v_mfma_f32_16x16x32_bf16 v[60:63], v[132:135], v[188:191], v[60:63]
	v_mfma_f32_16x16x32_bf16 v[56:59], v[140:143], v[188:191], v[56:59]
	v_mfma_f32_16x16x32_bf16 v[52:55], v[132:135], v[196:199], v[52:55]
	v_mfma_f32_16x16x32_bf16 v[48:51], v[140:143], v[196:199], v[48:51]
	v_mfma_f32_16x16x32_bf16 v[44:47], v[132:135], v[204:207], v[44:47]
	v_mfma_f32_16x16x32_bf16 v[40:43], v[140:143], v[204:207], v[40:43]
	v_mfma_f32_16x16x32_bf16 v[36:39], v[132:135], v[212:215], v[36:39]
	v_mfma_f32_16x16x32_bf16 v[32:35], v[140:143], v[212:215], v[32:35]
	v_mfma_f32_16x16x32_bf16 v[28:31], v[144:147], v[184:187], v[28:31]
	v_mfma_f32_16x16x32_bf16 v[24:27], v[166:169], v[184:187], v[24:27]
	v_mfma_f32_16x16x32_bf16 v[20:23], v[144:147], v[192:195], v[20:23]
	v_mfma_f32_16x16x32_bf16 v[16:19], v[166:169], v[192:195], v[16:19]
	v_mfma_f32_16x16x32_bf16 v[12:15], v[144:147], v[200:203], v[12:15]
	v_mfma_f32_16x16x32_bf16 v[8:11], v[166:169], v[200:203], v[8:11]
	v_mfma_f32_16x16x32_bf16 v[4:7], v[144:147], v[208:211], v[4:7]
	v_mfma_f32_16x16x32_bf16 v[0:3], v[166:169], v[208:211], v[0:3]
	v_mfma_f32_16x16x32_bf16 v[28:31], v[148:151], v[188:191], v[28:31]
	v_mfma_f32_16x16x32_bf16 v[24:27], v[170:173], v[188:191], v[24:27]
	v_mfma_f32_16x16x32_bf16 v[20:23], v[148:151], v[196:199], v[20:23]
	v_mfma_f32_16x16x32_bf16 v[16:19], v[170:173], v[196:199], v[16:19]
	v_mfma_f32_16x16x32_bf16 v[12:15], v[148:151], v[204:207], v[12:15]
	v_mfma_f32_16x16x32_bf16 v[8:11], v[170:173], v[204:207], v[8:11]
	v_mfma_f32_16x16x32_bf16 v[4:7], v[148:151], v[212:215], v[4:7]
	v_mfma_f32_16x16x32_bf16 v[0:3], v[170:173], v[212:215], v[0:3]
	s_barrier
	s_add_i32 s62, 0, 0x18000
	s_add_i32 s63, 0, 0x1c000
	v_add_u32_e32 v140, s62, v181
	v_add_u32_e32 v170, s63, v181
	ds_read_b128 v[128:131], v140
	ds_read_b128 v[132:135], v140 offset:1024
	ds_read_b128 v[136:139], v140 offset:2048
	ds_read_b128 v[140:143], v140 offset:3072
	ds_read_b128 v[144:147], v170
	ds_read_b128 v[148:151], v170 offset:1024
	ds_read_b128 v[166:169], v170 offset:2048
	ds_read_b128 v[170:173], v170 offset:3072
	s_add_u32 s4, s24, 0xc0000
	s_addc_u32 s5, s25, 0
	s_mov_b32 m0, s35
	v_lshl_add_u64 v[222:223], s[4:5], 0, v[154:155]
	ds_read_b128 v[184:187], v183 offset:32768
	ds_read_b128 v[188:191], v183 offset:33792
	ds_read_b128 v[192:195], v183 offset:34816
	ds_read_b128 v[196:199], v183 offset:35840
	ds_read_b128 v[200:203], v183 offset:36864
	ds_read_b128 v[204:207], v183 offset:37888
	ds_read_b128 v[208:211], v183 offset:38912
	ds_read_b128 v[212:215], v183 offset:39936
	global_load_lds_dwordx4 v[222:223], off
	v_lshl_add_u64 v[222:223], s[4:5], 0, v[158:159]
	s_mov_b32 m0, s36
	s_nop 0
	global_load_lds_dwordx4 v[222:223], off
	s_waitcnt vmcnt(8)
	s_waitcnt lgkmcnt(0)
	s_barrier
	s_waitcnt lgkmcnt(0)
	v_mfma_f32_16x16x32_bf16 v[124:127], v[128:131], v[184:187], v[124:127]
	v_mfma_f32_16x16x32_bf16 v[120:123], v[136:139], v[184:187], v[120:123]
	v_mfma_f32_16x16x32_bf16 v[116:119], v[128:131], v[192:195], v[116:119]
	v_mfma_f32_16x16x32_bf16 v[112:115], v[136:139], v[192:195], v[112:115]
	v_mfma_f32_16x16x32_bf16 v[108:111], v[128:131], v[200:203], v[108:111]
	v_mfma_f32_16x16x32_bf16 v[104:107], v[136:139], v[200:203], v[104:107]
	v_mfma_f32_16x16x32_bf16 v[100:103], v[128:131], v[208:211], v[100:103]
	v_mfma_f32_16x16x32_bf16 v[96:99], v[136:139], v[208:211], v[96:99]
	v_mfma_f32_16x16x32_bf16 v[124:127], v[132:135], v[188:191], v[124:127]
	v_mfma_f32_16x16x32_bf16 v[120:123], v[140:143], v[188:191], v[120:123]
	v_mfma_f32_16x16x32_bf16 v[116:119], v[132:135], v[196:199], v[116:119]
	v_mfma_f32_16x16x32_bf16 v[112:115], v[140:143], v[196:199], v[112:115]
	v_mfma_f32_16x16x32_bf16 v[108:111], v[132:135], v[204:207], v[108:111]
	v_mfma_f32_16x16x32_bf16 v[104:107], v[140:143], v[204:207], v[104:107]
	v_mfma_f32_16x16x32_bf16 v[100:103], v[132:135], v[212:215], v[100:103]
	v_mfma_f32_16x16x32_bf16 v[96:99], v[140:143], v[212:215], v[96:99]
	v_mfma_f32_16x16x32_bf16 v[92:95], v[144:147], v[184:187], v[92:95]
	v_mfma_f32_16x16x32_bf16 v[88:91], v[166:169], v[184:187], v[88:91]
	v_mfma_f32_16x16x32_bf16 v[84:87], v[144:147], v[192:195], v[84:87]
	v_mfma_f32_16x16x32_bf16 v[80:83], v[166:169], v[192:195], v[80:83]
	v_mfma_f32_16x16x32_bf16 v[76:79], v[144:147], v[200:203], v[76:79]
	v_mfma_f32_16x16x32_bf16 v[72:75], v[166:169], v[200:203], v[72:75]
	v_mfma_f32_16x16x32_bf16 v[68:71], v[144:147], v[208:211], v[68:71]
	v_mfma_f32_16x16x32_bf16 v[64:67], v[166:169], v[208:211], v[64:67]
	v_mfma_f32_16x16x32_bf16 v[92:95], v[148:151], v[188:191], v[92:95]
	v_mfma_f32_16x16x32_bf16 v[88:91], v[170:173], v[188:191], v[88:91]
	v_mfma_f32_16x16x32_bf16 v[84:87], v[148:151], v[196:199], v[84:87]
	v_mfma_f32_16x16x32_bf16 v[80:83], v[170:173], v[196:199], v[80:83]
	v_mfma_f32_16x16x32_bf16 v[76:79], v[148:151], v[204:207], v[76:79]
	v_mfma_f32_16x16x32_bf16 v[72:75], v[170:173], v[204:207], v[72:75]
	v_mfma_f32_16x16x32_bf16 v[68:71], v[148:151], v[212:215], v[68:71]
	v_mfma_f32_16x16x32_bf16 v[64:67], v[170:173], v[212:215], v[64:67]
	s_barrier
; #define PG8_STAGE(bufoff, gbase, voff) do { _Pragma("unroll") for (int _i = 0; _i < 2; ++_i) \
;         __builtin_amdgcn_global_load_lds((const unsigned*)((const char*)(gbase) + (voff)[_i]), (LAS unsigned*)(lds + (bufoff) + ldsw + _i * 8192), 16, 0, 0); } while (0)
; #define PG8_LDA(dst, b, h) do { _Pragma("unroll") for (int m = 0; m < 4; ++m) _Pragma("unroll") for (int k = 0; k < 2; ++k) dst[m][k] = *(const LAS bf16x8*)(lds + PG8_SA(b, h) + aoff + m * 2048 + k * 1024); } while (0)
; #define PG8_MMA(ai, bj, At, Bt) do { __builtin_amdgcn_s_setprio(1); _Pragma("unroll") for (int m = 0; m < 4; ++m) _Pragma("unroll") for (int n = 0; n < 2; ++n) _Pragma("unroll") for (int k = 0; k < 2; ++k) \
;         acc[ai][bj][m][n] = __builtin_amdgcn_mfma_f32_16x16x32_bf16(Bt[n][k], At[m][k], acc[ai][bj][m][n], 0, 0, 0); __builtin_amdgcn_s_setprio(0); } while (0)
; #define PG8_WAIT_V(n) asm volatile("s_waitcnt vmcnt(" #n ")" ::: "memory")
; #define PG8_WAIT_L(n) asm volatile("s_waitcnt lgkmcnt(" #n ")" ::: "memory")
; #define PG8_BAR __builtin_amdgcn_s_barrier()
; #define PG8_SCHED __builtin_amdgcn_sched_barrier(0)
; template <class Sched, class Epi, bool ALIGN_EPI, bool SP2>
; __device__ __forceinline__ void gemm_phase(LAS unsigned char* lds, const int K, const int lda, const int ldb, const Sched& S, const Epi& E) {
;     ...
;             PG8_LDA(At, 1, 1); PG8_STAGE(PG8_SB(1, 0), b3, voffB); PG8_STAGE(PG8_SB(1, 1), b3 + hstepB, voffB); PG8_STAGE(PG8_SA(1, 0), a3, voffA);
;             PG8_WAIT_V(8); PG8_WAIT_L(0); PG8_BAR; PG8_MMA(1, 0, At, B0); PG8_MMA(1, 1, At, B1); PG8_BAR; PG8_SCHED;
;     ...
;         }
;         if constexpr (ALIGN_EPI) { if (wr == 0) PG8_BAR; }
	s_add_i32 s4, s62, s28
	v_lshl_add_u64 v[174:175], v[174:175], 0, s[8:9]
	s_mov_b32 m0, s4
	ds_read_b128 v[184:187], v183 offset:49152
	ds_read_b128 v[188:191], v183 offset:50176
	ds_read_b128 v[192:195], v183 offset:51200
	ds_read_b128 v[196:199], v183 offset:52224
	ds_read_b128 v[200:203], v183 offset:53248
	ds_read_b128 v[204:207], v183 offset:54272
	ds_read_b128 v[208:211], v183 offset:55296
	ds_read_b128 v[212:215], v183 offset:56320
	global_load_lds_dwordx4 v[174:175], off
	s_add_i32 m0, s4, 0x2000
	s_add_u32 s4, s22, 0x40080
	v_lshl_add_u64 v[174:175], v[216:217], 0, s[8:9]
	s_addc_u32 s5, s23, 0
	s_add_i32 s22, s63, s28
	global_load_lds_dwordx4 v[174:175], off
	v_lshl_add_u64 v[174:175], s[4:5], 0, v[156:157]
	s_mov_b32 m0, s22
	s_nop 0
	global_load_lds_dwordx4 v[174:175], off
	v_lshl_add_u64 v[174:175], s[4:5], 0, v[160:161]
	s_add_i32 m0, s22, 0x2000
	s_nop 0
	global_load_lds_dwordx4 v[174:175], off
	v_lshl_add_u64 v[174:175], v[218:219], 0, s[8:9]
	s_mov_b32 m0, s42
	s_nop 0
	global_load_lds_dwordx4 v[174:175], off
	v_lshl_add_u64 v[174:175], v[220:221], 0, s[8:9]
	s_mov_b32 m0, s43
	s_nop 0
	global_load_lds_dwordx4 v[174:175], off
	s_waitcnt vmcnt(8)
	s_waitcnt lgkmcnt(0)
	s_barrier
	s_waitcnt lgkmcnt(0)
	v_mfma_f32_16x16x32_bf16 v[60:63], v[128:131], v[184:187], v[60:63]
	v_mfma_f32_16x16x32_bf16 v[56:59], v[136:139], v[184:187], v[56:59]
	v_mfma_f32_16x16x32_bf16 v[52:55], v[128:131], v[192:195], v[52:55]
	v_mfma_f32_16x16x32_bf16 v[48:51], v[136:139], v[192:195], v[48:51]
	v_mfma_f32_16x16x32_bf16 v[44:47], v[128:131], v[200:203], v[44:47]
	v_mfma_f32_16x16x32_bf16 v[40:43], v[136:139], v[200:203], v[40:43]
	v_mfma_f32_16x16x32_bf16 v[36:39], v[128:131], v[208:211], v[36:39]
	v_mfma_f32_16x16x32_bf16 v[32:35], v[136:139], v[208:211], v[32:35]
	v_mfma_f32_16x16x32_bf16 v[60:63], v[132:135], v[188:191], v[60:63]
	v_mfma_f32_16x16x32_bf16 v[56:59], v[140:143], v[188:191], v[56:59]
	v_mfma_f32_16x16x32_bf16 v[52:55], v[132:135], v[196:199], v[52:55]
	v_mfma_f32_16x16x32_bf16 v[48:51], v[140:143], v[196:199], v[48:51]
	v_mfma_f32_16x16x32_bf16 v[44:47], v[132:135], v[204:207], v[44:47]
	v_mfma_f32_16x16x32_bf16 v[40:43], v[140:143], v[204:207], v[40:43]
	v_mfma_f32_16x16x32_bf16 v[36:39], v[132:135], v[212:215], v[36:39]
	v_mfma_f32_16x16x32_bf16 v[32:35], v[140:143], v[212:215], v[32:35]
	v_mfma_f32_16x16x32_bf16 v[28:31], v[144:147], v[184:187], v[28:31]
	v_mfma_f32_16x16x32_bf16 v[24:27], v[166:169], v[184:187], v[24:27]
	v_mfma_f32_16x16x32_bf16 v[20:23], v[144:147], v[192:195], v[20:23]
	v_mfma_f32_16x16x32_bf16 v[16:19], v[166:169], v[192:195], v[16:19]
	v_mfma_f32_16x16x32_bf16 v[12:15], v[144:147], v[200:203], v[12:15]
	v_mfma_f32_16x16x32_bf16 v[8:11], v[166:169], v[200:203], v[8:11]
	v_mfma_f32_16x16x32_bf16 v[4:7], v[144:147], v[208:211], v[4:7]
	v_mfma_f32_16x16x32_bf16 v[0:3], v[166:169], v[208:211], v[0:3]
	v_mfma_f32_16x16x32_bf16 v[28:31], v[148:151], v[188:191], v[28:31]
	v_mfma_f32_16x16x32_bf16 v[24:27], v[170:173], v[188:191], v[24:27]
	v_mfma_f32_16x16x32_bf16 v[20:23], v[148:151], v[196:199], v[20:23]
	v_mfma_f32_16x16x32_bf16 v[16:19], v[170:173], v[196:199], v[16:19]
	v_mfma_f32_16x16x32_bf16 v[12:15], v[148:151], v[204:207], v[12:15]
	v_mfma_f32_16x16x32_bf16 v[8:11], v[170:173], v[204:207], v[8:11]
	v_mfma_f32_16x16x32_bf16 v[4:7], v[148:151], v[212:215], v[4:7]
	v_mfma_f32_16x16x32_bf16 v[0:3], v[170:173], v[212:215], v[0:3]
	s_barrier
	s_add_i32 s61, s61, 2
	s_add_u32 s53, s53, 0x100
	s_addc_u32 s60, s60, 0
	s_cmp_gt_u32 s61, 13
	s_mov_b64 s[4:5], s[20:21]
	s_cbranch_scc0 .LBB0_821
	s_and_b64 vcc, exec, s[10:11]
	s_cbranch_vccz .LBB0_824
	s_barrier

; #define PG8_STAGE(bufoff, gbase, voff) do { _Pragma("unroll") for (int _i = 0; _i < 2; ++_i) \
;         __builtin_amdgcn_global_load_lds((const unsigned*)((const char*)(gbase) + (voff)[_i]), (LAS unsigned*)(lds + (bufoff) + ldsw + _i * 8192), 16, 0, 0); } while (0)
; #define PG8_LDA(dst, b, h) do { _Pragma("unroll") for (int m = 0; m < 4; ++m) _Pragma("unroll") for (int k = 0; k < 2; ++k) dst[m][k] = *(const LAS bf16x8*)(lds + PG8_SA(b, h) + aoff + m * 2048 + k * 1024); } while (0)
; #define PG8_LDB(dst, b, h) do { _Pragma("unroll") for (int n = 0; n < 2; ++n) _Pragma("unroll") for (int k = 0; k < 2; ++k) dst[n][k] = *(const LAS bf16x8*)(lds + PG8_SB(b, h) + boff + n * 2048 + k * 1024); } while (0)
; #define PG8_MMA(ai, bj, At, Bt) do { __builtin_amdgcn_s_setprio(1); _Pragma("unroll") for (int m = 0; m < 4; ++m) _Pragma("unroll") for (int n = 0; n < 2; ++n) _Pragma("unroll") for (int k = 0; k < 2; ++k) \
;         acc[ai][bj][m][n] = __builtin_amdgcn_mfma_f32_16x16x32_bf16(Bt[n][k], At[m][k], acc[ai][bj][m][n], 0, 0, 0); __builtin_amdgcn_s_setprio(0); } while (0)
; #define PG8_WAIT_V(n) asm volatile("s_waitcnt vmcnt(" #n ")" ::: "memory")
; #define PG8_WAIT_L(n) asm volatile("s_waitcnt lgkmcnt(" #n ")" ::: "memory")
; #define PG8_BAR __builtin_amdgcn_s_barrier()
; #define PG8_SCHED __builtin_amdgcn_sched_barrier(0)
; template <class Sched, class Epi, bool ALIGN_EPI, bool SP2>
; __device__ __forceinline__ void gemm_phase(LAS unsigned char* lds, const int K, const int lda, const int ldb, const Sched& S, const Epi& E) {
;     ...
;             const bool last = (t == nt - 2);
;             const char* a1 = cA + (size_t)(t + 1) * kstep;
;             const char* a2 = last ? nA : cA + (size_t)(t + 2) * kstep; const char* b2 = last ? nB : cB + (size_t)(t + 2) * kstep;
;             const char* a3 = a2 + kstep; const char* b3 = b2 + kstep;
;             if constexpr (SP2) {
;             PG8_LDB(B0, 0, 0); PG8_LDB(B1, 0, 1); PG8_SCHED; PG8_LDA(At, 0, 0); PG8_STAGE(PG8_SA(1, 1), a1 + hstepA, voffA);
;             PG8_WAIT_V(8); PG8_WAIT_L(0); PG8_BAR; PG8_MMA(0, 0, At, B0); PG8_MMA(0, 1, At, B1); PG8_BAR; PG8_SCHED;
;             PG8_LDA(At, 0, 1); PG8_STAGE(PG8_SB(0, 0), b2, voffB); PG8_STAGE(PG8_SB(0, 1), b2 + hstepB, voffB); PG8_STAGE(PG8_SA(0, 0), a2, voffA);
.Lprio_skip_945:
.LBB0_945:
	ds_read_b128 v[52:55], v209
	ds_read_b128 v[56:59], v209 offset:1024
	ds_read_b128 v[64:67], v209 offset:2048
	ds_read_b128 v[68:71], v209 offset:3072
	ds_read_b128 v[72:75], v210
	ds_read_b128 v[76:79], v210 offset:1024
	ds_read_b128 v[88:91], v210 offset:2048
	ds_read_b128 v[92:95], v210 offset:3072
	s_add_u32 s42, s36, 0xfff80080
	s_addc_u32 s43, s37, -1
	s_cmp_eq_u32 s61, 28
	s_cselect_b32 s45, s27, s43
	s_cselect_b32 s44, s26, s42
	s_cselect_b32 s43, s29, s25
	s_cselect_b32 s42, s28, s1
	v_lshl_add_u64 v[206:207], s[36:37], 0, v[186:187]
	s_add_i32 m0, s21, 0xc000
	ds_read_b128 v[160:163], v211
	ds_read_b128 v[164:167], v211 offset:1024
	ds_read_b128 v[168:171], v211 offset:2048
	ds_read_b128 v[172:175], v211 offset:3072
	ds_read_b128 v[190:193], v211 offset:4096
	ds_read_b128 v[194:197], v211 offset:5120
	ds_read_b128 v[198:201], v211 offset:6144
	ds_read_b128 v[202:205], v211 offset:7168
	global_load_lds_dwordx4 v[206:207], off
	v_lshl_add_u64 v[206:207], s[36:37], 0, v[188:189]
	s_add_i32 m0, s21, 0xe000
	s_nop 0
	global_load_lds_dwordx4 v[206:207], off
	s_waitcnt vmcnt(8)
	s_waitcnt lgkmcnt(0)
	s_barrier
	s_waitcnt lgkmcnt(0)
	v_mfma_f32_16x16x32_bf16 v[156:159], v[52:55], v[160:163], v[156:159]
	v_mfma_f32_16x16x32_bf16 v[152:155], v[64:67], v[160:163], v[152:155]
	v_mfma_f32_16x16x32_bf16 v[140:143], v[52:55], v[168:171], v[140:143]
	v_mfma_f32_16x16x32_bf16 v[136:139], v[64:67], v[168:171], v[136:139]
	v_mfma_f32_16x16x32_bf16 v[124:127], v[52:55], v[190:193], v[124:127]
	v_mfma_f32_16x16x32_bf16 v[120:123], v[64:67], v[190:193], v[120:123]
	v_mfma_f32_16x16x32_bf16 v[108:111], v[52:55], v[198:201], v[108:111]
	v_mfma_f32_16x16x32_bf16 v[104:107], v[64:67], v[198:201], v[104:107]
	v_mfma_f32_16x16x32_bf16 v[156:159], v[56:59], v[164:167], v[156:159]
	v_mfma_f32_16x16x32_bf16 v[152:155], v[68:71], v[164:167], v[152:155]
	v_mfma_f32_16x16x32_bf16 v[140:143], v[56:59], v[172:175], v[140:143]
	v_mfma_f32_16x16x32_bf16 v[136:139], v[68:71], v[172:175], v[136:139]
	v_mfma_f32_16x16x32_bf16 v[124:127], v[56:59], v[194:197], v[124:127]
	v_mfma_f32_16x16x32_bf16 v[120:123], v[68:71], v[194:197], v[120:123]
	v_mfma_f32_16x16x32_bf16 v[108:111], v[56:59], v[202:205], v[108:111]
	v_mfma_f32_16x16x32_bf16 v[104:107], v[68:71], v[202:205], v[104:107]
	v_mfma_f32_16x16x32_bf16 v[148:151], v[72:75], v[160:163], v[148:151]
	v_mfma_f32_16x16x32_bf16 v[144:147], v[88:91], v[160:163], v[144:147]
	v_mfma_f32_16x16x32_bf16 v[132:135], v[72:75], v[168:171], v[132:135]
	v_mfma_f32_16x16x32_bf16 v[128:131], v[88:91], v[168:171], v[128:131]
	v_mfma_f32_16x16x32_bf16 v[116:119], v[72:75], v[190:193], v[116:119]
	v_mfma_f32_16x16x32_bf16 v[112:115], v[88:91], v[190:193], v[112:115]
	v_mfma_f32_16x16x32_bf16 v[100:103], v[72:75], v[198:201], v[100:103]
	v_mfma_f32_16x16x32_bf16 v[96:99], v[88:91], v[198:201], v[96:99]
	v_mfma_f32_16x16x32_bf16 v[148:151], v[76:79], v[164:167], v[148:151]
	v_mfma_f32_16x16x32_bf16 v[144:147], v[92:95], v[164:167], v[144:147]
	v_mfma_f32_16x16x32_bf16 v[132:135], v[76:79], v[172:175], v[132:135]
	v_mfma_f32_16x16x32_bf16 v[128:131], v[92:95], v[172:175], v[128:131]
	v_mfma_f32_16x16x32_bf16 v[116:119], v[76:79], v[194:197], v[116:119]
	v_mfma_f32_16x16x32_bf16 v[112:115], v[92:95], v[194:197], v[112:115]
	v_mfma_f32_16x16x32_bf16 v[100:103], v[76:79], v[202:205], v[100:103]
	v_mfma_f32_16x16x32_bf16 v[96:99], v[92:95], v[202:205], v[96:99]
	s_barrier
	s_add_i32 s62, s50, s19
	v_lshl_add_u64 v[206:207], s[42:43], 0, v[182:183]
	s_mov_b32 m0, s62
	ds_read_b128 v[160:163], v211 offset:16384
	ds_read_b128 v[164:167], v211 offset:17408
	ds_read_b128 v[168:171], v211 offset:18432
	ds_read_b128 v[172:175], v211 offset:19456
	ds_read_b128 v[190:193], v211 offset:20480
	ds_read_b128 v[194:197], v211 offset:21504
	ds_read_b128 v[198:201], v211 offset:22528
	ds_read_b128 v[202:205], v211 offset:23552
	global_load_lds_dwordx4 v[206:207], off
	s_add_i32 m0, s62, 0x2000
	s_add_u32 s62, s42, 0x80000
	v_lshl_add_u64 v[214:215], s[42:43], 0, v[184:185]
	s_addc_u32 s63, s43, 0
	s_add_i32 s64, s51, s19
	global_load_lds_dwordx4 v[214:215], off
	v_lshl_add_u64 v[216:217], s[62:63], 0, v[182:183]
	s_mov_b32 m0, s64
	v_lshl_add_u64 v[218:219], s[44:45], 0, v[184:185]
	global_load_lds_dwordx4 v[216:217], off
	v_lshl_add_u64 v[216:217], s[62:63], 0, v[184:185]
	s_add_i32 m0, s64, 0x2000
	s_nop 0
	global_load_lds_dwordx4 v[216:217], off
	v_lshl_add_u64 v[216:217], s[44:45], 0, v[182:183]
	s_mov_b32 m0, s21
	s_nop 0
	global_load_lds_dwordx4 v[216:217], off
	s_mov_b32 m0, s33
	s_nop 0
	global_load_lds_dwordx4 v[218:219], off
	s_waitcnt vmcnt(8)
	s_waitcnt lgkmcnt(0)
	s_barrier
; #define PG8_STAGE(bufoff, gbase, voff) do { _Pragma("unroll") for (int _i = 0; _i < 2; ++_i) \
;         __builtin_amdgcn_global_load_lds((const unsigned*)((const char*)(gbase) + (voff)[_i]), (LAS unsigned*)(lds + (bufoff) + ldsw + _i * 8192), 16, 0, 0); } while (0)
; #define PG8_LDA(dst, b, h) do { _Pragma("unroll") for (int m = 0; m < 4; ++m) _Pragma("unroll") for (int k = 0; k < 2; ++k) dst[m][k] = *(const LAS bf16x8*)(lds + PG8_SA(b, h) + aoff + m * 2048 + k * 1024); } while (0)
; #define PG8_LDB(dst, b, h) do { _Pragma("unroll") for (int n = 0; n < 2; ++n) _Pragma("unroll") for (int k = 0; k < 2; ++k) dst[n][k] = *(const LAS bf16x8*)(lds + PG8_SB(b, h) + boff + n * 2048 + k * 1024); } while (0)
; #define PG8_MMA(ai, bj, At, Bt) do { __builtin_amdgcn_s_setprio(1); _Pragma("unroll") for (int m = 0; m < 4; ++m) _Pragma("unroll") for (int n = 0; n < 2; ++n) _Pragma("unroll") for (int k = 0; k < 2; ++k) \
;         acc[ai][bj][m][n] = __builtin_amdgcn_mfma_f32_16x16x32_bf16(Bt[n][k], At[m][k], acc[ai][bj][m][n], 0, 0, 0); __builtin_amdgcn_s_setprio(0); } while (0)
; #define PG8_WAIT_V(n) asm volatile("s_waitcnt vmcnt(" #n ")" ::: "memory")
; #define PG8_WAIT_L(n) asm volatile("s_waitcnt lgkmcnt(" #n ")" ::: "memory")
; #define PG8_BAR __builtin_amdgcn_s_barrier()
; #define PG8_SCHED __builtin_amdgcn_sched_barrier(0)
; template <class Sched, class Epi, bool ALIGN_EPI, bool SP2>
; __device__ __forceinline__ void gemm_phase(LAS unsigned char* lds, const int K, const int lda, const int ldb, const Sched& S, const Epi& E) {
;     ...
;             PG8_WAIT_V(8); PG8_WAIT_L(0); PG8_BAR; PG8_MMA(1, 0, At, B0); PG8_MMA(1, 1, At, B1); PG8_BAR; PG8_SCHED;
;             PG8_LDB(B0, 1, 0); PG8_LDB(B1, 1, 1); PG8_SCHED; PG8_LDA(At, 1, 0); PG8_STAGE(PG8_SA(0, 1), a2 + hstepA, voffA);
;             PG8_WAIT_V(8); PG8_WAIT_L(0); PG8_BAR; PG8_MMA(0, 0, At, B0); PG8_MMA(0, 1, At, B1); PG8_BAR; PG8_SCHED;
	s_waitcnt lgkmcnt(0)
	v_mfma_f32_16x16x32_bf16 v[84:87], v[52:55], v[160:163], v[84:87]
	v_mfma_f32_16x16x32_bf16 v[80:83], v[64:67], v[160:163], v[80:83]
	v_mfma_f32_16x16x32_bf16 v[44:47], v[52:55], v[168:171], v[44:47]
	v_mfma_f32_16x16x32_bf16 v[40:43], v[64:67], v[168:171], v[40:43]
	v_mfma_f32_16x16x32_bf16 v[28:31], v[52:55], v[190:193], v[28:31]
	v_mfma_f32_16x16x32_bf16 v[24:27], v[64:67], v[190:193], v[24:27]
	v_mfma_f32_16x16x32_bf16 v[12:15], v[52:55], v[198:201], v[12:15]
	v_mfma_f32_16x16x32_bf16 v[8:11], v[64:67], v[198:201], v[8:11]
	v_mfma_f32_16x16x32_bf16 v[84:87], v[56:59], v[164:167], v[84:87]
	v_mfma_f32_16x16x32_bf16 v[80:83], v[68:71], v[164:167], v[80:83]
	v_mfma_f32_16x16x32_bf16 v[44:47], v[56:59], v[172:175], v[44:47]
	v_mfma_f32_16x16x32_bf16 v[40:43], v[68:71], v[172:175], v[40:43]
	v_mfma_f32_16x16x32_bf16 v[28:31], v[56:59], v[194:197], v[28:31]
	v_mfma_f32_16x16x32_bf16 v[24:27], v[68:71], v[194:197], v[24:27]
	v_mfma_f32_16x16x32_bf16 v[12:15], v[56:59], v[202:205], v[12:15]
	v_mfma_f32_16x16x32_bf16 v[8:11], v[68:71], v[202:205], v[8:11]
	v_mfma_f32_16x16x32_bf16 v[48:51], v[88:91], v[160:163], v[48:51]
	v_mfma_f32_16x16x32_bf16 v[36:39], v[72:75], v[168:171], v[36:39]
	v_mfma_f32_16x16x32_bf16 v[32:35], v[88:91], v[168:171], v[32:35]
	v_mfma_f32_16x16x32_bf16 v[20:23], v[72:75], v[190:193], v[20:23]
	v_mfma_f32_16x16x32_bf16 v[16:19], v[88:91], v[190:193], v[16:19]
	v_mfma_f32_16x16x32_bf16 v[4:7], v[72:75], v[198:201], v[4:7]
	v_mfma_f32_16x16x32_bf16 v[0:3], v[88:91], v[198:201], v[0:3]
	v_mfma_f32_16x16x32_bf16 v[52:55], v[72:75], v[160:163], v[60:63]
	v_mfma_f32_16x16x32_bf16 v[48:51], v[92:95], v[164:167], v[48:51]
	v_mfma_f32_16x16x32_bf16 v[36:39], v[76:79], v[172:175], v[36:39]
	v_mfma_f32_16x16x32_bf16 v[32:35], v[92:95], v[172:175], v[32:35]
	v_mfma_f32_16x16x32_bf16 v[20:23], v[76:79], v[194:197], v[20:23]
	v_mfma_f32_16x16x32_bf16 v[16:19], v[92:95], v[194:197], v[16:19]
	v_mfma_f32_16x16x32_bf16 v[4:7], v[76:79], v[202:205], v[4:7]
	v_mfma_f32_16x16x32_bf16 v[0:3], v[92:95], v[202:205], v[0:3]
	v_mfma_f32_16x16x32_bf16 v[52:55], v[76:79], v[164:167], v[52:55]
	s_barrier
	s_add_i32 s62, 0, 0x18000
	s_add_i32 s63, 0, 0x1c000
	v_add_u32_e32 v68, s62, v181
	v_add_u32_e32 v92, s63, v181
	ds_read_b128 v[56:59], v68
	ds_read_b128 v[60:63], v68 offset:1024
	ds_read_b128 v[64:67], v68 offset:2048
	ds_read_b128 v[68:71], v68 offset:3072
	ds_read_b128 v[72:75], v92
	ds_read_b128 v[76:79], v92 offset:1024
	ds_read_b128 v[88:91], v92 offset:2048
	ds_read_b128 v[92:95], v92 offset:3072
	s_add_u32 s44, s44, 0x80000
	s_addc_u32 s45, s45, 0
	s_mov_b32 m0, s35
	v_lshl_add_u64 v[220:221], s[44:45], 0, v[182:183]
	ds_read_b128 v[160:163], v211 offset:32768
	ds_read_b128 v[164:167], v211 offset:33792
	ds_read_b128 v[168:171], v211 offset:34816
	ds_read_b128 v[172:175], v211 offset:35840
	ds_read_b128 v[190:193], v211 offset:36864
	ds_read_b128 v[194:197], v211 offset:37888
	ds_read_b128 v[198:201], v211 offset:38912
	ds_read_b128 v[202:205], v211 offset:39936
	global_load_lds_dwordx4 v[220:221], off
	v_lshl_add_u64 v[220:221], s[44:45], 0, v[184:185]
	s_mov_b32 m0, s46
	s_nop 0
	global_load_lds_dwordx4 v[220:221], off
	s_waitcnt vmcnt(8)
	s_waitcnt lgkmcnt(0)
	s_barrier
	s_waitcnt lgkmcnt(0)
	v_mfma_f32_16x16x32_bf16 v[156:159], v[56:59], v[160:163], v[156:159]
	v_mfma_f32_16x16x32_bf16 v[152:155], v[64:67], v[160:163], v[152:155]
	v_mfma_f32_16x16x32_bf16 v[140:143], v[56:59], v[168:171], v[140:143]
	v_mfma_f32_16x16x32_bf16 v[136:139], v[64:67], v[168:171], v[136:139]
	v_mfma_f32_16x16x32_bf16 v[124:127], v[56:59], v[190:193], v[124:127]
	v_mfma_f32_16x16x32_bf16 v[120:123], v[64:67], v[190:193], v[120:123]
	v_mfma_f32_16x16x32_bf16 v[108:111], v[56:59], v[198:201], v[108:111]
	v_mfma_f32_16x16x32_bf16 v[104:107], v[64:67], v[198:201], v[104:107]
	v_mfma_f32_16x16x32_bf16 v[156:159], v[60:63], v[164:167], v[156:159]
	v_mfma_f32_16x16x32_bf16 v[152:155], v[68:71], v[164:167], v[152:155]
	v_mfma_f32_16x16x32_bf16 v[140:143], v[60:63], v[172:175], v[140:143]
	v_mfma_f32_16x16x32_bf16 v[136:139], v[68:71], v[172:175], v[136:139]
	v_mfma_f32_16x16x32_bf16 v[124:127], v[60:63], v[194:197], v[124:127]
	v_mfma_f32_16x16x32_bf16 v[120:123], v[68:71], v[194:197], v[120:123]
	v_mfma_f32_16x16x32_bf16 v[108:111], v[60:63], v[202:205], v[108:111]
	v_mfma_f32_16x16x32_bf16 v[104:107], v[68:71], v[202:205], v[104:107]
	v_mfma_f32_16x16x32_bf16 v[148:151], v[72:75], v[160:163], v[148:151]
	v_mfma_f32_16x16x32_bf16 v[144:147], v[88:91], v[160:163], v[144:147]
	v_mfma_f32_16x16x32_bf16 v[132:135], v[72:75], v[168:171], v[132:135]
	v_mfma_f32_16x16x32_bf16 v[128:131], v[88:91], v[168:171], v[128:131]
	v_mfma_f32_16x16x32_bf16 v[116:119], v[72:75], v[190:193], v[116:119]
	v_mfma_f32_16x16x32_bf16 v[112:115], v[88:91], v[190:193], v[112:115]
	v_mfma_f32_16x16x32_bf16 v[100:103], v[72:75], v[198:201], v[100:103]
	v_mfma_f32_16x16x32_bf16 v[96:99], v[88:91], v[198:201], v[96:99]
	v_mfma_f32_16x16x32_bf16 v[148:151], v[76:79], v[164:167], v[148:151]
	v_mfma_f32_16x16x32_bf16 v[144:147], v[92:95], v[164:167], v[144:147]
	v_mfma_f32_16x16x32_bf16 v[132:135], v[76:79], v[172:175], v[132:135]
	v_mfma_f32_16x16x32_bf16 v[128:131], v[92:95], v[172:175], v[128:131]
	v_mfma_f32_16x16x32_bf16 v[116:119], v[76:79], v[194:197], v[116:119]
	v_mfma_f32_16x16x32_bf16 v[112:115], v[92:95], v[194:197], v[112:115]
	v_mfma_f32_16x16x32_bf16 v[100:103], v[76:79], v[202:205], v[100:103]
	v_mfma_f32_16x16x32_bf16 v[96:99], v[92:95], v[202:205], v[96:99]
	s_barrier
; #define PG8_STAGE(bufoff, gbase, voff) do { _Pragma("unroll") for (int _i = 0; _i < 2; ++_i) \
;         __builtin_amdgcn_global_load_lds((const unsigned*)((const char*)(gbase) + (voff)[_i]), (LAS unsigned*)(lds + (bufoff) + ldsw + _i * 8192), 16, 0, 0); } while (0)
; #define PG8_LDA(dst, b, h) do { _Pragma("unroll") for (int m = 0; m < 4; ++m) _Pragma("unroll") for (int k = 0; k < 2; ++k) dst[m][k] = *(const LAS bf16x8*)(lds + PG8_SA(b, h) + aoff + m * 2048 + k * 1024); } while (0)
; #define PG8_MMA(ai, bj, At, Bt) do { __builtin_amdgcn_s_setprio(1); _Pragma("unroll") for (int m = 0; m < 4; ++m) _Pragma("unroll") for (int n = 0; n < 2; ++n) _Pragma("unroll") for (int k = 0; k < 2; ++k) \
;         acc[ai][bj][m][n] = __builtin_amdgcn_mfma_f32_16x16x32_bf16(Bt[n][k], At[m][k], acc[ai][bj][m][n], 0, 0, 0); __builtin_amdgcn_s_setprio(0); } while (0)
; #define PG8_WAIT_V(n) asm volatile("s_waitcnt vmcnt(" #n ")" ::: "memory")
; #define PG8_WAIT_L(n) asm volatile("s_waitcnt lgkmcnt(" #n ")" ::: "memory")
; #define PG8_BAR __builtin_amdgcn_s_barrier()
; #define PG8_SCHED __builtin_amdgcn_sched_barrier(0)
; template <class Sched, class Epi, bool ALIGN_EPI, bool SP2>
; __device__ __forceinline__ void gemm_phase(LAS unsigned char* lds, const int K, const int lda, const int ldb, const Sched& S, const Epi& E) {
;     ...
;             PG8_LDA(At, 1, 1); PG8_STAGE(PG8_SB(1, 0), b3, voffB); PG8_STAGE(PG8_SB(1, 1), b3 + hstepB, voffB); PG8_STAGE(PG8_SA(1, 0), a3, voffA);
;             PG8_WAIT_V(8); PG8_WAIT_L(0); PG8_BAR; PG8_MMA(1, 0, At, B0); PG8_MMA(1, 1, At, B1); PG8_BAR; PG8_SCHED;
;     ...
;         }
;         if constexpr (ALIGN_EPI) { if (wr == 0) PG8_BAR; }
	s_add_i32 s44, s62, s19
	v_lshl_add_u64 v[206:207], v[206:207], 0, s[14:15]
	s_mov_b32 m0, s44
	ds_read_b128 v[160:163], v211 offset:49152
	ds_read_b128 v[164:167], v211 offset:50176
	ds_read_b128 v[168:171], v211 offset:51200
	ds_read_b128 v[172:175], v211 offset:52224
	ds_read_b128 v[190:193], v211 offset:53248
	ds_read_b128 v[194:197], v211 offset:54272
	ds_read_b128 v[198:201], v211 offset:55296
	ds_read_b128 v[202:205], v211 offset:56320
	global_load_lds_dwordx4 v[206:207], off
	s_add_i32 m0, s44, 0x2000
	s_add_u32 s42, s42, 0x80080
	v_lshl_add_u64 v[206:207], v[214:215], 0, s[14:15]
	s_addc_u32 s43, s43, 0
	s_add_i32 s44, s63, s19
	global_load_lds_dwordx4 v[206:207], off
	v_lshl_add_u64 v[206:207], s[42:43], 0, v[182:183]
	s_mov_b32 m0, s44
	s_nop 0
	global_load_lds_dwordx4 v[206:207], off
	v_lshl_add_u64 v[206:207], s[42:43], 0, v[184:185]
	s_add_i32 m0, s44, 0x2000
	s_nop 0
	global_load_lds_dwordx4 v[206:207], off
	v_lshl_add_u64 v[206:207], v[216:217], 0, s[14:15]
	s_mov_b32 m0, s48
	s_nop 0
	global_load_lds_dwordx4 v[206:207], off
	v_lshl_add_u64 v[206:207], v[218:219], 0, s[14:15]
	s_mov_b32 m0, s49
	s_nop 0
	global_load_lds_dwordx4 v[206:207], off
	s_waitcnt vmcnt(8)
	s_waitcnt lgkmcnt(0)
	s_barrier
	s_waitcnt lgkmcnt(0)
	v_mfma_f32_16x16x32_bf16 v[84:87], v[56:59], v[160:163], v[84:87]
	v_mfma_f32_16x16x32_bf16 v[80:83], v[64:67], v[160:163], v[80:83]
	v_mfma_f32_16x16x32_bf16 v[44:47], v[56:59], v[168:171], v[44:47]
	v_mfma_f32_16x16x32_bf16 v[40:43], v[64:67], v[168:171], v[40:43]
	v_mfma_f32_16x16x32_bf16 v[28:31], v[56:59], v[190:193], v[28:31]
	v_mfma_f32_16x16x32_bf16 v[24:27], v[64:67], v[190:193], v[24:27]
	v_mfma_f32_16x16x32_bf16 v[12:15], v[56:59], v[198:201], v[12:15]
	v_mfma_f32_16x16x32_bf16 v[8:11], v[64:67], v[198:201], v[8:11]
	v_mfma_f32_16x16x32_bf16 v[84:87], v[60:63], v[164:167], v[84:87]
	v_mfma_f32_16x16x32_bf16 v[80:83], v[68:71], v[164:167], v[80:83]
	v_mfma_f32_16x16x32_bf16 v[44:47], v[60:63], v[172:175], v[44:47]
	v_mfma_f32_16x16x32_bf16 v[40:43], v[68:71], v[172:175], v[40:43]
	v_mfma_f32_16x16x32_bf16 v[28:31], v[60:63], v[194:197], v[28:31]
	v_mfma_f32_16x16x32_bf16 v[24:27], v[68:71], v[194:197], v[24:27]
	v_mfma_f32_16x16x32_bf16 v[12:15], v[60:63], v[202:205], v[12:15]
	v_mfma_f32_16x16x32_bf16 v[8:11], v[68:71], v[202:205], v[8:11]
	v_mfma_f32_16x16x32_bf16 v[52:55], v[72:75], v[160:163], v[52:55]
	v_mfma_f32_16x16x32_bf16 v[48:51], v[88:91], v[160:163], v[48:51]
	v_mfma_f32_16x16x32_bf16 v[36:39], v[72:75], v[168:171], v[36:39]
	v_mfma_f32_16x16x32_bf16 v[32:35], v[88:91], v[168:171], v[32:35]
	v_mfma_f32_16x16x32_bf16 v[20:23], v[72:75], v[190:193], v[20:23]
	v_mfma_f32_16x16x32_bf16 v[16:19], v[88:91], v[190:193], v[16:19]
	v_mfma_f32_16x16x32_bf16 v[4:7], v[72:75], v[198:201], v[4:7]
	v_mfma_f32_16x16x32_bf16 v[0:3], v[88:91], v[198:201], v[0:3]
	v_mfma_f32_16x16x32_bf16 v[60:63], v[76:79], v[164:167], v[52:55]
	v_mfma_f32_16x16x32_bf16 v[48:51], v[92:95], v[164:167], v[48:51]
	v_mfma_f32_16x16x32_bf16 v[36:39], v[76:79], v[172:175], v[36:39]
	v_mfma_f32_16x16x32_bf16 v[32:35], v[92:95], v[172:175], v[32:35]
	v_mfma_f32_16x16x32_bf16 v[20:23], v[76:79], v[194:197], v[20:23]
	v_mfma_f32_16x16x32_bf16 v[16:19], v[92:95], v[194:197], v[16:19]
	v_mfma_f32_16x16x32_bf16 v[4:7], v[76:79], v[202:205], v[4:7]
	v_mfma_f32_16x16x32_bf16 v[0:3], v[92:95], v[202:205], v[0:3]
	s_barrier
	s_add_i32 s61, s61, 2
	s_add_u32 s36, s36, 0x100
	s_addc_u32 s37, s37, 0
	s_add_u32 s1, s1, 0x100
	s_addc_u32 s25, s25, 0
	s_cmp_gt_u32 s61, 29
	s_cbranch_scc0 .LBB0_945
	s_and_b64 vcc, exec, s[16:17]
	s_cbranch_vccz .LBB0_948
	s_barrier

; #define PG8_STAGE(bufoff, gbase, voff) do { _Pragma("unroll") for (int _i = 0; _i < 2; ++_i) \
;         __builtin_amdgcn_global_load_lds((const unsigned*)((const char*)(gbase) + (voff)[_i]), (LAS unsigned*)(lds + (bufoff) + ldsw + _i * 8192), 16, 0, 0); } while (0)
; #define PG8_LDA(dst, b, h) do { _Pragma("unroll") for (int m = 0; m < 4; ++m) _Pragma("unroll") for (int k = 0; k < 2; ++k) dst[m][k] = *(const LAS bf16x8*)(lds + PG8_SA(b, h) + aoff + m * 2048 + k * 1024); } while (0)
; #define PG8_LDB(dst, b, h) do { _Pragma("unroll") for (int n = 0; n < 2; ++n) _Pragma("unroll") for (int k = 0; k < 2; ++k) dst[n][k] = *(const LAS bf16x8*)(lds + PG8_SB(b, h) + boff + n * 2048 + k * 1024); } while (0)
; #define PG8_MMA(ai, bj, At, Bt) do { __builtin_amdgcn_s_setprio(1); _Pragma("unroll") for (int m = 0; m < 4; ++m) _Pragma("unroll") for (int n = 0; n < 2; ++n) _Pragma("unroll") for (int k = 0; k < 2; ++k) \
;         acc[ai][bj][m][n] = __builtin_amdgcn_mfma_f32_16x16x32_bf16(Bt[n][k], At[m][k], acc[ai][bj][m][n], 0, 0, 0); __builtin_amdgcn_s_setprio(0); } while (0)
; #define PG8_WAIT_V(n) asm volatile("s_waitcnt vmcnt(" #n ")" ::: "memory")
; #define PG8_WAIT_L(n) asm volatile("s_waitcnt lgkmcnt(" #n ")" ::: "memory")
; #define PG8_BAR __builtin_amdgcn_s_barrier()
; #define PG8_SCHED __builtin_amdgcn_sched_barrier(0)
; template <class Sched, class Epi, bool ALIGN_EPI, bool SP2>
; __device__ __forceinline__ void gemm_phase(LAS unsigned char* lds, const int K, const int lda, const int ldb, const Sched& S, const Epi& E) {
;     ...
;             const bool last = (t == nt - 2);
;             const char* a1 = cA + (size_t)(t + 1) * kstep;
;             const char* a2 = last ? nA : cA + (size_t)(t + 2) * kstep; const char* b2 = last ? nB : cB + (size_t)(t + 2) * kstep;
;             const char* a3 = a2 + kstep; const char* b3 = b2 + kstep;
;             if constexpr (SP2) {
;             PG8_LDB(B0, 0, 0); PG8_LDB(B1, 0, 1); PG8_SCHED; PG8_LDA(At, 0, 0); PG8_STAGE(PG8_SA(1, 1), a1 + hstepA, voffA);
;             PG8_WAIT_V(8); PG8_WAIT_L(0); PG8_BAR; PG8_MMA(0, 0, At, B0); PG8_MMA(0, 1, At, B1); PG8_BAR; PG8_SCHED;
;             PG8_LDA(At, 0, 1); PG8_STAGE(PG8_SB(0, 0), b2, voffB); PG8_STAGE(PG8_SB(0, 1), b2 + hstepB, voffB); PG8_STAGE(PG8_SA(0, 0), a2, voffA);
.Lprio_skip_1037:
.LBB0_1037:
	ds_read_b128 v[64:67], v183
	ds_read_b128 v[68:71], v183 offset:1024
	ds_read_b128 v[72:75], v183 offset:2048
	ds_read_b128 v[76:79], v183 offset:3072
	ds_read_b128 v[144:147], v184
	ds_read_b128 v[160:163], v184 offset:1024
	ds_read_b128 v[164:167], v184 offset:2048
	ds_read_b128 v[168:171], v184 offset:3072
	s_add_u32 s42, s36, 0xfff80080
	s_addc_u32 s43, s37, -1
	s_cmp_eq_u32 s57, 28
	s_cselect_b32 s45, s27, s43
	s_cselect_b32 s44, s26, s42
	s_cselect_b32 s43, s29, s56
	s_cselect_b32 s42, s28, s25
	v_lshl_add_u64 v[216:217], s[36:37], 0, v[156:157]
	s_add_i32 m0, s33, 0xc000
	ds_read_b128 v[172:175], v185
	ds_read_b128 v[188:191], v185 offset:1024
	ds_read_b128 v[192:195], v185 offset:2048
	ds_read_b128 v[196:199], v185 offset:3072
	ds_read_b128 v[200:203], v185 offset:4096
	ds_read_b128 v[204:207], v185 offset:5120
	ds_read_b128 v[208:211], v185 offset:6144
	ds_read_b128 v[212:215], v185 offset:7168
	global_load_lds_dwordx4 v[216:217], off
	v_lshl_add_u64 v[216:217], s[36:37], 0, v[158:159]
	s_add_i32 m0, s33, 0xe000
	s_nop 0
	global_load_lds_dwordx4 v[216:217], off
	s_waitcnt vmcnt(8)
	s_waitcnt lgkmcnt(0)
	s_barrier
	s_waitcnt lgkmcnt(0)
	v_mfma_f32_16x16x32_bf16 v[140:143], v[64:67], v[172:175], v[140:143]
	v_mfma_f32_16x16x32_bf16 v[136:139], v[72:75], v[172:175], v[136:139]
	v_mfma_f32_16x16x32_bf16 v[124:127], v[64:67], v[192:195], v[124:127]
	v_mfma_f32_16x16x32_bf16 v[120:123], v[72:75], v[192:195], v[120:123]
	v_mfma_f32_16x16x32_bf16 v[108:111], v[64:67], v[200:203], v[108:111]
	v_mfma_f32_16x16x32_bf16 v[104:107], v[72:75], v[200:203], v[104:107]
	v_mfma_f32_16x16x32_bf16 v[92:95], v[64:67], v[208:211], v[92:95]
	v_mfma_f32_16x16x32_bf16 v[88:91], v[72:75], v[208:211], v[88:91]
	v_mfma_f32_16x16x32_bf16 v[140:143], v[68:71], v[188:191], v[140:143]
	v_mfma_f32_16x16x32_bf16 v[136:139], v[76:79], v[188:191], v[136:139]
	v_mfma_f32_16x16x32_bf16 v[124:127], v[68:71], v[196:199], v[124:127]
	v_mfma_f32_16x16x32_bf16 v[120:123], v[76:79], v[196:199], v[120:123]
	v_mfma_f32_16x16x32_bf16 v[108:111], v[68:71], v[204:207], v[108:111]
	v_mfma_f32_16x16x32_bf16 v[104:107], v[76:79], v[204:207], v[104:107]
	v_mfma_f32_16x16x32_bf16 v[92:95], v[68:71], v[212:215], v[92:95]
	v_mfma_f32_16x16x32_bf16 v[88:91], v[76:79], v[212:215], v[88:91]
	v_mfma_f32_16x16x32_bf16 v[132:135], v[144:147], v[172:175], v[132:135]
	v_mfma_f32_16x16x32_bf16 v[128:131], v[164:167], v[172:175], v[128:131]
	v_mfma_f32_16x16x32_bf16 v[116:119], v[144:147], v[192:195], v[116:119]
	v_mfma_f32_16x16x32_bf16 v[112:115], v[164:167], v[192:195], v[112:115]
	v_mfma_f32_16x16x32_bf16 v[100:103], v[144:147], v[200:203], v[100:103]
	v_mfma_f32_16x16x32_bf16 v[96:99], v[164:167], v[200:203], v[96:99]
	v_mfma_f32_16x16x32_bf16 v[84:87], v[144:147], v[208:211], v[84:87]
	v_mfma_f32_16x16x32_bf16 v[80:83], v[164:167], v[208:211], v[80:83]
	v_mfma_f32_16x16x32_bf16 v[132:135], v[160:163], v[188:191], v[132:135]
	v_mfma_f32_16x16x32_bf16 v[128:131], v[168:171], v[188:191], v[128:131]
	v_mfma_f32_16x16x32_bf16 v[116:119], v[160:163], v[196:199], v[116:119]
	v_mfma_f32_16x16x32_bf16 v[112:115], v[168:171], v[196:199], v[112:115]
	v_mfma_f32_16x16x32_bf16 v[100:103], v[160:163], v[204:207], v[100:103]
	v_mfma_f32_16x16x32_bf16 v[96:99], v[168:171], v[204:207], v[96:99]
	v_mfma_f32_16x16x32_bf16 v[84:87], v[160:163], v[212:215], v[84:87]
	v_mfma_f32_16x16x32_bf16 v[80:83], v[168:171], v[212:215], v[80:83]
	s_barrier
	s_add_i32 s58, s51, s21
	v_lshl_add_u64 v[216:217], s[42:43], 0, v[150:151]
	s_mov_b32 m0, s58
	ds_read_b128 v[172:175], v185 offset:16384
	ds_read_b128 v[188:191], v185 offset:17408
	ds_read_b128 v[192:195], v185 offset:18432
	ds_read_b128 v[196:199], v185 offset:19456
	ds_read_b128 v[200:203], v185 offset:20480
	ds_read_b128 v[204:207], v185 offset:21504
	ds_read_b128 v[208:211], v185 offset:22528
	ds_read_b128 v[212:215], v185 offset:23552
	global_load_lds_dwordx4 v[216:217], off
	s_add_i32 m0, s58, 0x2000
	s_add_u32 s58, s42, 0x80000
	v_lshl_add_u64 v[218:219], s[42:43], 0, v[154:155]
	s_addc_u32 s59, s43, 0
	s_add_i32 s60, s52, s21
	global_load_lds_dwordx4 v[218:219], off
	v_lshl_add_u64 v[220:221], s[58:59], 0, v[150:151]
	s_mov_b32 m0, s60
	v_lshl_add_u64 v[222:223], s[44:45], 0, v[152:153]
	global_load_lds_dwordx4 v[220:221], off
	v_lshl_add_u64 v[220:221], s[58:59], 0, v[154:155]
	s_add_i32 m0, s60, 0x2000
	s_nop 0
	global_load_lds_dwordx4 v[220:221], off
	v_lshl_add_u64 v[220:221], s[44:45], 0, v[148:149]
	s_mov_b32 m0, s33
	s_nop 0
	global_load_lds_dwordx4 v[220:221], off
	s_mov_b32 m0, s35
	s_nop 0
	global_load_lds_dwordx4 v[222:223], off
	s_waitcnt vmcnt(8)
	s_waitcnt lgkmcnt(0)
	s_barrier
; #define PG8_STAGE(bufoff, gbase, voff) do { _Pragma("unroll") for (int _i = 0; _i < 2; ++_i) \
;         __builtin_amdgcn_global_load_lds((const unsigned*)((const char*)(gbase) + (voff)[_i]), (LAS unsigned*)(lds + (bufoff) + ldsw + _i * 8192), 16, 0, 0); } while (0)
; #define PG8_LDA(dst, b, h) do { _Pragma("unroll") for (int m = 0; m < 4; ++m) _Pragma("unroll") for (int k = 0; k < 2; ++k) dst[m][k] = *(const LAS bf16x8*)(lds + PG8_SA(b, h) + aoff + m * 2048 + k * 1024); } while (0)
; #define PG8_LDB(dst, b, h) do { _Pragma("unroll") for (int n = 0; n < 2; ++n) _Pragma("unroll") for (int k = 0; k < 2; ++k) dst[n][k] = *(const LAS bf16x8*)(lds + PG8_SB(b, h) + boff + n * 2048 + k * 1024); } while (0)
; #define PG8_MMA(ai, bj, At, Bt) do { __builtin_amdgcn_s_setprio(1); _Pragma("unroll") for (int m = 0; m < 4; ++m) _Pragma("unroll") for (int n = 0; n < 2; ++n) _Pragma("unroll") for (int k = 0; k < 2; ++k) \
;         acc[ai][bj][m][n] = __builtin_amdgcn_mfma_f32_16x16x32_bf16(Bt[n][k], At[m][k], acc[ai][bj][m][n], 0, 0, 0); __builtin_amdgcn_s_setprio(0); } while (0)
; #define PG8_WAIT_V(n) asm volatile("s_waitcnt vmcnt(" #n ")" ::: "memory")
; #define PG8_WAIT_L(n) asm volatile("s_waitcnt lgkmcnt(" #n ")" ::: "memory")
; #define PG8_BAR __builtin_amdgcn_s_barrier()
; #define PG8_SCHED __builtin_amdgcn_sched_barrier(0)
; template <class Sched, class Epi, bool ALIGN_EPI, bool SP2>
; __device__ __forceinline__ void gemm_phase(LAS unsigned char* lds, const int K, const int lda, const int ldb, const Sched& S, const Epi& E) {
;     ...
;             PG8_WAIT_V(8); PG8_WAIT_L(0); PG8_BAR; PG8_MMA(1, 0, At, B0); PG8_MMA(1, 1, At, B1); PG8_BAR; PG8_SCHED;
;             PG8_LDB(B0, 1, 0); PG8_LDB(B1, 1, 1); PG8_SCHED; PG8_LDA(At, 1, 0); PG8_STAGE(PG8_SA(0, 1), a2 + hstepA, voffA);
;             PG8_WAIT_V(8); PG8_WAIT_L(0); PG8_BAR; PG8_MMA(0, 0, At, B0); PG8_MMA(0, 1, At, B1); PG8_BAR; PG8_SCHED;
	s_waitcnt lgkmcnt(0)
	v_mfma_f32_16x16x32_bf16 v[60:63], v[64:67], v[172:175], v[60:63]
	v_mfma_f32_16x16x32_bf16 v[56:59], v[72:75], v[172:175], v[56:59]
	v_mfma_f32_16x16x32_bf16 v[44:47], v[64:67], v[192:195], v[44:47]
	v_mfma_f32_16x16x32_bf16 v[40:43], v[72:75], v[192:195], v[40:43]
	v_mfma_f32_16x16x32_bf16 v[24:27], v[64:67], v[200:203], v[24:27]
	v_mfma_f32_16x16x32_bf16 v[20:23], v[72:75], v[200:203], v[20:23]
	v_mfma_f32_16x16x32_bf16 v[8:11], v[64:67], v[208:211], v[8:11]
	v_mfma_f32_16x16x32_bf16 v[0:3], v[72:75], v[208:211], v[0:3]
	v_mfma_f32_16x16x32_bf16 v[60:63], v[68:71], v[188:191], v[60:63]
	v_mfma_f32_16x16x32_bf16 v[56:59], v[76:79], v[188:191], v[56:59]
	v_mfma_f32_16x16x32_bf16 v[44:47], v[68:71], v[196:199], v[44:47]
	v_mfma_f32_16x16x32_bf16 v[40:43], v[76:79], v[196:199], v[40:43]
	v_mfma_f32_16x16x32_bf16 v[24:27], v[68:71], v[204:207], v[24:27]
	v_mfma_f32_16x16x32_bf16 v[20:23], v[76:79], v[204:207], v[20:23]
	v_mfma_f32_16x16x32_bf16 v[8:11], v[68:71], v[212:215], v[8:11]
	v_mfma_f32_16x16x32_bf16 v[0:3], v[76:79], v[212:215], v[0:3]
	v_mfma_f32_16x16x32_bf16 v[52:55], v[144:147], v[172:175], v[52:55]
	v_mfma_f32_16x16x32_bf16 v[48:51], v[164:167], v[172:175], v[48:51]
	v_mfma_f32_16x16x32_bf16 v[36:39], v[144:147], v[192:195], v[36:39]
	v_mfma_f32_16x16x32_bf16 v[32:35], v[164:167], v[192:195], v[32:35]
	v_mfma_f32_16x16x32_bf16 v[28:31], v[144:147], v[200:203], v[28:31]
	v_mfma_f32_16x16x32_bf16 v[16:19], v[164:167], v[200:203], v[16:19]
	v_mfma_f32_16x16x32_bf16 v[12:15], v[144:147], v[208:211], v[12:15]
	v_mfma_f32_16x16x32_bf16 v[4:7], v[164:167], v[208:211], v[4:7]
	v_mfma_f32_16x16x32_bf16 v[52:55], v[160:163], v[188:191], v[52:55]
	v_mfma_f32_16x16x32_bf16 v[48:51], v[168:171], v[188:191], v[48:51]
	v_mfma_f32_16x16x32_bf16 v[36:39], v[160:163], v[196:199], v[36:39]
	v_mfma_f32_16x16x32_bf16 v[32:35], v[168:171], v[196:199], v[32:35]
	v_mfma_f32_16x16x32_bf16 v[28:31], v[160:163], v[204:207], v[28:31]
	v_mfma_f32_16x16x32_bf16 v[16:19], v[168:171], v[204:207], v[16:19]
	v_mfma_f32_16x16x32_bf16 v[12:15], v[160:163], v[212:215], v[12:15]
	v_mfma_f32_16x16x32_bf16 v[4:7], v[168:171], v[212:215], v[4:7]
	s_barrier
	s_add_i32 s58, 0, 0x18000
	s_add_i32 s59, 0, 0x1c000
	v_add_u32_e32 v76, s58, v181
	v_add_u32_e32 v168, s59, v181
	ds_read_b128 v[64:67], v76
	ds_read_b128 v[68:71], v76 offset:1024
	ds_read_b128 v[72:75], v76 offset:2048
	ds_read_b128 v[76:79], v76 offset:3072
	ds_read_b128 v[144:147], v168
	ds_read_b128 v[160:163], v168 offset:1024
	ds_read_b128 v[164:167], v168 offset:2048
	ds_read_b128 v[168:171], v168 offset:3072
	s_add_u32 s44, s44, 0x80000
	s_addc_u32 s45, s45, 0
	s_mov_b32 m0, s46
	v_lshl_add_u64 v[224:225], s[44:45], 0, v[148:149]
	ds_read_b128 v[172:175], v185 offset:32768
	ds_read_b128 v[188:191], v185 offset:33792
	ds_read_b128 v[192:195], v185 offset:34816
	ds_read_b128 v[196:199], v185 offset:35840
	ds_read_b128 v[200:203], v185 offset:36864
	ds_read_b128 v[204:207], v185 offset:37888
	ds_read_b128 v[208:211], v185 offset:38912
	ds_read_b128 v[212:215], v185 offset:39936
	global_load_lds_dwordx4 v[224:225], off
	v_lshl_add_u64 v[224:225], s[44:45], 0, v[152:153]
	s_mov_b32 m0, s47
	s_nop 0
	global_load_lds_dwordx4 v[224:225], off
	s_waitcnt vmcnt(8)
	s_waitcnt lgkmcnt(0)
	s_barrier
	s_waitcnt lgkmcnt(0)
	v_mfma_f32_16x16x32_bf16 v[140:143], v[64:67], v[172:175], v[140:143]
	v_mfma_f32_16x16x32_bf16 v[136:139], v[72:75], v[172:175], v[136:139]
	v_mfma_f32_16x16x32_bf16 v[124:127], v[64:67], v[192:195], v[124:127]
	v_mfma_f32_16x16x32_bf16 v[120:123], v[72:75], v[192:195], v[120:123]
	v_mfma_f32_16x16x32_bf16 v[108:111], v[64:67], v[200:203], v[108:111]
	v_mfma_f32_16x16x32_bf16 v[104:107], v[72:75], v[200:203], v[104:107]
	v_mfma_f32_16x16x32_bf16 v[92:95], v[64:67], v[208:211], v[92:95]
	v_mfma_f32_16x16x32_bf16 v[88:91], v[72:75], v[208:211], v[88:91]
	v_mfma_f32_16x16x32_bf16 v[140:143], v[68:71], v[188:191], v[140:143]
	v_mfma_f32_16x16x32_bf16 v[136:139], v[76:79], v[188:191], v[136:139]
	v_mfma_f32_16x16x32_bf16 v[124:127], v[68:71], v[196:199], v[124:127]
	v_mfma_f32_16x16x32_bf16 v[120:123], v[76:79], v[196:199], v[120:123]
	v_mfma_f32_16x16x32_bf16 v[108:111], v[68:71], v[204:207], v[108:111]
	v_mfma_f32_16x16x32_bf16 v[104:107], v[76:79], v[204:207], v[104:107]
	v_mfma_f32_16x16x32_bf16 v[92:95], v[68:71], v[212:215], v[92:95]
	v_mfma_f32_16x16x32_bf16 v[88:91], v[76:79], v[212:215], v[88:91]
	v_mfma_f32_16x16x32_bf16 v[132:135], v[144:147], v[172:175], v[132:135]
	v_mfma_f32_16x16x32_bf16 v[128:131], v[164:167], v[172:175], v[128:131]
	v_mfma_f32_16x16x32_bf16 v[116:119], v[144:147], v[192:195], v[116:119]
	v_mfma_f32_16x16x32_bf16 v[112:115], v[164:167], v[192:195], v[112:115]
	v_mfma_f32_16x16x32_bf16 v[100:103], v[144:147], v[200:203], v[100:103]
	v_mfma_f32_16x16x32_bf16 v[96:99], v[164:167], v[200:203], v[96:99]
	v_mfma_f32_16x16x32_bf16 v[84:87], v[144:147], v[208:211], v[84:87]
	v_mfma_f32_16x16x32_bf16 v[80:83], v[164:167], v[208:211], v[80:83]
	v_mfma_f32_16x16x32_bf16 v[132:135], v[160:163], v[188:191], v[132:135]
	v_mfma_f32_16x16x32_bf16 v[128:131], v[168:171], v[188:191], v[128:131]
	v_mfma_f32_16x16x32_bf16 v[116:119], v[160:163], v[196:199], v[116:119]
	v_mfma_f32_16x16x32_bf16 v[112:115], v[168:171], v[196:199], v[112:115]
	v_mfma_f32_16x16x32_bf16 v[100:103], v[160:163], v[204:207], v[100:103]
	v_mfma_f32_16x16x32_bf16 v[96:99], v[168:171], v[204:207], v[96:99]
	v_mfma_f32_16x16x32_bf16 v[84:87], v[160:163], v[212:215], v[84:87]
	v_mfma_f32_16x16x32_bf16 v[80:83], v[168:171], v[212:215], v[80:83]
	s_barrier
; #define PG8_STAGE(bufoff, gbase, voff) do { _Pragma("unroll") for (int _i = 0; _i < 2; ++_i) \
;         __builtin_amdgcn_global_load_lds((const unsigned*)((const char*)(gbase) + (voff)[_i]), (LAS unsigned*)(lds + (bufoff) + ldsw + _i * 8192), 16, 0, 0); } while (0)
; #define PG8_LDA(dst, b, h) do { _Pragma("unroll") for (int m = 0; m < 4; ++m) _Pragma("unroll") for (int k = 0; k < 2; ++k) dst[m][k] = *(const LAS bf16x8*)(lds + PG8_SA(b, h) + aoff + m * 2048 + k * 1024); } while (0)
; #define PG8_MMA(ai, bj, At, Bt) do { __builtin_amdgcn_s_setprio(1); _Pragma("unroll") for (int m = 0; m < 4; ++m) _Pragma("unroll") for (int n = 0; n < 2; ++n) _Pragma("unroll") for (int k = 0; k < 2; ++k) \
;         acc[ai][bj][m][n] = __builtin_amdgcn_mfma_f32_16x16x32_bf16(Bt[n][k], At[m][k], acc[ai][bj][m][n], 0, 0, 0); __builtin_amdgcn_s_setprio(0); } while (0)
; #define PG8_WAIT_V(n) asm volatile("s_waitcnt vmcnt(" #n ")" ::: "memory")
; #define PG8_WAIT_L(n) asm volatile("s_waitcnt lgkmcnt(" #n ")" ::: "memory")
; #define PG8_BAR __builtin_amdgcn_s_barrier()
; #define PG8_SCHED __builtin_amdgcn_sched_barrier(0)
; template <class Sched, class Epi, bool ALIGN_EPI, bool SP2>
; __device__ __forceinline__ void gemm_phase(LAS unsigned char* lds, const int K, const int lda, const int ldb, const Sched& S, const Epi& E) {
;     ...
;             PG8_LDA(At, 1, 1); PG8_STAGE(PG8_SB(1, 0), b3, voffB); PG8_STAGE(PG8_SB(1, 1), b3 + hstepB, voffB); PG8_STAGE(PG8_SA(1, 0), a3, voffA);
;             PG8_WAIT_V(8); PG8_WAIT_L(0); PG8_BAR; PG8_MMA(1, 0, At, B0); PG8_MMA(1, 1, At, B1); PG8_BAR; PG8_SCHED;
;     ...
;         }
;         if constexpr (ALIGN_EPI) { if (wr == 0) PG8_BAR; }
	s_add_i32 s44, s58, s21
	v_lshl_add_u64 v[216:217], v[216:217], 0, s[14:15]
	s_mov_b32 m0, s44
	ds_read_b128 v[172:175], v185 offset:49152
	ds_read_b128 v[188:191], v185 offset:50176
	ds_read_b128 v[192:195], v185 offset:51200
	ds_read_b128 v[196:199], v185 offset:52224
	ds_read_b128 v[200:203], v185 offset:53248
	ds_read_b128 v[204:207], v185 offset:54272
	ds_read_b128 v[208:211], v185 offset:55296
	ds_read_b128 v[212:215], v185 offset:56320
	global_load_lds_dwordx4 v[216:217], off
	s_add_i32 m0, s44, 0x2000
	s_add_u32 s42, s42, 0x80080
	v_lshl_add_u64 v[216:217], v[218:219], 0, s[14:15]
	s_addc_u32 s43, s43, 0
	s_add_i32 s44, s59, s21
	global_load_lds_dwordx4 v[216:217], off
	v_lshl_add_u64 v[216:217], s[42:43], 0, v[150:151]
	s_mov_b32 m0, s44
	s_nop 0
	global_load_lds_dwordx4 v[216:217], off
	v_lshl_add_u64 v[216:217], s[42:43], 0, v[154:155]
	s_add_i32 m0, s44, 0x2000
	s_nop 0
	global_load_lds_dwordx4 v[216:217], off
	v_lshl_add_u64 v[216:217], v[220:221], 0, s[14:15]
	s_mov_b32 m0, s49
	s_nop 0
	global_load_lds_dwordx4 v[216:217], off
	v_lshl_add_u64 v[216:217], v[222:223], 0, s[14:15]
	s_mov_b32 m0, s50
	s_nop 0
	global_load_lds_dwordx4 v[216:217], off
	s_waitcnt vmcnt(8)
	s_waitcnt lgkmcnt(0)
	s_barrier
	s_waitcnt lgkmcnt(0)
	v_mfma_f32_16x16x32_bf16 v[60:63], v[64:67], v[172:175], v[60:63]
	v_mfma_f32_16x16x32_bf16 v[56:59], v[72:75], v[172:175], v[56:59]
	v_mfma_f32_16x16x32_bf16 v[44:47], v[64:67], v[192:195], v[44:47]
	v_mfma_f32_16x16x32_bf16 v[40:43], v[72:75], v[192:195], v[40:43]
	v_mfma_f32_16x16x32_bf16 v[24:27], v[64:67], v[200:203], v[24:27]
	v_mfma_f32_16x16x32_bf16 v[20:23], v[72:75], v[200:203], v[20:23]
	v_mfma_f32_16x16x32_bf16 v[8:11], v[64:67], v[208:211], v[8:11]
	v_mfma_f32_16x16x32_bf16 v[0:3], v[72:75], v[208:211], v[0:3]
	v_mfma_f32_16x16x32_bf16 v[60:63], v[68:71], v[188:191], v[60:63]
	v_mfma_f32_16x16x32_bf16 v[56:59], v[76:79], v[188:191], v[56:59]
	v_mfma_f32_16x16x32_bf16 v[44:47], v[68:71], v[196:199], v[44:47]
	v_mfma_f32_16x16x32_bf16 v[40:43], v[76:79], v[196:199], v[40:43]
	v_mfma_f32_16x16x32_bf16 v[24:27], v[68:71], v[204:207], v[24:27]
	v_mfma_f32_16x16x32_bf16 v[20:23], v[76:79], v[204:207], v[20:23]
	v_mfma_f32_16x16x32_bf16 v[8:11], v[68:71], v[212:215], v[8:11]
	v_mfma_f32_16x16x32_bf16 v[0:3], v[76:79], v[212:215], v[0:3]
	v_mfma_f32_16x16x32_bf16 v[52:55], v[144:147], v[172:175], v[52:55]
	v_mfma_f32_16x16x32_bf16 v[48:51], v[164:167], v[172:175], v[48:51]
	v_mfma_f32_16x16x32_bf16 v[36:39], v[144:147], v[192:195], v[36:39]
	v_mfma_f32_16x16x32_bf16 v[32:35], v[164:167], v[192:195], v[32:35]
	v_mfma_f32_16x16x32_bf16 v[28:31], v[144:147], v[200:203], v[28:31]
	v_mfma_f32_16x16x32_bf16 v[16:19], v[164:167], v[200:203], v[16:19]
	v_mfma_f32_16x16x32_bf16 v[12:15], v[144:147], v[208:211], v[12:15]
	v_mfma_f32_16x16x32_bf16 v[4:7], v[164:167], v[208:211], v[4:7]
	v_mfma_f32_16x16x32_bf16 v[52:55], v[160:163], v[188:191], v[52:55]
	v_mfma_f32_16x16x32_bf16 v[48:51], v[168:171], v[188:191], v[48:51]
	v_mfma_f32_16x16x32_bf16 v[36:39], v[160:163], v[196:199], v[36:39]
	v_mfma_f32_16x16x32_bf16 v[32:35], v[168:171], v[196:199], v[32:35]
	v_mfma_f32_16x16x32_bf16 v[28:31], v[160:163], v[204:207], v[28:31]
	v_mfma_f32_16x16x32_bf16 v[16:19], v[168:171], v[204:207], v[16:19]
	v_mfma_f32_16x16x32_bf16 v[12:15], v[160:163], v[212:215], v[12:15]
	v_mfma_f32_16x16x32_bf16 v[4:7], v[168:171], v[212:215], v[4:7]
	s_barrier
	s_add_i32 s57, s57, 2
	s_add_u32 s36, s36, 0x100
	s_addc_u32 s37, s37, 0
	s_add_u32 s25, s25, 0x100
	s_addc_u32 s56, s56, 0
	s_cmp_gt_u32 s57, 29
	s_cbranch_scc0 .LBB0_1037
	s_and_b64 vcc, exec, s[16:17]
	s_mov_b32 s56, s62
	s_cbranch_vccz .LBB0_1040
	s_barrier

; #define PG8_STAGE(bufoff, gbase, voff) do { _Pragma("unroll") for (int _i = 0; _i < 2; ++_i) \
;         __builtin_amdgcn_global_load_lds((const unsigned*)((const char*)(gbase) + (voff)[_i]), (LAS unsigned*)(lds + (bufoff) + ldsw + _i * 8192), 16, 0, 0); } while (0)
; #define PG8_LDA(dst, b, h) do { _Pragma("unroll") for (int m = 0; m < 4; ++m) _Pragma("unroll") for (int k = 0; k < 2; ++k) dst[m][k] = *(const LAS bf16x8*)(lds + PG8_SA(b, h) + aoff + m * 2048 + k * 1024); } while (0)
; #define PG8_LDB(dst, b, h) do { _Pragma("unroll") for (int n = 0; n < 2; ++n) _Pragma("unroll") for (int k = 0; k < 2; ++k) dst[n][k] = *(const LAS bf16x8*)(lds + PG8_SB(b, h) + boff + n * 2048 + k * 1024); } while (0)
; #define PG8_MMA(ai, bj, At, Bt) do { __builtin_amdgcn_s_setprio(1); _Pragma("unroll") for (int m = 0; m < 4; ++m) _Pragma("unroll") for (int n = 0; n < 2; ++n) _Pragma("unroll") for (int k = 0; k < 2; ++k) \
;         acc[ai][bj][m][n] = __builtin_amdgcn_mfma_f32_16x16x32_bf16(Bt[n][k], At[m][k], acc[ai][bj][m][n], 0, 0, 0); __builtin_amdgcn_s_setprio(0); } while (0)
; #define PG8_WAIT_V(n) asm volatile("s_waitcnt vmcnt(" #n ")" ::: "memory")
; #define PG8_WAIT_L(n) asm volatile("s_waitcnt lgkmcnt(" #n ")" ::: "memory")
; #define PG8_BAR __builtin_amdgcn_s_barrier()
; #define PG8_SCHED __builtin_amdgcn_sched_barrier(0)
; template <class Sched, class Epi, bool ALIGN_EPI, bool SP2>
; __device__ __forceinline__ void gemm_phase(LAS unsigned char* lds, const int K, const int lda, const int ldb, const Sched& S, const Epi& E) {
;     ...
;             const bool last = (t == nt - 2);
;             const char* a1 = cA + (size_t)(t + 1) * kstep;
;             const char* a2 = last ? nA : cA + (size_t)(t + 2) * kstep; const char* b2 = last ? nB : cB + (size_t)(t + 2) * kstep;
;             const char* a3 = a2 + kstep; const char* b3 = b2 + kstep;
;             if constexpr (SP2) {
;             PG8_LDB(B0, 0, 0); PG8_LDB(B1, 0, 1); PG8_SCHED; PG8_LDA(At, 0, 0); PG8_STAGE(PG8_SA(1, 1), a1 + hstepA, voffA);
;             PG8_WAIT_V(8); PG8_WAIT_L(0); PG8_BAR; PG8_MMA(0, 0, At, B0); PG8_MMA(0, 1, At, B1); PG8_BAR; PG8_SCHED;
;             PG8_LDA(At, 0, 1); PG8_STAGE(PG8_SB(0, 0), b2, voffB); PG8_STAGE(PG8_SB(0, 1), b2 + hstepB, voffB); PG8_STAGE(PG8_SA(0, 0), a2, voffA);
.Lprio_skip_1120:
.LBB0_1120:
	ds_read_b128 v[96:99], v178
	ds_read_b128 v[100:103], v178 offset:1024
	ds_read_b128 v[104:107], v178 offset:2048
	ds_read_b128 v[108:111], v178 offset:3072
	ds_read_b128 v[112:115], v180
	ds_read_b128 v[116:119], v180 offset:1024
	ds_read_b128 v[120:123], v180 offset:2048
	ds_read_b128 v[124:127], v180 offset:3072
	s_add_u32 s4, s0, 0x100
	s_addc_u32 s5, s1, 0
	s_cmpk_eq_i32 s51, 0x54
	s_cselect_b32 s27, s21, s5
	s_cselect_b32 s26, s20, s4
	s_cselect_b32 s25, s23, s50
	s_cselect_b32 s24, s22, s49
	v_lshl_add_u64 v[172:173], s[0:1], 0, v[164:165]
	s_add_i32 m0, s17, 0xc000
	ds_read_b128 v[168:171], v181
	ds_read_b128 v[184:187], v181 offset:1024
	ds_read_b128 v[188:191], v181 offset:2048
	ds_read_b128 v[192:195], v181 offset:3072
	ds_read_b128 v[196:199], v181 offset:4096
	ds_read_b128 v[200:203], v181 offset:5120
	ds_read_b128 v[204:207], v181 offset:6144
	ds_read_b128 v[208:211], v181 offset:7168
	global_load_lds_dwordx4 v[172:173], off
	v_lshl_add_u64 v[172:173], s[0:1], 0, v[166:167]
	s_add_i32 m0, s17, 0xe000
	s_nop 0
	global_load_lds_dwordx4 v[172:173], off
	s_waitcnt vmcnt(8)
	s_waitcnt lgkmcnt(0)
	s_barrier
	s_waitcnt lgkmcnt(0)
	v_mfma_f32_16x16x32_bf16 v[156:159], v[96:99], v[168:171], v[156:159]
	v_mfma_f32_16x16x32_bf16 v[152:155], v[104:107], v[168:171], v[152:155]
	v_mfma_f32_16x16x32_bf16 v[144:147], v[96:99], v[188:191], v[144:147]
	v_mfma_f32_16x16x32_bf16 v[136:139], v[104:107], v[188:191], v[136:139]
	v_mfma_f32_16x16x32_bf16 v[92:95], v[96:99], v[196:199], v[92:95]
	v_mfma_f32_16x16x32_bf16 v[88:91], v[104:107], v[196:199], v[88:91]
	v_mfma_f32_16x16x32_bf16 v[80:83], v[96:99], v[204:207], v[80:83]
	v_mfma_f32_16x16x32_bf16 v[72:75], v[104:107], v[204:207], v[72:75]
	v_mfma_f32_16x16x32_bf16 v[156:159], v[100:103], v[184:187], v[156:159]
	v_mfma_f32_16x16x32_bf16 v[152:155], v[108:111], v[184:187], v[152:155]
	v_mfma_f32_16x16x32_bf16 v[144:147], v[100:103], v[192:195], v[144:147]
	v_mfma_f32_16x16x32_bf16 v[136:139], v[108:111], v[192:195], v[136:139]
	v_mfma_f32_16x16x32_bf16 v[92:95], v[100:103], v[200:203], v[92:95]
	v_mfma_f32_16x16x32_bf16 v[88:91], v[108:111], v[200:203], v[88:91]
	v_mfma_f32_16x16x32_bf16 v[80:83], v[100:103], v[208:211], v[80:83]
	v_mfma_f32_16x16x32_bf16 v[72:75], v[108:111], v[208:211], v[72:75]
	v_mfma_f32_16x16x32_bf16 v[148:151], v[112:115], v[168:171], v[148:151]
	v_mfma_f32_16x16x32_bf16 v[140:143], v[120:123], v[168:171], v[140:143]
	v_mfma_f32_16x16x32_bf16 v[132:135], v[112:115], v[188:191], v[132:135]
	v_mfma_f32_16x16x32_bf16 v[128:131], v[120:123], v[188:191], v[128:131]
	v_mfma_f32_16x16x32_bf16 v[84:87], v[112:115], v[196:199], v[84:87]
	v_mfma_f32_16x16x32_bf16 v[76:79], v[120:123], v[196:199], v[76:79]
	v_mfma_f32_16x16x32_bf16 v[68:71], v[112:115], v[204:207], v[68:71]
	v_mfma_f32_16x16x32_bf16 v[64:67], v[120:123], v[204:207], v[64:67]
	v_mfma_f32_16x16x32_bf16 v[148:151], v[116:119], v[184:187], v[148:151]
	v_mfma_f32_16x16x32_bf16 v[140:143], v[124:127], v[184:187], v[140:143]
	v_mfma_f32_16x16x32_bf16 v[132:135], v[116:119], v[192:195], v[132:135]
	v_mfma_f32_16x16x32_bf16 v[128:131], v[124:127], v[192:195], v[128:131]
	v_mfma_f32_16x16x32_bf16 v[84:87], v[116:119], v[200:203], v[84:87]
	v_mfma_f32_16x16x32_bf16 v[76:79], v[124:127], v[200:203], v[76:79]
	v_mfma_f32_16x16x32_bf16 v[68:71], v[116:119], v[208:211], v[68:71]
	v_mfma_f32_16x16x32_bf16 v[64:67], v[124:127], v[208:211], v[64:67]
	s_barrier
	s_add_i32 s0, s42, s15
	v_lshl_add_u64 v[172:173], s[24:25], 0, v[160:161]
	s_mov_b32 m0, s0
	ds_read_b128 v[168:171], v181 offset:16384
	ds_read_b128 v[184:187], v181 offset:17408
	ds_read_b128 v[188:191], v181 offset:18432
	ds_read_b128 v[192:195], v181 offset:19456
	ds_read_b128 v[196:199], v181 offset:20480
	ds_read_b128 v[200:203], v181 offset:21504
	ds_read_b128 v[204:207], v181 offset:22528
	ds_read_b128 v[208:211], v181 offset:23552
	global_load_lds_dwordx4 v[172:173], off
	s_add_i32 m0, s0, 0x2000
	s_add_u32 s0, s24, 0x160000
	v_lshl_add_u64 v[212:213], s[24:25], 0, v[162:163]
	s_addc_u32 s1, s25, 0
	s_add_i32 s52, s43, s15
	global_load_lds_dwordx4 v[212:213], off
	v_lshl_add_u64 v[214:215], s[0:1], 0, v[160:161]
	s_mov_b32 m0, s52
	v_lshl_add_u64 v[216:217], s[26:27], 0, v[162:163]
	global_load_lds_dwordx4 v[214:215], off
	v_lshl_add_u64 v[214:215], s[0:1], 0, v[162:163]
	s_add_i32 m0, s52, 0x2000
	s_nop 0
	global_load_lds_dwordx4 v[214:215], off
	v_lshl_add_u64 v[214:215], s[26:27], 0, v[160:161]
	s_mov_b32 m0, s17
	s_nop 0
	global_load_lds_dwordx4 v[214:215], off
	s_mov_b32 m0, s28
	s_nop 0
	global_load_lds_dwordx4 v[216:217], off
	s_waitcnt vmcnt(8)
	s_waitcnt lgkmcnt(0)
	s_barrier
; #define PG8_STAGE(bufoff, gbase, voff) do { _Pragma("unroll") for (int _i = 0; _i < 2; ++_i) \
;         __builtin_amdgcn_global_load_lds((const unsigned*)((const char*)(gbase) + (voff)[_i]), (LAS unsigned*)(lds + (bufoff) + ldsw + _i * 8192), 16, 0, 0); } while (0)
; #define PG8_LDA(dst, b, h) do { _Pragma("unroll") for (int m = 0; m < 4; ++m) _Pragma("unroll") for (int k = 0; k < 2; ++k) dst[m][k] = *(const LAS bf16x8*)(lds + PG8_SA(b, h) + aoff + m * 2048 + k * 1024); } while (0)
; #define PG8_LDB(dst, b, h) do { _Pragma("unroll") for (int n = 0; n < 2; ++n) _Pragma("unroll") for (int k = 0; k < 2; ++k) dst[n][k] = *(const LAS bf16x8*)(lds + PG8_SB(b, h) + boff + n * 2048 + k * 1024); } while (0)
; #define PG8_MMA(ai, bj, At, Bt) do { __builtin_amdgcn_s_setprio(1); _Pragma("unroll") for (int m = 0; m < 4; ++m) _Pragma("unroll") for (int n = 0; n < 2; ++n) _Pragma("unroll") for (int k = 0; k < 2; ++k) \
;         acc[ai][bj][m][n] = __builtin_amdgcn_mfma_f32_16x16x32_bf16(Bt[n][k], At[m][k], acc[ai][bj][m][n], 0, 0, 0); __builtin_amdgcn_s_setprio(0); } while (0)
; #define PG8_WAIT_V(n) asm volatile("s_waitcnt vmcnt(" #n ")" ::: "memory")
; #define PG8_WAIT_L(n) asm volatile("s_waitcnt lgkmcnt(" #n ")" ::: "memory")
; #define PG8_BAR __builtin_amdgcn_s_barrier()
; #define PG8_SCHED __builtin_amdgcn_sched_barrier(0)
; template <class Sched, class Epi, bool ALIGN_EPI, bool SP2>
; __device__ __forceinline__ void gemm_phase(LAS unsigned char* lds, const int K, const int lda, const int ldb, const Sched& S, const Epi& E) {
;     ...
;             PG8_WAIT_V(8); PG8_WAIT_L(0); PG8_BAR; PG8_MMA(0, 0, At, B0); PG8_MMA(0, 1, At, B1); PG8_BAR; PG8_SCHED;
;             PG8_LDA(At, 0, 1); PG8_STAGE(PG8_SB(0, 0), b2, voffB); PG8_STAGE(PG8_SB(0, 1), b2 + hstepB, voffB); PG8_STAGE(PG8_SA(0, 0), a2, voffA);
;             PG8_WAIT_V(8); PG8_WAIT_L(0); PG8_BAR; PG8_MMA(1, 0, At, B0); PG8_MMA(1, 1, At, B1); PG8_BAR; PG8_SCHED;
;             PG8_LDB(B0, 1, 0); PG8_LDB(B1, 1, 1); PG8_SCHED; PG8_LDA(At, 1, 0); PG8_STAGE(PG8_SA(0, 1), a2 + hstepA, voffA);
;             PG8_WAIT_V(8); PG8_WAIT_L(0); PG8_BAR; PG8_MMA(0, 0, At, B0); PG8_MMA(0, 1, At, B1); PG8_BAR; PG8_SCHED;
	s_waitcnt lgkmcnt(0)
	v_mfma_f32_16x16x32_bf16 v[60:63], v[96:99], v[168:171], v[60:63]
	v_mfma_f32_16x16x32_bf16 v[56:59], v[104:107], v[168:171], v[56:59]
	v_mfma_f32_16x16x32_bf16 v[48:51], v[96:99], v[188:191], v[48:51]
	v_mfma_f32_16x16x32_bf16 v[40:43], v[104:107], v[188:191], v[40:43]
	v_mfma_f32_16x16x32_bf16 v[28:31], v[96:99], v[196:199], v[28:31]
	v_mfma_f32_16x16x32_bf16 v[24:27], v[104:107], v[196:199], v[24:27]
	v_mfma_f32_16x16x32_bf16 v[16:19], v[96:99], v[204:207], v[16:19]
	v_mfma_f32_16x16x32_bf16 v[8:11], v[104:107], v[204:207], v[8:11]
	v_mfma_f32_16x16x32_bf16 v[60:63], v[100:103], v[184:187], v[60:63]
	v_mfma_f32_16x16x32_bf16 v[56:59], v[108:111], v[184:187], v[56:59]
	v_mfma_f32_16x16x32_bf16 v[48:51], v[100:103], v[192:195], v[48:51]
	v_mfma_f32_16x16x32_bf16 v[40:43], v[108:111], v[192:195], v[40:43]
	v_mfma_f32_16x16x32_bf16 v[28:31], v[100:103], v[200:203], v[28:31]
	v_mfma_f32_16x16x32_bf16 v[24:27], v[108:111], v[200:203], v[24:27]
	v_mfma_f32_16x16x32_bf16 v[16:19], v[100:103], v[208:211], v[16:19]
	v_mfma_f32_16x16x32_bf16 v[8:11], v[108:111], v[208:211], v[8:11]
	v_mfma_f32_16x16x32_bf16 v[52:55], v[112:115], v[168:171], v[52:55]
	v_mfma_f32_16x16x32_bf16 v[44:47], v[120:123], v[168:171], v[44:47]
	v_mfma_f32_16x16x32_bf16 v[36:39], v[112:115], v[188:191], v[36:39]
	v_mfma_f32_16x16x32_bf16 v[32:35], v[120:123], v[188:191], v[32:35]
	v_mfma_f32_16x16x32_bf16 v[20:23], v[112:115], v[196:199], v[20:23]
	v_mfma_f32_16x16x32_bf16 v[12:15], v[120:123], v[196:199], v[12:15]
	v_mfma_f32_16x16x32_bf16 v[4:7], v[112:115], v[204:207], v[4:7]
	v_mfma_f32_16x16x32_bf16 v[0:3], v[120:123], v[204:207], v[0:3]
	v_mfma_f32_16x16x32_bf16 v[52:55], v[116:119], v[184:187], v[52:55]
	v_mfma_f32_16x16x32_bf16 v[44:47], v[124:127], v[184:187], v[44:47]
	v_mfma_f32_16x16x32_bf16 v[36:39], v[116:119], v[192:195], v[36:39]
	v_mfma_f32_16x16x32_bf16 v[32:35], v[124:127], v[192:195], v[32:35]
	v_mfma_f32_16x16x32_bf16 v[20:23], v[116:119], v[200:203], v[20:23]
	v_mfma_f32_16x16x32_bf16 v[12:15], v[124:127], v[200:203], v[12:15]
	v_mfma_f32_16x16x32_bf16 v[4:7], v[116:119], v[208:211], v[4:7]
	v_mfma_f32_16x16x32_bf16 v[0:3], v[124:127], v[208:211], v[0:3]
	s_barrier
	s_add_i32 s52, 0, 0x18000
	s_add_i32 s53, 0, 0x1c000
	v_add_u32_e32 v108, s52, v175
	v_add_u32_e32 v124, s53, v175
	ds_read_b128 v[96:99], v108
	ds_read_b128 v[100:103], v108 offset:1024
	ds_read_b128 v[104:107], v108 offset:2048
	ds_read_b128 v[108:111], v108 offset:3072
	ds_read_b128 v[112:115], v124
	ds_read_b128 v[116:119], v124 offset:1024
	ds_read_b128 v[120:123], v124 offset:2048
	ds_read_b128 v[124:127], v124 offset:3072
	s_add_u32 s0, s26, 0x160000
	s_addc_u32 s1, s27, 0
	s_mov_b32 m0, s29
	v_lshl_add_u64 v[218:219], s[0:1], 0, v[160:161]
	ds_read_b128 v[168:171], v181 offset:32768
	ds_read_b128 v[184:187], v181 offset:33792
	ds_read_b128 v[188:191], v181 offset:34816
	ds_read_b128 v[192:195], v181 offset:35840
	ds_read_b128 v[196:199], v181 offset:36864
	ds_read_b128 v[200:203], v181 offset:37888
	ds_read_b128 v[204:207], v181 offset:38912
	ds_read_b128 v[208:211], v181 offset:39936
	global_load_lds_dwordx4 v[218:219], off
	v_lshl_add_u64 v[218:219], s[0:1], 0, v[162:163]
	s_mov_b32 m0, s33
	s_nop 0
	global_load_lds_dwordx4 v[218:219], off
	s_waitcnt vmcnt(8)
	s_waitcnt lgkmcnt(0)
	s_barrier
	s_waitcnt lgkmcnt(0)
	v_mfma_f32_16x16x32_bf16 v[156:159], v[96:99], v[168:171], v[156:159]
	v_mfma_f32_16x16x32_bf16 v[152:155], v[104:107], v[168:171], v[152:155]
	v_mfma_f32_16x16x32_bf16 v[144:147], v[96:99], v[188:191], v[144:147]
	v_mfma_f32_16x16x32_bf16 v[136:139], v[104:107], v[188:191], v[136:139]
	v_mfma_f32_16x16x32_bf16 v[92:95], v[96:99], v[196:199], v[92:95]
	v_mfma_f32_16x16x32_bf16 v[88:91], v[104:107], v[196:199], v[88:91]
	v_mfma_f32_16x16x32_bf16 v[80:83], v[96:99], v[204:207], v[80:83]
	v_mfma_f32_16x16x32_bf16 v[72:75], v[104:107], v[204:207], v[72:75]
	v_mfma_f32_16x16x32_bf16 v[156:159], v[100:103], v[184:187], v[156:159]
	v_mfma_f32_16x16x32_bf16 v[152:155], v[108:111], v[184:187], v[152:155]
	v_mfma_f32_16x16x32_bf16 v[144:147], v[100:103], v[192:195], v[144:147]
	v_mfma_f32_16x16x32_bf16 v[136:139], v[108:111], v[192:195], v[136:139]
	v_mfma_f32_16x16x32_bf16 v[92:95], v[100:103], v[200:203], v[92:95]
	v_mfma_f32_16x16x32_bf16 v[88:91], v[108:111], v[200:203], v[88:91]
	v_mfma_f32_16x16x32_bf16 v[80:83], v[100:103], v[208:211], v[80:83]
	v_mfma_f32_16x16x32_bf16 v[72:75], v[108:111], v[208:211], v[72:75]
	v_mfma_f32_16x16x32_bf16 v[148:151], v[112:115], v[168:171], v[148:151]
	v_mfma_f32_16x16x32_bf16 v[140:143], v[120:123], v[168:171], v[140:143]
	v_mfma_f32_16x16x32_bf16 v[132:135], v[112:115], v[188:191], v[132:135]
	v_mfma_f32_16x16x32_bf16 v[128:131], v[120:123], v[188:191], v[128:131]
	v_mfma_f32_16x16x32_bf16 v[84:87], v[112:115], v[196:199], v[84:87]
	v_mfma_f32_16x16x32_bf16 v[76:79], v[120:123], v[196:199], v[76:79]
	v_mfma_f32_16x16x32_bf16 v[68:71], v[112:115], v[204:207], v[68:71]
	v_mfma_f32_16x16x32_bf16 v[64:67], v[120:123], v[204:207], v[64:67]
	v_mfma_f32_16x16x32_bf16 v[148:151], v[116:119], v[184:187], v[148:151]
	v_mfma_f32_16x16x32_bf16 v[140:143], v[124:127], v[184:187], v[140:143]
	v_mfma_f32_16x16x32_bf16 v[132:135], v[116:119], v[192:195], v[132:135]
	v_mfma_f32_16x16x32_bf16 v[128:131], v[124:127], v[192:195], v[128:131]
	v_mfma_f32_16x16x32_bf16 v[84:87], v[116:119], v[200:203], v[84:87]
	v_mfma_f32_16x16x32_bf16 v[76:79], v[124:127], v[200:203], v[76:79]
	v_mfma_f32_16x16x32_bf16 v[68:71], v[116:119], v[208:211], v[68:71]
	v_mfma_f32_16x16x32_bf16 v[64:67], v[124:127], v[208:211], v[64:67]
	s_barrier
; #define PG8_STAGE(bufoff, gbase, voff) do { _Pragma("unroll") for (int _i = 0; _i < 2; ++_i) \
;         __builtin_amdgcn_global_load_lds((const unsigned*)((const char*)(gbase) + (voff)[_i]), (LAS unsigned*)(lds + (bufoff) + ldsw + _i * 8192), 16, 0, 0); } while (0)
; #define PG8_LDA(dst, b, h) do { _Pragma("unroll") for (int m = 0; m < 4; ++m) _Pragma("unroll") for (int k = 0; k < 2; ++k) dst[m][k] = *(const LAS bf16x8*)(lds + PG8_SA(b, h) + aoff + m * 2048 + k * 1024); } while (0)
; #define PG8_MMA(ai, bj, At, Bt) do { __builtin_amdgcn_s_setprio(1); _Pragma("unroll") for (int m = 0; m < 4; ++m) _Pragma("unroll") for (int n = 0; n < 2; ++n) _Pragma("unroll") for (int k = 0; k < 2; ++k) \
;         acc[ai][bj][m][n] = __builtin_amdgcn_mfma_f32_16x16x32_bf16(Bt[n][k], At[m][k], acc[ai][bj][m][n], 0, 0, 0); __builtin_amdgcn_s_setprio(0); } while (0)
; #define PG8_WAIT_V(n) asm volatile("s_waitcnt vmcnt(" #n ")" ::: "memory")
; #define PG8_WAIT_L(n) asm volatile("s_waitcnt lgkmcnt(" #n ")" ::: "memory")
; #define PG8_BAR __builtin_amdgcn_s_barrier()
; #define PG8_SCHED __builtin_amdgcn_sched_barrier(0)
; template <class Sched, class Epi, bool ALIGN_EPI, bool SP2>
; __device__ __forceinline__ void gemm_phase(LAS unsigned char* lds, const int K, const int lda, const int ldb, const Sched& S, const Epi& E) {
;     ...
;             PG8_LDA(At, 1, 1); PG8_STAGE(PG8_SB(1, 0), b3, voffB); PG8_STAGE(PG8_SB(1, 1), b3 + hstepB, voffB); PG8_STAGE(PG8_SA(1, 0), a3, voffA);
;             PG8_WAIT_V(8); PG8_WAIT_L(0); PG8_BAR; PG8_MMA(1, 0, At, B0); PG8_MMA(1, 1, At, B1); PG8_BAR; PG8_SCHED;
	s_add_i32 s0, s52, s15
	v_lshl_add_u64 v[172:173], v[172:173], 0, s[10:11]
	s_mov_b32 m0, s0
	ds_read_b128 v[168:171], v181 offset:49152
	ds_read_b128 v[184:187], v181 offset:50176
	ds_read_b128 v[188:191], v181 offset:51200
	ds_read_b128 v[192:195], v181 offset:52224
	ds_read_b128 v[196:199], v181 offset:53248
	ds_read_b128 v[200:203], v181 offset:54272
	ds_read_b128 v[204:207], v181 offset:55296
	ds_read_b128 v[208:211], v181 offset:56320
	global_load_lds_dwordx4 v[172:173], off
	s_add_i32 m0, s0, 0x2000
	s_add_u32 s0, s24, 0x160080
	v_lshl_add_u64 v[172:173], v[212:213], 0, s[10:11]
	s_addc_u32 s1, s25, 0
	s_add_i32 s24, s53, s15
	global_load_lds_dwordx4 v[172:173], off
	v_lshl_add_u64 v[172:173], s[0:1], 0, v[160:161]
	s_mov_b32 m0, s24
	s_nop 0
	global_load_lds_dwordx4 v[172:173], off
	v_lshl_add_u64 v[172:173], s[0:1], 0, v[162:163]
	s_add_i32 m0, s24, 0x2000
	s_nop 0
	global_load_lds_dwordx4 v[172:173], off
	v_lshl_add_u64 v[172:173], v[214:215], 0, s[10:11]
	s_mov_b32 m0, s36
	s_nop 0
	global_load_lds_dwordx4 v[172:173], off
	v_lshl_add_u64 v[172:173], v[216:217], 0, s[10:11]
	s_mov_b32 m0, s37
	s_nop 0
	global_load_lds_dwordx4 v[172:173], off
	s_waitcnt vmcnt(8)
	s_waitcnt lgkmcnt(0)
	s_barrier
	s_waitcnt lgkmcnt(0)
	v_mfma_f32_16x16x32_bf16 v[60:63], v[96:99], v[168:171], v[60:63]
	v_mfma_f32_16x16x32_bf16 v[56:59], v[104:107], v[168:171], v[56:59]
	v_mfma_f32_16x16x32_bf16 v[48:51], v[96:99], v[188:191], v[48:51]
	v_mfma_f32_16x16x32_bf16 v[40:43], v[104:107], v[188:191], v[40:43]
	v_mfma_f32_16x16x32_bf16 v[28:31], v[96:99], v[196:199], v[28:31]
	v_mfma_f32_16x16x32_bf16 v[24:27], v[104:107], v[196:199], v[24:27]
	v_mfma_f32_16x16x32_bf16 v[16:19], v[96:99], v[204:207], v[16:19]
	v_mfma_f32_16x16x32_bf16 v[8:11], v[104:107], v[204:207], v[8:11]
	v_mfma_f32_16x16x32_bf16 v[60:63], v[100:103], v[184:187], v[60:63]
	v_mfma_f32_16x16x32_bf16 v[56:59], v[108:111], v[184:187], v[56:59]
	v_mfma_f32_16x16x32_bf16 v[48:51], v[100:103], v[192:195], v[48:51]
	v_mfma_f32_16x16x32_bf16 v[40:43], v[108:111], v[192:195], v[40:43]
	v_mfma_f32_16x16x32_bf16 v[28:31], v[100:103], v[200:203], v[28:31]
	v_mfma_f32_16x16x32_bf16 v[24:27], v[108:111], v[200:203], v[24:27]
	v_mfma_f32_16x16x32_bf16 v[16:19], v[100:103], v[208:211], v[16:19]
	v_mfma_f32_16x16x32_bf16 v[8:11], v[108:111], v[208:211], v[8:11]
	v_mfma_f32_16x16x32_bf16 v[52:55], v[112:115], v[168:171], v[52:55]
	v_mfma_f32_16x16x32_bf16 v[44:47], v[120:123], v[168:171], v[44:47]
	v_mfma_f32_16x16x32_bf16 v[36:39], v[112:115], v[188:191], v[36:39]
	v_mfma_f32_16x16x32_bf16 v[32:35], v[120:123], v[188:191], v[32:35]
	v_mfma_f32_16x16x32_bf16 v[20:23], v[112:115], v[196:199], v[20:23]
	v_mfma_f32_16x16x32_bf16 v[12:15], v[120:123], v[196:199], v[12:15]
	v_mfma_f32_16x16x32_bf16 v[4:7], v[112:115], v[204:207], v[4:7]
	v_mfma_f32_16x16x32_bf16 v[0:3], v[120:123], v[204:207], v[0:3]
	v_mfma_f32_16x16x32_bf16 v[52:55], v[116:119], v[184:187], v[52:55]
	v_mfma_f32_16x16x32_bf16 v[44:47], v[124:127], v[184:187], v[44:47]
	v_mfma_f32_16x16x32_bf16 v[36:39], v[116:119], v[192:195], v[36:39]
	v_mfma_f32_16x16x32_bf16 v[32:35], v[124:127], v[192:195], v[32:35]
	v_mfma_f32_16x16x32_bf16 v[20:23], v[116:119], v[200:203], v[20:23]
	v_mfma_f32_16x16x32_bf16 v[12:15], v[124:127], v[200:203], v[12:15]
	v_mfma_f32_16x16x32_bf16 v[4:7], v[116:119], v[208:211], v[4:7]
	v_mfma_f32_16x16x32_bf16 v[0:3], v[124:127], v[208:211], v[0:3]
	s_barrier
	s_add_i32 s51, s51, 2
	s_add_u32 s49, s49, 0x100
	s_addc_u32 s50, s50, 0
	s_cmpk_gt_u32 s51, 0x55
	s_mov_b64 s[0:1], s[4:5]
	s_cbranch_scc0 .LBB0_1120
	s_and_b64 vcc, exec, s[12:13]
	s_cbranch_vccz .LBB0_1123
	s_barrier
